# GEMM 8-phase loops: LDS-read rebalance - B-fragment ds_reads of phases 1/5 hoisted into read-free phases 8/4, covering vmcnt moved to phases 7/3 (on top of convert order + LN permlane + relu2 trims)
# speedup vs baseline: 1.0144x; 1.0125x over previous
.LBB0_126:
	s_ashr_i32 s19, s18, 31
	v_readlane_b32 s52, v253, 50
	s_lshl_b64 s[48:49], s[18:19], 18
	v_readlane_b32 s54, v253, 52
	v_readlane_b32 s55, v253, 53
	s_add_u32 s82, s54, s48
	s_addc_u32 s83, s55, s49
	s_and_b64 s[38:39], s[38:39], exec
	s_cselect_b32 s19, s83, s23
	s_cselect_b32 s31, s82, s22
	s_add_u32 s20, s20, 0x80080
	s_addc_u32 s21, s21, 0
	s_add_u32 s47, s22, 0x100
	v_mov_b32_e32 v2, 0
	s_addc_u32 s48, s23, 0
	s_mov_b32 s49, -2
	v_mov_b32_e32 v3, v2
	v_mov_b32_e32 v4, v2
	v_mov_b32_e32 v5, v2
	v_mov_b32_e32 v6, v2
	v_mov_b32_e32 v7, v2
	v_mov_b32_e32 v8, v2
	v_mov_b32_e32 v9, v2
	v_mov_b32_e32 v10, v2
	v_mov_b32_e32 v11, v2
	v_mov_b32_e32 v12, v2
	v_mov_b32_e32 v13, v2
	v_mov_b32_e32 v14, v2
	v_mov_b32_e32 v15, v2
	v_mov_b32_e32 v16, v2
	v_mov_b32_e32 v17, v2
	v_mov_b32_e32 v26, v2
	v_mov_b32_e32 v27, v2
	v_mov_b32_e32 v28, v2
	v_mov_b32_e32 v29, v2
	v_mov_b32_e32 v30, v2
	v_mov_b32_e32 v31, v2
	v_mov_b32_e32 v32, v2
	v_mov_b32_e32 v33, v2
	v_mov_b32_e32 v42, v2
	v_mov_b32_e32 v43, v2
	v_mov_b32_e32 v44, v2
	v_mov_b32_e32 v45, v2
	v_mov_b32_e32 v46, v2
	v_mov_b32_e32 v47, v2
	v_mov_b32_e32 v48, v2
	v_mov_b32_e32 v49, v2
	v_mov_b32_e32 v18, v2
	v_mov_b32_e32 v19, v2
	v_mov_b32_e32 v20, v2
	v_mov_b32_e32 v21, v2
	v_mov_b32_e32 v22, v2
	v_mov_b32_e32 v23, v2
	v_mov_b32_e32 v24, v2
	v_mov_b32_e32 v25, v2
	v_mov_b32_e32 v34, v2
	v_mov_b32_e32 v35, v2
	v_mov_b32_e32 v36, v2
	v_mov_b32_e32 v37, v2
	v_mov_b32_e32 v38, v2
	v_mov_b32_e32 v39, v2
	v_mov_b32_e32 v40, v2
	v_mov_b32_e32 v41, v2
	v_mov_b32_e32 v50, v2
	v_mov_b32_e32 v51, v2
	v_mov_b32_e32 v52, v2
	v_mov_b32_e32 v53, v2
	v_mov_b32_e32 v54, v2
	v_mov_b32_e32 v55, v2
	v_mov_b32_e32 v56, v2
	v_mov_b32_e32 v57, v2
	v_mov_b32_e32 v58, v2
	v_mov_b32_e32 v59, v2
	v_mov_b32_e32 v60, v2
	v_mov_b32_e32 v61, v2
	v_mov_b32_e32 v62, v2
	v_mov_b32_e32 v63, v2
	v_mov_b32_e32 v64, v2
	v_mov_b32_e32 v65, v2
	v_mov_b32_e32 v66, v2
	v_mov_b32_e32 v67, v2
	v_mov_b32_e32 v68, v2
	v_mov_b32_e32 v69, v2
	v_mov_b32_e32 v70, v2
	v_mov_b32_e32 v71, v2
	v_mov_b32_e32 v72, v2
	v_mov_b32_e32 v73, v2
	v_mov_b32_e32 v74, v2
	v_mov_b32_e32 v75, v2
	v_mov_b32_e32 v76, v2
	v_mov_b32_e32 v77, v2
	v_mov_b32_e32 v78, v2
	v_mov_b32_e32 v79, v2
	v_mov_b32_e32 v80, v2
	v_mov_b32_e32 v81, v2
	v_mov_b32_e32 v90, v2
	v_mov_b32_e32 v91, v2
	v_mov_b32_e32 v92, v2
	v_mov_b32_e32 v93, v2
	v_mov_b32_e32 v94, v2
	v_mov_b32_e32 v95, v2
	v_mov_b32_e32 v96, v2
	v_mov_b32_e32 v97, v2
	v_mov_b32_e32 v106, v2
	v_mov_b32_e32 v107, v2
	v_mov_b32_e32 v108, v2
	v_mov_b32_e32 v109, v2
	v_mov_b32_e32 v110, v2
	v_mov_b32_e32 v111, v2
	v_mov_b32_e32 v112, v2
	v_mov_b32_e32 v113, v2
	v_mov_b32_e32 v82, v2
	v_mov_b32_e32 v83, v2
	v_mov_b32_e32 v84, v2
	v_mov_b32_e32 v85, v2
	v_mov_b32_e32 v86, v2
	v_mov_b32_e32 v87, v2
	v_mov_b32_e32 v88, v2
	v_mov_b32_e32 v89, v2
	v_mov_b32_e32 v98, v2
	v_mov_b32_e32 v99, v2
	v_mov_b32_e32 v100, v2
	v_mov_b32_e32 v101, v2
	v_mov_b32_e32 v102, v2
	v_mov_b32_e32 v103, v2
	v_mov_b32_e32 v104, v2
	v_mov_b32_e32 v105, v2
	v_mov_b32_e32 v114, v2
	v_mov_b32_e32 v115, v2
	v_mov_b32_e32 v116, v2
	v_mov_b32_e32 v117, v2
	v_mov_b32_e32 v118, v2
	v_mov_b32_e32 v119, v2
	v_mov_b32_e32 v120, v2
	v_mov_b32_e32 v121, v2
	v_mov_b32_e32 v122, v2
	v_mov_b32_e32 v123, v2
	v_mov_b32_e32 v124, v2
	v_mov_b32_e32 v125, v2
	v_mov_b32_e32 v126, v2
	v_mov_b32_e32 v127, v2
	v_mov_b32_e32 v128, v2
	v_mov_b32_e32 v129, v2
	v_readlane_b32 s53, v253, 51
	v_readlane_b32 s56, v253, 54
	v_readlane_b32 s57, v253, 55
	v_readlane_b32 s58, v253, 56
	v_readlane_b32 s59, v253, 57
	v_readlane_b32 s60, v253, 58
	v_readlane_b32 s61, v253, 59
	v_readlane_b32 s62, v253, 60
	v_readlane_b32 s63, v253, 61
	v_readlane_b32 s64, v253, 62
	v_readlane_b32 s65, v253, 63
	v_readlane_b32 s66, v254, 0
	v_readlane_b32 s67, v254, 1
	v_add_u32_e32 v145, 0x10000, v142
	ds_read_b128 v[146:149], v145
	ds_read_b128 v[150:153], v145 offset:1024
	ds_read_b128 v[154:157], v145 offset:2048
	ds_read_b128 v[158:161], v145 offset:3072
.LBB0_127:
	s_add_u32 s22, s20, 0xfff80080
	s_addc_u32 s23, s21, -1
	s_add_i32 s50, 0, 0x10000
	s_cmp_eq_u32 s49, 4
	s_cselect_b32 s23, s81, s23
	s_cselect_b32 s22, s80, s22
	s_cselect_b32 s39, s19, s48
	s_cselect_b32 s38, s31, s47
	v_lshl_add_u64 v[178:179], s[20:21], 0, v[138:139]
	s_add_i32 m0, s27, 0xc000
	ds_read_b128 v[162:165], v144
	ds_read_b128 v[166:169], v144 offset:1024
	ds_read_b128 v[170:173], v144 offset:2048
	ds_read_b128 v[174:177], v144 offset:3072
	ds_read_b128 v[192:195], v144 offset:4096
	ds_read_b128 v[196:199], v144 offset:5120
	ds_read_b128 v[200:203], v144 offset:6144
	ds_read_b128 v[204:207], v144 offset:7168
	global_load_lds_dwordx4 v[178:179], off
	v_lshl_add_u64 v[178:179], s[20:21], 0, v[140:141]
	s_add_i32 m0, s27, 0xe000
	s_nop 0
	global_load_lds_dwordx4 v[178:179], off
	s_waitcnt lgkmcnt(8)
	s_barrier
	s_waitcnt lgkmcnt(0)
	s_setprio 1
	s_waitcnt lgkmcnt(0)
	v_mfma_f32_16x16x32_bf16 v[126:129], v[146:149], v[162:165], v[126:129]
	v_mfma_f32_16x16x32_bf16 v[122:125], v[154:157], v[162:165], v[122:125]
	v_mfma_f32_16x16x32_bf16 v[118:121], v[146:149], v[170:173], v[118:121]
	v_mfma_f32_16x16x32_bf16 v[114:117], v[154:157], v[170:173], v[114:117]
	v_mfma_f32_16x16x32_bf16 v[102:105], v[146:149], v[192:195], v[102:105]
	v_mfma_f32_16x16x32_bf16 v[98:101], v[154:157], v[192:195], v[98:101]
	v_mfma_f32_16x16x32_bf16 v[86:89], v[146:149], v[200:203], v[86:89]
	v_mfma_f32_16x16x32_bf16 v[82:85], v[154:157], v[200:203], v[82:85]
	v_mfma_f32_16x16x32_bf16 v[126:129], v[150:153], v[166:169], v[126:129]
	v_mfma_f32_16x16x32_bf16 v[122:125], v[158:161], v[166:169], v[122:125]
	v_mfma_f32_16x16x32_bf16 v[118:121], v[150:153], v[174:177], v[118:121]
	v_mfma_f32_16x16x32_bf16 v[114:117], v[158:161], v[174:177], v[114:117]
	v_mfma_f32_16x16x32_bf16 v[102:105], v[150:153], v[196:199], v[102:105]
	v_mfma_f32_16x16x32_bf16 v[98:101], v[158:161], v[196:199], v[98:101]
	v_mfma_f32_16x16x32_bf16 v[86:89], v[150:153], v[204:207], v[86:89]
	v_mfma_f32_16x16x32_bf16 v[82:85], v[158:161], v[204:207], v[82:85]
	s_setprio 0
	s_barrier
	s_add_i32 s52, 0, 0x14000
	s_add_i32 s50, s50, s26
	v_add_u32_e32 v145, s52, v142
	v_lshl_add_u64 v[178:179], s[38:39], 0, v[134:135]
	s_mov_b32 m0, s50
	ds_read_b128 v[208:211], v145
	ds_read_b128 v[224:227], v145 offset:1024
	ds_read_b128 v[228:231], v145 offset:2048
	ds_read_b128 v[232:235], v145 offset:3072
	global_load_lds_dwordx4 v[178:179], off
	v_lshl_add_u64 v[212:213], s[38:39], 0, v[130:131]
	s_add_i32 m0, s50, 0x2000
	s_nop 0
	global_load_lds_dwordx4 v[212:213], off
	s_barrier
	s_waitcnt lgkmcnt(0)
	s_setprio 1
	s_waitcnt lgkmcnt(0)
	v_mfma_f32_16x16x32_bf16 v[110:113], v[208:211], v[162:165], v[110:113]
	v_mfma_f32_16x16x32_bf16 v[106:109], v[228:231], v[162:165], v[106:109]
	v_mfma_f32_16x16x32_bf16 v[94:97], v[208:211], v[170:173], v[94:97]
	v_mfma_f32_16x16x32_bf16 v[90:93], v[228:231], v[170:173], v[90:93]
	v_mfma_f32_16x16x32_bf16 v[78:81], v[208:211], v[192:195], v[78:81]
	v_mfma_f32_16x16x32_bf16 v[74:77], v[228:231], v[192:195], v[74:77]
	v_mfma_f32_16x16x32_bf16 v[70:73], v[208:211], v[200:203], v[70:73]
	v_mfma_f32_16x16x32_bf16 v[66:69], v[228:231], v[200:203], v[66:69]
	v_mfma_f32_16x16x32_bf16 v[110:113], v[224:227], v[166:169], v[110:113]
	v_mfma_f32_16x16x32_bf16 v[106:109], v[232:235], v[166:169], v[106:109]
	v_mfma_f32_16x16x32_bf16 v[94:97], v[224:227], v[174:177], v[94:97]
	v_mfma_f32_16x16x32_bf16 v[90:93], v[232:235], v[174:177], v[90:93]
	v_mfma_f32_16x16x32_bf16 v[78:81], v[224:227], v[196:199], v[78:81]
	v_mfma_f32_16x16x32_bf16 v[74:77], v[232:235], v[196:199], v[74:77]
	v_mfma_f32_16x16x32_bf16 v[70:73], v[224:227], v[204:207], v[70:73]
	v_mfma_f32_16x16x32_bf16 v[66:69], v[232:235], v[204:207], v[66:69]
	s_setprio 0
	s_mov_b32 m0, s27
	v_lshl_add_u64 v[236:237], s[22:23], 0, v[136:137]
	s_barrier
	ds_read_b128 v[162:165], v144 offset:16384
	ds_read_b128 v[166:169], v144 offset:17408
	ds_read_b128 v[170:173], v144 offset:18432
	ds_read_b128 v[174:177], v144 offset:19456
	ds_read_b128 v[192:195], v144 offset:20480
	ds_read_b128 v[196:199], v144 offset:21504
	ds_read_b128 v[200:203], v144 offset:22528
	ds_read_b128 v[204:207], v144 offset:23552
	global_load_lds_dwordx4 v[236:237], off
	v_lshl_add_u64 v[238:239], s[22:23], 0, v[132:133]
	s_mov_b32 m0, s28
	s_nop 0
	global_load_lds_dwordx4 v[238:239], off
	s_waitcnt vmcnt(10)
	s_barrier
	s_waitcnt lgkmcnt(0)
	s_setprio 1
	s_waitcnt lgkmcnt(0)
	v_mfma_f32_16x16x32_bf16 v[62:65], v[146:149], v[162:165], v[62:65]
	v_mfma_f32_16x16x32_bf16 v[58:61], v[154:157], v[162:165], v[58:61]
	v_mfma_f32_16x16x32_bf16 v[54:57], v[146:149], v[170:173], v[54:57]
	v_mfma_f32_16x16x32_bf16 v[50:53], v[154:157], v[170:173], v[50:53]
	v_mfma_f32_16x16x32_bf16 v[38:41], v[146:149], v[192:195], v[38:41]
	v_mfma_f32_16x16x32_bf16 v[34:37], v[154:157], v[192:195], v[34:37]
	v_mfma_f32_16x16x32_bf16 v[22:25], v[146:149], v[200:203], v[22:25]
	v_mfma_f32_16x16x32_bf16 v[18:21], v[154:157], v[200:203], v[18:21]
	v_mfma_f32_16x16x32_bf16 v[62:65], v[150:153], v[166:169], v[62:65]
	v_mfma_f32_16x16x32_bf16 v[58:61], v[158:161], v[166:169], v[58:61]
	v_mfma_f32_16x16x32_bf16 v[54:57], v[150:153], v[174:177], v[54:57]
	v_mfma_f32_16x16x32_bf16 v[50:53], v[158:161], v[174:177], v[50:53]
	v_mfma_f32_16x16x32_bf16 v[38:41], v[150:153], v[196:199], v[38:41]
	v_mfma_f32_16x16x32_bf16 v[34:37], v[158:161], v[196:199], v[34:37]
	v_mfma_f32_16x16x32_bf16 v[22:25], v[150:153], v[204:207], v[22:25]
	v_mfma_f32_16x16x32_bf16 v[18:21], v[158:161], v[204:207], v[18:21]
	s_setprio 0
	s_barrier
	s_add_u32 s50, s38, 0x20000
	s_addc_u32 s51, s39, 0
	s_add_i32 s52, s52, s26
	v_lshl_add_u64 v[146:147], s[50:51], 0, v[134:135]
	s_mov_b32 m0, s52
	s_nop 0
	global_load_lds_dwordx4 v[146:147], off
	v_lshl_add_u64 v[146:147], s[50:51], 0, v[130:131]
	s_add_i32 m0, s52, 0x2000
	s_nop 0
	global_load_lds_dwordx4 v[146:147], off
	v_add_u32_e32 v145, 0x18000, v142
	ds_read_b128 v[146:149], v145
	ds_read_b128 v[150:153], v145 offset:1024
	ds_read_b128 v[154:157], v145 offset:2048
	ds_read_b128 v[158:161], v145 offset:3072
	s_waitcnt vmcnt(6)
	s_barrier
	s_setprio 1
	v_mfma_f32_16x16x32_bf16 v[46:49], v[208:211], v[162:165], v[46:49]
	v_mfma_f32_16x16x32_bf16 v[42:45], v[228:231], v[162:165], v[42:45]
	v_mfma_f32_16x16x32_bf16 v[30:33], v[208:211], v[170:173], v[30:33]
	v_mfma_f32_16x16x32_bf16 v[26:29], v[228:231], v[170:173], v[26:29]
	v_mfma_f32_16x16x32_bf16 v[14:17], v[208:211], v[192:195], v[14:17]
	v_mfma_f32_16x16x32_bf16 v[10:13], v[228:231], v[192:195], v[10:13]
	v_mfma_f32_16x16x32_bf16 v[6:9], v[208:211], v[200:203], v[6:9]
	v_mfma_f32_16x16x32_bf16 v[2:5], v[228:231], v[200:203], v[2:5]
	v_mfma_f32_16x16x32_bf16 v[46:49], v[224:227], v[166:169], v[46:49]
	v_mfma_f32_16x16x32_bf16 v[42:45], v[232:235], v[166:169], v[42:45]
	v_mfma_f32_16x16x32_bf16 v[30:33], v[224:227], v[174:177], v[30:33]
	v_mfma_f32_16x16x32_bf16 v[26:29], v[232:235], v[174:177], v[26:29]
	v_mfma_f32_16x16x32_bf16 v[14:17], v[224:227], v[196:199], v[14:17]
	v_mfma_f32_16x16x32_bf16 v[10:13], v[232:235], v[196:199], v[10:13]
	v_mfma_f32_16x16x32_bf16 v[6:9], v[224:227], v[204:207], v[6:9]
	v_mfma_f32_16x16x32_bf16 v[2:5], v[232:235], v[204:207], v[2:5]
	s_setprio 0
	s_add_i32 s50, 0, 0x18000
	s_barrier
	s_add_u32 s22, s22, 0x80000
	s_addc_u32 s23, s23, 0
	s_mov_b32 m0, s29
	v_lshl_add_u64 v[208:209], s[22:23], 0, v[136:137]
	ds_read_b128 v[162:165], v144 offset:32768
	ds_read_b128 v[166:169], v144 offset:33792
	ds_read_b128 v[170:173], v144 offset:34816
	ds_read_b128 v[174:177], v144 offset:35840
	ds_read_b128 v[192:195], v144 offset:36864
	ds_read_b128 v[196:199], v144 offset:37888
	ds_read_b128 v[200:203], v144 offset:38912
	ds_read_b128 v[204:207], v144 offset:39936
	global_load_lds_dwordx4 v[208:209], off
	v_lshl_add_u64 v[208:209], s[22:23], 0, v[132:133]
	s_mov_b32 m0, s36
	s_nop 0
	global_load_lds_dwordx4 v[208:209], off
	s_waitcnt lgkmcnt(8)
	s_barrier
	s_waitcnt lgkmcnt(0)
	s_setprio 1
	s_waitcnt lgkmcnt(0)
	v_mfma_f32_16x16x32_bf16 v[126:129], v[146:149], v[162:165], v[126:129]
	v_mfma_f32_16x16x32_bf16 v[122:125], v[154:157], v[162:165], v[122:125]
	v_mfma_f32_16x16x32_bf16 v[118:121], v[146:149], v[170:173], v[118:121]
	v_mfma_f32_16x16x32_bf16 v[114:117], v[154:157], v[170:173], v[114:117]
	v_mfma_f32_16x16x32_bf16 v[102:105], v[146:149], v[192:195], v[102:105]
	v_mfma_f32_16x16x32_bf16 v[98:101], v[154:157], v[192:195], v[98:101]
	v_mfma_f32_16x16x32_bf16 v[86:89], v[146:149], v[200:203], v[86:89]
	v_mfma_f32_16x16x32_bf16 v[82:85], v[154:157], v[200:203], v[82:85]
	v_mfma_f32_16x16x32_bf16 v[126:129], v[150:153], v[166:169], v[126:129]
	v_mfma_f32_16x16x32_bf16 v[122:125], v[158:161], v[166:169], v[122:125]
	v_mfma_f32_16x16x32_bf16 v[118:121], v[150:153], v[174:177], v[118:121]
	v_mfma_f32_16x16x32_bf16 v[114:117], v[158:161], v[174:177], v[114:117]
	v_mfma_f32_16x16x32_bf16 v[102:105], v[150:153], v[196:199], v[102:105]
	v_mfma_f32_16x16x32_bf16 v[98:101], v[158:161], v[196:199], v[98:101]
	v_mfma_f32_16x16x32_bf16 v[86:89], v[150:153], v[204:207], v[86:89]
	v_mfma_f32_16x16x32_bf16 v[82:85], v[158:161], v[204:207], v[82:85]
	s_setprio 0
	s_barrier
	s_add_i32 s51, 0, 0x1c000
	s_add_i32 s22, s50, s26
	v_add_u32_e32 v145, s51, v142
	v_lshl_add_u64 v[178:179], v[178:179], 0, s[78:79]
	s_mov_b32 m0, s22
	ds_read_b128 v[208:211], v145
	ds_read_b128 v[224:227], v145 offset:1024
	ds_read_b128 v[228:231], v145 offset:2048
	ds_read_b128 v[232:235], v145 offset:3072
	global_load_lds_dwordx4 v[178:179], off
	v_lshl_add_u64 v[178:179], v[212:213], 0, s[78:79]
	s_add_i32 m0, s22, 0x2000
	s_nop 0
	global_load_lds_dwordx4 v[178:179], off
	s_barrier
	s_waitcnt lgkmcnt(0)
	s_setprio 1
	s_waitcnt lgkmcnt(0)
	v_mfma_f32_16x16x32_bf16 v[110:113], v[208:211], v[162:165], v[110:113]
	v_mfma_f32_16x16x32_bf16 v[106:109], v[228:231], v[162:165], v[106:109]
	v_mfma_f32_16x16x32_bf16 v[94:97], v[208:211], v[170:173], v[94:97]
	v_mfma_f32_16x16x32_bf16 v[90:93], v[228:231], v[170:173], v[90:93]
	v_mfma_f32_16x16x32_bf16 v[78:81], v[208:211], v[192:195], v[78:81]
	v_mfma_f32_16x16x32_bf16 v[74:77], v[228:231], v[192:195], v[74:77]
	v_mfma_f32_16x16x32_bf16 v[70:73], v[208:211], v[200:203], v[70:73]
	v_mfma_f32_16x16x32_bf16 v[66:69], v[228:231], v[200:203], v[66:69]
	v_mfma_f32_16x16x32_bf16 v[110:113], v[224:227], v[166:169], v[110:113]
	v_mfma_f32_16x16x32_bf16 v[106:109], v[232:235], v[166:169], v[106:109]
	v_mfma_f32_16x16x32_bf16 v[94:97], v[224:227], v[174:177], v[94:97]
	v_mfma_f32_16x16x32_bf16 v[90:93], v[232:235], v[174:177], v[90:93]
	v_mfma_f32_16x16x32_bf16 v[78:81], v[224:227], v[196:199], v[78:81]
	v_mfma_f32_16x16x32_bf16 v[74:77], v[232:235], v[196:199], v[74:77]
	v_mfma_f32_16x16x32_bf16 v[70:73], v[224:227], v[204:207], v[70:73]
	v_mfma_f32_16x16x32_bf16 v[66:69], v[232:235], v[204:207], v[66:69]
	s_setprio 0
	s_mov_b32 m0, s42
	v_lshl_add_u64 v[178:179], v[236:237], 0, s[78:79]
	s_barrier
	ds_read_b128 v[162:165], v144 offset:49152
	ds_read_b128 v[166:169], v144 offset:50176
	ds_read_b128 v[170:173], v144 offset:51200
	ds_read_b128 v[174:177], v144 offset:52224
	ds_read_b128 v[192:195], v144 offset:53248
	ds_read_b128 v[196:199], v144 offset:54272
	ds_read_b128 v[200:203], v144 offset:55296
	ds_read_b128 v[204:207], v144 offset:56320
	global_load_lds_dwordx4 v[178:179], off
	v_lshl_add_u64 v[178:179], v[238:239], 0, s[78:79]
	s_mov_b32 m0, s43
	s_nop 0
	global_load_lds_dwordx4 v[178:179], off
	s_waitcnt vmcnt(10)
	s_barrier
	s_waitcnt lgkmcnt(0)
	s_setprio 1
	s_waitcnt lgkmcnt(0)
	v_mfma_f32_16x16x32_bf16 v[62:65], v[146:149], v[162:165], v[62:65]
	v_mfma_f32_16x16x32_bf16 v[58:61], v[154:157], v[162:165], v[58:61]
	v_mfma_f32_16x16x32_bf16 v[54:57], v[146:149], v[170:173], v[54:57]
	v_mfma_f32_16x16x32_bf16 v[50:53], v[154:157], v[170:173], v[50:53]
	v_mfma_f32_16x16x32_bf16 v[38:41], v[146:149], v[192:195], v[38:41]
	v_mfma_f32_16x16x32_bf16 v[34:37], v[154:157], v[192:195], v[34:37]
	v_mfma_f32_16x16x32_bf16 v[22:25], v[146:149], v[200:203], v[22:25]
	v_mfma_f32_16x16x32_bf16 v[18:21], v[154:157], v[200:203], v[18:21]
	v_mfma_f32_16x16x32_bf16 v[62:65], v[150:153], v[166:169], v[62:65]
	v_mfma_f32_16x16x32_bf16 v[58:61], v[158:161], v[166:169], v[58:61]
	v_mfma_f32_16x16x32_bf16 v[54:57], v[150:153], v[174:177], v[54:57]
	v_mfma_f32_16x16x32_bf16 v[50:53], v[158:161], v[174:177], v[50:53]
	v_mfma_f32_16x16x32_bf16 v[38:41], v[150:153], v[196:199], v[38:41]
	v_mfma_f32_16x16x32_bf16 v[34:37], v[158:161], v[196:199], v[34:37]
	v_mfma_f32_16x16x32_bf16 v[22:25], v[150:153], v[204:207], v[22:25]
	v_mfma_f32_16x16x32_bf16 v[18:21], v[158:161], v[204:207], v[18:21]
	s_setprio 0
	s_barrier
	s_add_u32 s22, s38, 0x20080
	s_addc_u32 s23, s39, 0
	s_add_i32 s38, s51, s26
	v_lshl_add_u64 v[146:147], s[22:23], 0, v[134:135]
	s_mov_b32 m0, s38
	s_nop 0
	global_load_lds_dwordx4 v[146:147], off
	v_lshl_add_u64 v[146:147], s[22:23], 0, v[130:131]
	s_add_i32 m0, s38, 0x2000
	s_nop 0
	global_load_lds_dwordx4 v[146:147], off
	v_add_u32_e32 v145, 0x10000, v142
	ds_read_b128 v[146:149], v145
	ds_read_b128 v[150:153], v145 offset:1024
	ds_read_b128 v[154:157], v145 offset:2048
	ds_read_b128 v[158:161], v145 offset:3072
	s_waitcnt vmcnt(6)
	s_barrier
	s_setprio 1
	v_mfma_f32_16x16x32_bf16 v[46:49], v[208:211], v[162:165], v[46:49]
	v_mfma_f32_16x16x32_bf16 v[42:45], v[228:231], v[162:165], v[42:45]
	v_mfma_f32_16x16x32_bf16 v[30:33], v[208:211], v[170:173], v[30:33]
	v_mfma_f32_16x16x32_bf16 v[26:29], v[228:231], v[170:173], v[26:29]
	v_mfma_f32_16x16x32_bf16 v[14:17], v[208:211], v[192:195], v[14:17]
	v_mfma_f32_16x16x32_bf16 v[10:13], v[228:231], v[192:195], v[10:13]
	v_mfma_f32_16x16x32_bf16 v[6:9], v[208:211], v[200:203], v[6:9]
	v_mfma_f32_16x16x32_bf16 v[2:5], v[228:231], v[200:203], v[2:5]
	v_mfma_f32_16x16x32_bf16 v[46:49], v[224:227], v[166:169], v[46:49]
	v_mfma_f32_16x16x32_bf16 v[42:45], v[232:235], v[166:169], v[42:45]
	v_mfma_f32_16x16x32_bf16 v[30:33], v[224:227], v[174:177], v[30:33]
	v_mfma_f32_16x16x32_bf16 v[26:29], v[232:235], v[174:177], v[26:29]
	v_mfma_f32_16x16x32_bf16 v[14:17], v[224:227], v[196:199], v[14:17]
	v_mfma_f32_16x16x32_bf16 v[10:13], v[232:235], v[196:199], v[10:13]
	v_mfma_f32_16x16x32_bf16 v[6:9], v[224:227], v[204:207], v[6:9]
	v_mfma_f32_16x16x32_bf16 v[2:5], v[232:235], v[204:207], v[2:5]
	s_setprio 0
	s_add_i32 s49, s49, 2
	s_add_u32 s20, s20, 0x100
	s_addc_u32 s21, s21, 0
	s_add_u32 s47, s47, 0x100
	s_addc_u32 s48, s48, 0
	s_cmp_gt_u32 s49, 5
	s_barrier
	s_cbranch_scc0 .LBB0_127
	s_waitcnt lgkmcnt(0)
	v_lshl_add_u32 v146, s46, 8, v1
	v_lshl_or_b32 v148, s45, 8, v143
	v_ashrrev_i32_e32 v147, 31, v146
	v_readlane_b32 s48, v254, 40
	v_ashrrev_i32_e32 v149, 31, v148
	v_lshlrev_b64 v[150:151], 12, v[146:147]
	v_readlane_b32 s52, v254, 44
	v_readlane_b32 s53, v254, 45
	v_lshlrev_b64 v[148:149], 1, v[148:149]
	s_mov_b32 s19, 0x80000
	v_lshl_add_u64 v[150:151], s[52:53], 0, v[150:151]
	v_lshl_add_u64 v[150:151], v[150:151], 0, v[148:149]
	s_mov_b64 s[20:21], 0x80000
	v_cvt_pk_bf16_f32 v62, v62, v63
	v_cvt_pk_bf16_f32 v63, v64, v65
	v_cvt_pk_bf16_f32 v64, v58, v59
	v_add_co_u32_e32 v58, vcc, s19, v150
	v_cvt_pk_bf16_f32 v70, v70, v71
	v_cvt_pk_bf16_f32 v71, v72, v73
	v_cvt_pk_bf16_f32 v72, v66, v67
	v_lshl_add_u64 v[66:67], v[150:151], 0, s[20:21]
	v_addc_co_u32_e32 v59, vcc, 0, v151, vcc
	v_cvt_pk_bf16_f32 v46, v46, v47
	v_cvt_pk_bf16_f32 v47, v48, v49
	v_cvt_pk_bf16_f32 v48, v42, v43
	v_cvt_pk_bf16_f32 v49, v44, v45
	s_mov_b32 s19, 0x90000
	v_cvt_pk_bf16_f32 v110, v110, v111
	v_cvt_pk_bf16_f32 v111, v112, v113
	v_cvt_pk_bf16_f32 v112, v106, v107
	v_or_b32_e32 v106, 16, v146
	global_store_dwordx4 v[66:67], v[46:49], off offset:256
	s_mov_b64 s[20:21], 0x90000
	v_ashrrev_i32_e32 v107, 31, v106
	v_add_co_u32_e32 v48, vcc, s19, v150
	v_cvt_pk_bf16_f32 v94, v94, v95
	v_cvt_pk_bf16_f32 v95, v96, v97
	v_cvt_pk_bf16_f32 v96, v90, v91
	v_or_b32_e32 v90, 32, v146
	v_lshl_add_u64 v[46:47], v[150:151], 0, s[20:21]
	v_addc_co_u32_e32 v49, vcc, 0, v151, vcc
	v_cvt_pk_bf16_f32 v30, v30, v31
	v_cvt_pk_bf16_f32 v31, v32, v33
	v_cvt_pk_bf16_f32 v32, v26, v27
	v_cvt_pk_bf16_f32 v33, v28, v29
	s_mov_b32 s19, 0xa0000
	v_lshlrev_b64 v[106:107], 12, v[106:107]
	v_ashrrev_i32_e32 v91, 31, v90
	v_cvt_pk_bf16_f32 v78, v78, v79
	v_cvt_pk_bf16_f32 v79, v80, v81
	v_cvt_pk_bf16_f32 v80, v74, v75
	v_or_b32_e32 v74, 48, v146
	global_store_dwordx4 v[46:47], v[30:33], off offset:256
	s_mov_b64 s[20:21], 0xa0000
	v_cvt_pk_bf16_f32 v113, v108, v109
	v_add_co_u32_e32 v32, vcc, s19, v150
	v_lshl_add_u64 v[106:107], s[52:53], 0, v[106:107]
	v_lshlrev_b64 v[90:91], 12, v[90:91]
	v_ashrrev_i32_e32 v75, 31, v74
	v_lshl_add_u64 v[30:31], v[150:151], 0, s[20:21]
	v_addc_co_u32_e32 v33, vcc, 0, v151, vcc
	v_cvt_pk_bf16_f32 v14, v14, v15
	v_cvt_pk_bf16_f32 v15, v16, v17
	v_cvt_pk_bf16_f32 v16, v10, v11
	v_cvt_pk_bf16_f32 v17, v12, v13
	s_mov_b32 s19, 0xb0000
	global_store_dwordx4 v[150:151], v[110:113], off offset:256
	v_cvt_pk_bf16_f32 v97, v92, v93
	v_lshl_add_u64 v[90:91], s[52:53], 0, v[90:91]
	v_lshl_add_u64 v[110:111], v[106:107], 0, v[148:149]
	v_lshlrev_b64 v[74:75], 12, v[74:75]
	global_store_dwordx4 v[30:31], v[14:17], off offset:256
	global_store_dwordx4 v[110:111], v[94:97], off offset:256
	v_cvt_pk_bf16_f32 v81, v76, v77
	v_add_co_u32_e32 v16, vcc, s19, v150
	v_lshl_add_u64 v[94:95], v[90:91], 0, v[148:149]
	v_lshl_add_u64 v[74:75], s[52:53], 0, v[74:75]
	s_mov_b64 s[20:21], 0xb0000
	v_addc_co_u32_e32 v17, vcc, 0, v151, vcc
	v_cvt_pk_bf16_f32 v126, v126, v127
	v_cvt_pk_bf16_f32 v127, v128, v129
	v_cvt_pk_bf16_f32 v128, v122, v123
	v_cvt_pk_bf16_f32 v129, v124, v125
	v_cvt_pk_bf16_f32 v106, v118, v119
	v_cvt_pk_bf16_f32 v107, v120, v121
	v_cvt_pk_bf16_f32 v108, v114, v115
	v_cvt_pk_bf16_f32 v109, v116, v117
	v_cvt_pk_bf16_f32 v90, v102, v103
	v_cvt_pk_bf16_f32 v91, v104, v105
	v_cvt_pk_bf16_f32 v92, v98, v99
	v_cvt_pk_bf16_f32 v93, v100, v101
	global_store_dwordx4 v[94:95], v[78:81], off offset:256
	v_cvt_pk_bf16_f32 v76, v82, v83
	v_cvt_pk_bf16_f32 v77, v84, v85
	v_lshl_add_u64 v[78:79], v[74:75], 0, v[148:149]
	v_cvt_pk_bf16_f32 v74, v86, v87
	v_cvt_pk_bf16_f32 v75, v88, v89
	v_cvt_pk_bf16_f32 v73, v68, v69
	v_cvt_pk_bf16_f32 v65, v60, v61
	v_cvt_pk_bf16_f32 v42, v54, v55
	v_cvt_pk_bf16_f32 v43, v56, v57
	v_cvt_pk_bf16_f32 v44, v50, v51
	v_cvt_pk_bf16_f32 v45, v52, v53
	v_cvt_pk_bf16_f32 v26, v38, v39
	v_cvt_pk_bf16_f32 v27, v40, v41
	v_cvt_pk_bf16_f32 v28, v34, v35
	v_cvt_pk_bf16_f32 v29, v36, v37
	v_lshl_add_u64 v[14:15], v[150:151], 0, s[20:21]
	v_cvt_pk_bf16_f32 v10, v22, v23
	v_cvt_pk_bf16_f32 v11, v24, v25
	v_cvt_pk_bf16_f32 v12, v18, v19
	v_cvt_pk_bf16_f32 v13, v20, v21
	v_cvt_pk_bf16_f32 v6, v6, v7
	v_cvt_pk_bf16_f32 v7, v8, v9
	v_cvt_pk_bf16_f32 v8, v2, v3
	v_cvt_pk_bf16_f32 v9, v4, v5
	s_and_b64 vcc, exec, s[0:1]
	s_mov_b32 s45, s18
	s_mov_b32 s46, s30
	s_mov_b64 s[22:23], s[82:83]
	s_mov_b64 s[20:21], s[80:81]
	s_mov_b32 s64, 0x800000
	s_movk_i32 s65, 0x1fff
	v_readlane_b32 s49, v254, 41
	v_readlane_b32 s50, v254, 42
	v_readlane_b32 s51, v254, 43
	v_readlane_b32 s54, v254, 46
	v_readlane_b32 s55, v254, 47
	v_readlane_b32 s56, v254, 48
	v_readlane_b32 s57, v254, 49
	v_readlane_b32 s58, v254, 50
	v_readlane_b32 s59, v254, 51
	v_readlane_b32 s60, v254, 52
	v_readlane_b32 s61, v254, 53
	v_readlane_b32 s62, v254, 54
	v_readlane_b32 s63, v254, 55
	global_store_dwordx4 v[150:151], v[126:129], off
	global_store_dwordx4 v[110:111], v[106:109], off
	global_store_dwordx4 v[94:95], v[90:93], off
	global_store_dwordx4 v[78:79], v[74:77], off
	global_store_dwordx4 v[78:79], v[70:73], off offset:256
	global_store_dwordx4 v[58:59], v[62:65], off
	global_store_dwordx4 v[48:49], v[42:45], off
	global_store_dwordx4 v[32:33], v[26:29], off
	global_store_dwordx4 v[16:17], v[10:13], off
	global_store_dwordx4 v[14:15], v[6:9], off offset:256
	s_cbranch_vccz .LBB0_118
	s_waitcnt vmcnt(0)
	v_readlane_b32 s44, v255, 30
	s_mov_b32 s66, s90
	s_cmpk_gt_u32 s25, 0xff
	v_readlane_b32 s45, v255, 31
	v_readlane_b32 s42, v255, 32
	s_cbranch_scc1 .LBB0_131
	s_barrier

.LBB0_239:
	v_mov_b64_e32 v[2:3], 0xa0
	s_ashr_i32 s21, s20, 31
	v_cmp_lt_i64_e32 vcc, s[30:31], v[2:3]
	s_lshl_b64 s[30:31], s[20:21], 20
	s_add_u32 s30, s34, s30
	s_addc_u32 s31, s35, s31
	s_and_b64 s[38:39], vcc, exec
	s_cselect_b32 s21, s31, s81
	s_cselect_b32 s47, s30, s80
	s_ashr_i32 s19, s18, 31
	s_lshl_b64 s[38:39], s[18:19], 20
	v_readlane_b32 s48, v253, 50
	v_readlane_b32 s49, v253, 51
	s_add_u32 s38, s48, s38
	s_addc_u32 s39, s49, s39
	s_and_b64 s[48:49], vcc, exec
	s_cselect_b32 s19, s39, s23
	s_cselect_b32 s48, s38, s22
	s_add_u32 s80, s80, 0x80080
	s_addc_u32 s81, s81, 0
	v_readlane_b32 s50, v253, 52
	v_readlane_b32 s51, v253, 53
	s_add_u32 s49, s22, 0x100
	v_mov_b32_e32 v2, 0
	s_addc_u32 s50, s23, 0
	s_mov_b32 s51, -2
	v_mov_b32_e32 v3, v2
	v_mov_b32_e32 v4, v2
	v_mov_b32_e32 v5, v2
	v_mov_b32_e32 v6, v2
	v_mov_b32_e32 v7, v2
	v_mov_b32_e32 v8, v2
	v_mov_b32_e32 v9, v2
	v_mov_b32_e32 v10, v2
	v_mov_b32_e32 v11, v2
	v_mov_b32_e32 v12, v2
	v_mov_b32_e32 v13, v2
	v_mov_b32_e32 v14, v2
	v_mov_b32_e32 v15, v2
	v_mov_b32_e32 v16, v2
	v_mov_b32_e32 v17, v2
	v_mov_b32_e32 v18, v2
	v_mov_b32_e32 v19, v2
	v_mov_b32_e32 v20, v2
	v_mov_b32_e32 v21, v2
	v_mov_b32_e32 v26, v2
	v_mov_b32_e32 v27, v2
	v_mov_b32_e32 v28, v2
	v_mov_b32_e32 v29, v2
	v_mov_b32_e32 v34, v2
	v_mov_b32_e32 v35, v2
	v_mov_b32_e32 v36, v2
	v_mov_b32_e32 v37, v2
	v_mov_b32_e32 v42, v2
	v_mov_b32_e32 v43, v2
	v_mov_b32_e32 v44, v2
	v_mov_b32_e32 v45, v2
	v_mov_b32_e32 v22, v2
	v_mov_b32_e32 v23, v2
	v_mov_b32_e32 v24, v2
	v_mov_b32_e32 v25, v2
	v_mov_b32_e32 v30, v2
	v_mov_b32_e32 v31, v2
	v_mov_b32_e32 v32, v2
	v_mov_b32_e32 v33, v2
	v_mov_b32_e32 v38, v2
	v_mov_b32_e32 v39, v2
	v_mov_b32_e32 v40, v2
	v_mov_b32_e32 v41, v2
	v_mov_b32_e32 v46, v2
	v_mov_b32_e32 v47, v2
	v_mov_b32_e32 v48, v2
	v_mov_b32_e32 v49, v2
	v_mov_b32_e32 v50, v2
	v_mov_b32_e32 v51, v2
	v_mov_b32_e32 v52, v2
	v_mov_b32_e32 v53, v2
	v_mov_b32_e32 v54, v2
	v_mov_b32_e32 v55, v2
	v_mov_b32_e32 v56, v2
	v_mov_b32_e32 v57, v2
	v_mov_b32_e32 v58, v2
	v_mov_b32_e32 v59, v2
	v_mov_b32_e32 v60, v2
	v_mov_b32_e32 v61, v2
	v_mov_b32_e32 v62, v2
	v_mov_b32_e32 v63, v2
	v_mov_b32_e32 v64, v2
	v_mov_b32_e32 v65, v2
	v_mov_b32_e32 v66, v2
	v_mov_b32_e32 v67, v2
	v_mov_b32_e32 v68, v2
	v_mov_b32_e32 v69, v2
	v_mov_b32_e32 v70, v2
	v_mov_b32_e32 v71, v2
	v_mov_b32_e32 v72, v2
	v_mov_b32_e32 v73, v2
	v_mov_b32_e32 v74, v2
	v_mov_b32_e32 v75, v2
	v_mov_b32_e32 v76, v2
	v_mov_b32_e32 v77, v2
	v_mov_b32_e32 v78, v2
	v_mov_b32_e32 v79, v2
	v_mov_b32_e32 v80, v2
	v_mov_b32_e32 v81, v2
	v_mov_b32_e32 v82, v2
	v_mov_b32_e32 v83, v2
	v_mov_b32_e32 v84, v2
	v_mov_b32_e32 v85, v2
	v_mov_b32_e32 v90, v2
	v_mov_b32_e32 v91, v2
	v_mov_b32_e32 v92, v2
	v_mov_b32_e32 v93, v2
	v_mov_b32_e32 v98, v2
	v_mov_b32_e32 v99, v2
	v_mov_b32_e32 v100, v2
	v_mov_b32_e32 v101, v2
	v_mov_b32_e32 v106, v2
	v_mov_b32_e32 v107, v2
	v_mov_b32_e32 v108, v2
	v_mov_b32_e32 v109, v2
	v_mov_b32_e32 v86, v2
	v_mov_b32_e32 v87, v2
	v_mov_b32_e32 v88, v2
	v_mov_b32_e32 v89, v2
	v_mov_b32_e32 v94, v2
	v_mov_b32_e32 v95, v2
	v_mov_b32_e32 v96, v2
	v_mov_b32_e32 v97, v2
	v_mov_b32_e32 v102, v2
	v_mov_b32_e32 v103, v2
	v_mov_b32_e32 v104, v2
	v_mov_b32_e32 v105, v2
	v_mov_b32_e32 v110, v2
	v_mov_b32_e32 v111, v2
	v_mov_b32_e32 v112, v2
	v_mov_b32_e32 v113, v2
	v_mov_b32_e32 v114, v2
	v_mov_b32_e32 v115, v2
	v_mov_b32_e32 v116, v2
	v_mov_b32_e32 v117, v2
	v_mov_b32_e32 v118, v2
	v_mov_b32_e32 v119, v2
	v_mov_b32_e32 v120, v2
	v_mov_b32_e32 v121, v2
	v_mov_b32_e32 v122, v2
	v_mov_b32_e32 v123, v2
	v_mov_b32_e32 v124, v2
	v_mov_b32_e32 v125, v2
	v_mov_b32_e32 v126, v2
	v_mov_b32_e32 v127, v2
	v_mov_b32_e32 v128, v2
	v_mov_b32_e32 v129, v2
	v_readlane_b32 s52, v253, 54
	v_readlane_b32 s53, v253, 55
	v_readlane_b32 s54, v253, 56
	v_readlane_b32 s55, v253, 57
	v_readlane_b32 s56, v253, 58
	v_readlane_b32 s57, v253, 59
	v_readlane_b32 s58, v253, 60
	v_readlane_b32 s59, v253, 61
	v_readlane_b32 s60, v253, 62
	v_readlane_b32 s61, v253, 63
	v_readlane_b32 s62, v254, 0
	v_readlane_b32 s63, v254, 1
	v_add_u32_e32 v141, 0x10000, v138
	ds_read_b128 v[142:145], v141
	ds_read_b128 v[146:149], v141 offset:1024
	ds_read_b128 v[150:153], v141 offset:2048
	ds_read_b128 v[154:157], v141 offset:3072
.LBB0_240:
	s_add_u32 s22, s80, 0xfff80080
	s_addc_u32 s23, s81, -1
	s_add_i32 s52, 0, 0x10000
	s_cmp_eq_u32 s51, 28
	s_cselect_b32 s23, s21, s23
	s_cselect_b32 s22, s47, s22
	s_cselect_b32 s83, s19, s50
	s_cselect_b32 s82, s48, s49
	v_lshl_add_u64 v[178:179], s[80:81], 0, v[134:135]
	s_add_i32 m0, s27, 0xc000
	ds_read_b128 v[158:161], v140
	ds_read_b128 v[162:165], v140 offset:1024
	ds_read_b128 v[166:169], v140 offset:2048
	ds_read_b128 v[170:173], v140 offset:3072
	ds_read_b128 v[174:177], v140 offset:4096
	ds_read_b128 v[192:195], v140 offset:5120
	ds_read_b128 v[196:199], v140 offset:6144
	ds_read_b128 v[200:203], v140 offset:7168
	global_load_lds_dwordx4 v[178:179], off
	v_lshl_add_u64 v[178:179], s[80:81], 0, v[136:137]
	s_add_i32 m0, s27, 0xe000
	s_nop 0
	global_load_lds_dwordx4 v[178:179], off
	s_waitcnt lgkmcnt(8)
	s_barrier
	s_waitcnt lgkmcnt(0)
	s_setprio 1
	s_waitcnt lgkmcnt(0)
	v_mfma_f32_16x16x32_bf16 v[126:129], v[142:145], v[158:161], v[126:129]
	v_mfma_f32_16x16x32_bf16 v[122:125], v[150:153], v[158:161], v[122:125]
	v_mfma_f32_16x16x32_bf16 v[118:121], v[142:145], v[166:169], v[118:121]
	v_mfma_f32_16x16x32_bf16 v[114:117], v[150:153], v[166:169], v[114:117]
	v_mfma_f32_16x16x32_bf16 v[110:113], v[142:145], v[174:177], v[110:113]
	v_mfma_f32_16x16x32_bf16 v[102:105], v[150:153], v[174:177], v[102:105]
	v_mfma_f32_16x16x32_bf16 v[94:97], v[142:145], v[196:199], v[94:97]
	v_mfma_f32_16x16x32_bf16 v[86:89], v[150:153], v[196:199], v[86:89]
	v_mfma_f32_16x16x32_bf16 v[126:129], v[146:149], v[162:165], v[126:129]
	v_mfma_f32_16x16x32_bf16 v[122:125], v[154:157], v[162:165], v[122:125]
	v_mfma_f32_16x16x32_bf16 v[118:121], v[146:149], v[170:173], v[118:121]
	v_mfma_f32_16x16x32_bf16 v[114:117], v[154:157], v[170:173], v[114:117]
	v_mfma_f32_16x16x32_bf16 v[110:113], v[146:149], v[192:195], v[110:113]
	v_mfma_f32_16x16x32_bf16 v[102:105], v[154:157], v[192:195], v[102:105]
	v_mfma_f32_16x16x32_bf16 v[94:97], v[146:149], v[200:203], v[94:97]
	v_mfma_f32_16x16x32_bf16 v[86:89], v[154:157], v[200:203], v[86:89]
	s_setprio 0
	s_barrier
	s_add_i32 s54, 0, 0x14000
	s_add_i32 s52, s52, s26
	v_add_u32_e32 v141, s54, v138
	v_lshl_add_u64 v[178:179], s[82:83], 0, v[132:133]
	s_mov_b32 m0, s52
	ds_read_b128 v[204:207], v141
	ds_read_b128 v[208:211], v141 offset:1024
	ds_read_b128 v[224:227], v141 offset:2048
	ds_read_b128 v[228:231], v141 offset:3072
	global_load_lds_dwordx4 v[178:179], off
	v_lshl_add_u64 v[212:213], s[82:83], 0, v[130:131]
	s_add_i32 m0, s52, 0x2000
	s_nop 0
	global_load_lds_dwordx4 v[212:213], off
	s_barrier
	s_waitcnt lgkmcnt(0)
	s_setprio 1
	s_waitcnt lgkmcnt(0)
	v_mfma_f32_16x16x32_bf16 v[106:109], v[204:207], v[158:161], v[106:109]
	v_mfma_f32_16x16x32_bf16 v[98:101], v[224:227], v[158:161], v[98:101]
	v_mfma_f32_16x16x32_bf16 v[90:93], v[204:207], v[166:169], v[90:93]
	v_mfma_f32_16x16x32_bf16 v[82:85], v[224:227], v[166:169], v[82:85]
	v_mfma_f32_16x16x32_bf16 v[78:81], v[204:207], v[174:177], v[78:81]
	v_mfma_f32_16x16x32_bf16 v[74:77], v[224:227], v[174:177], v[74:77]
	v_mfma_f32_16x16x32_bf16 v[70:73], v[204:207], v[196:199], v[70:73]
	v_mfma_f32_16x16x32_bf16 v[66:69], v[224:227], v[196:199], v[66:69]
	v_mfma_f32_16x16x32_bf16 v[106:109], v[208:211], v[162:165], v[106:109]
	v_mfma_f32_16x16x32_bf16 v[98:101], v[228:231], v[162:165], v[98:101]
	v_mfma_f32_16x16x32_bf16 v[90:93], v[208:211], v[170:173], v[90:93]
	v_mfma_f32_16x16x32_bf16 v[82:85], v[228:231], v[170:173], v[82:85]
	v_mfma_f32_16x16x32_bf16 v[78:81], v[208:211], v[192:195], v[78:81]
	v_mfma_f32_16x16x32_bf16 v[74:77], v[228:231], v[192:195], v[74:77]
	v_mfma_f32_16x16x32_bf16 v[70:73], v[208:211], v[200:203], v[70:73]
	v_mfma_f32_16x16x32_bf16 v[66:69], v[228:231], v[200:203], v[66:69]
	s_setprio 0
	s_mov_b32 m0, s27
	v_lshl_add_u64 v[232:233], s[22:23], 0, v[132:133]
	s_barrier
	ds_read_b128 v[158:161], v140 offset:16384
	ds_read_b128 v[162:165], v140 offset:17408
	ds_read_b128 v[166:169], v140 offset:18432
	ds_read_b128 v[170:173], v140 offset:19456
	ds_read_b128 v[174:177], v140 offset:20480
	ds_read_b128 v[192:195], v140 offset:21504
	ds_read_b128 v[196:199], v140 offset:22528
	ds_read_b128 v[200:203], v140 offset:23552
	global_load_lds_dwordx4 v[232:233], off
	v_lshl_add_u64 v[234:235], s[22:23], 0, v[130:131]
	s_mov_b32 m0, s28
	s_nop 0
	global_load_lds_dwordx4 v[234:235], off
	s_waitcnt vmcnt(10)
	s_barrier
	s_waitcnt lgkmcnt(0)
	s_setprio 1
	s_waitcnt lgkmcnt(0)
	v_mfma_f32_16x16x32_bf16 v[62:65], v[142:145], v[158:161], v[62:65]
	v_mfma_f32_16x16x32_bf16 v[58:61], v[150:153], v[158:161], v[58:61]
	v_mfma_f32_16x16x32_bf16 v[54:57], v[142:145], v[166:169], v[54:57]
	v_mfma_f32_16x16x32_bf16 v[50:53], v[150:153], v[166:169], v[50:53]
	v_mfma_f32_16x16x32_bf16 v[46:49], v[142:145], v[174:177], v[46:49]
	v_mfma_f32_16x16x32_bf16 v[38:41], v[150:153], v[174:177], v[38:41]
	v_mfma_f32_16x16x32_bf16 v[30:33], v[142:145], v[196:199], v[30:33]
	v_mfma_f32_16x16x32_bf16 v[22:25], v[150:153], v[196:199], v[22:25]
	v_mfma_f32_16x16x32_bf16 v[62:65], v[146:149], v[162:165], v[62:65]
	v_mfma_f32_16x16x32_bf16 v[58:61], v[154:157], v[162:165], v[58:61]
	v_mfma_f32_16x16x32_bf16 v[54:57], v[146:149], v[170:173], v[54:57]
	v_mfma_f32_16x16x32_bf16 v[50:53], v[154:157], v[170:173], v[50:53]
	v_mfma_f32_16x16x32_bf16 v[46:49], v[146:149], v[192:195], v[46:49]
	v_mfma_f32_16x16x32_bf16 v[38:41], v[154:157], v[192:195], v[38:41]
	v_mfma_f32_16x16x32_bf16 v[30:33], v[146:149], v[200:203], v[30:33]
	v_mfma_f32_16x16x32_bf16 v[22:25], v[154:157], v[200:203], v[22:25]
	s_setprio 0
	s_barrier
	s_add_u32 s52, s82, 0x80000
	s_addc_u32 s53, s83, 0
	s_add_i32 s54, s54, s26
	v_lshl_add_u64 v[142:143], s[52:53], 0, v[132:133]
	s_mov_b32 m0, s54
	s_nop 0
	global_load_lds_dwordx4 v[142:143], off
	v_lshl_add_u64 v[142:143], s[52:53], 0, v[130:131]
	s_add_i32 m0, s54, 0x2000
	s_nop 0
	global_load_lds_dwordx4 v[142:143], off
	v_add_u32_e32 v141, 0x18000, v138
	ds_read_b128 v[142:145], v141
	ds_read_b128 v[146:149], v141 offset:1024
	ds_read_b128 v[150:153], v141 offset:2048
	ds_read_b128 v[154:157], v141 offset:3072
	s_waitcnt vmcnt(6)
	s_barrier
	s_setprio 1
	v_mfma_f32_16x16x32_bf16 v[42:45], v[204:207], v[158:161], v[42:45]
	v_mfma_f32_16x16x32_bf16 v[34:37], v[224:227], v[158:161], v[34:37]
	v_mfma_f32_16x16x32_bf16 v[26:29], v[204:207], v[166:169], v[26:29]
	v_mfma_f32_16x16x32_bf16 v[18:21], v[224:227], v[166:169], v[18:21]
	v_mfma_f32_16x16x32_bf16 v[14:17], v[204:207], v[174:177], v[14:17]
	v_mfma_f32_16x16x32_bf16 v[10:13], v[224:227], v[174:177], v[10:13]
	v_mfma_f32_16x16x32_bf16 v[6:9], v[204:207], v[196:199], v[6:9]
	v_mfma_f32_16x16x32_bf16 v[2:5], v[224:227], v[196:199], v[2:5]
	v_mfma_f32_16x16x32_bf16 v[42:45], v[208:211], v[162:165], v[42:45]
	v_mfma_f32_16x16x32_bf16 v[34:37], v[228:231], v[162:165], v[34:37]
	v_mfma_f32_16x16x32_bf16 v[26:29], v[208:211], v[170:173], v[26:29]
	v_mfma_f32_16x16x32_bf16 v[18:21], v[228:231], v[170:173], v[18:21]
	v_mfma_f32_16x16x32_bf16 v[14:17], v[208:211], v[192:195], v[14:17]
	v_mfma_f32_16x16x32_bf16 v[10:13], v[228:231], v[192:195], v[10:13]
	v_mfma_f32_16x16x32_bf16 v[6:9], v[208:211], v[200:203], v[6:9]
	v_mfma_f32_16x16x32_bf16 v[2:5], v[228:231], v[200:203], v[2:5]
	s_setprio 0
	s_add_i32 s52, 0, 0x18000
	s_barrier
	s_add_u32 s22, s22, 0x80000
	s_addc_u32 s23, s23, 0
	s_mov_b32 m0, s29
	v_lshl_add_u64 v[204:205], s[22:23], 0, v[132:133]
	ds_read_b128 v[158:161], v140 offset:32768
	ds_read_b128 v[162:165], v140 offset:33792
	ds_read_b128 v[166:169], v140 offset:34816
	ds_read_b128 v[170:173], v140 offset:35840
	ds_read_b128 v[174:177], v140 offset:36864
	ds_read_b128 v[192:195], v140 offset:37888
	ds_read_b128 v[196:199], v140 offset:38912
	ds_read_b128 v[200:203], v140 offset:39936
	global_load_lds_dwordx4 v[204:205], off
	v_lshl_add_u64 v[204:205], s[22:23], 0, v[130:131]
	s_mov_b32 m0, s36
	s_nop 0
	global_load_lds_dwordx4 v[204:205], off
	s_waitcnt lgkmcnt(8)
	s_barrier
	s_waitcnt lgkmcnt(0)
	s_setprio 1
	s_waitcnt lgkmcnt(0)
	v_mfma_f32_16x16x32_bf16 v[126:129], v[142:145], v[158:161], v[126:129]
	v_mfma_f32_16x16x32_bf16 v[122:125], v[150:153], v[158:161], v[122:125]
	v_mfma_f32_16x16x32_bf16 v[118:121], v[142:145], v[166:169], v[118:121]
	v_mfma_f32_16x16x32_bf16 v[114:117], v[150:153], v[166:169], v[114:117]
	v_mfma_f32_16x16x32_bf16 v[110:113], v[142:145], v[174:177], v[110:113]
	v_mfma_f32_16x16x32_bf16 v[102:105], v[150:153], v[174:177], v[102:105]
	v_mfma_f32_16x16x32_bf16 v[94:97], v[142:145], v[196:199], v[94:97]
	v_mfma_f32_16x16x32_bf16 v[86:89], v[150:153], v[196:199], v[86:89]
	v_mfma_f32_16x16x32_bf16 v[126:129], v[146:149], v[162:165], v[126:129]
	v_mfma_f32_16x16x32_bf16 v[122:125], v[154:157], v[162:165], v[122:125]
	v_mfma_f32_16x16x32_bf16 v[118:121], v[146:149], v[170:173], v[118:121]
	v_mfma_f32_16x16x32_bf16 v[114:117], v[154:157], v[170:173], v[114:117]
	v_mfma_f32_16x16x32_bf16 v[110:113], v[146:149], v[192:195], v[110:113]
	v_mfma_f32_16x16x32_bf16 v[102:105], v[154:157], v[192:195], v[102:105]
	v_mfma_f32_16x16x32_bf16 v[94:97], v[146:149], v[200:203], v[94:97]
	v_mfma_f32_16x16x32_bf16 v[86:89], v[154:157], v[200:203], v[86:89]
	s_setprio 0
	s_barrier
	s_add_i32 s53, 0, 0x1c000
	s_add_i32 s22, s52, s26
	v_add_u32_e32 v141, s53, v138
	v_lshl_add_u64 v[178:179], v[178:179], 0, s[78:79]
	s_mov_b32 m0, s22
	ds_read_b128 v[204:207], v141
	ds_read_b128 v[208:211], v141 offset:1024
	ds_read_b128 v[224:227], v141 offset:2048
	ds_read_b128 v[228:231], v141 offset:3072
	global_load_lds_dwordx4 v[178:179], off
	v_lshl_add_u64 v[178:179], v[212:213], 0, s[78:79]
	s_add_i32 m0, s22, 0x2000
	s_nop 0
	global_load_lds_dwordx4 v[178:179], off
	s_barrier
	s_waitcnt lgkmcnt(0)
	s_setprio 1
	s_waitcnt lgkmcnt(0)
	v_mfma_f32_16x16x32_bf16 v[106:109], v[204:207], v[158:161], v[106:109]
	v_mfma_f32_16x16x32_bf16 v[98:101], v[224:227], v[158:161], v[98:101]
	v_mfma_f32_16x16x32_bf16 v[90:93], v[204:207], v[166:169], v[90:93]
	v_mfma_f32_16x16x32_bf16 v[82:85], v[224:227], v[166:169], v[82:85]
	v_mfma_f32_16x16x32_bf16 v[78:81], v[204:207], v[174:177], v[78:81]
	v_mfma_f32_16x16x32_bf16 v[74:77], v[224:227], v[174:177], v[74:77]
	v_mfma_f32_16x16x32_bf16 v[70:73], v[204:207], v[196:199], v[70:73]
	v_mfma_f32_16x16x32_bf16 v[66:69], v[224:227], v[196:199], v[66:69]
	v_mfma_f32_16x16x32_bf16 v[106:109], v[208:211], v[162:165], v[106:109]
	v_mfma_f32_16x16x32_bf16 v[98:101], v[228:231], v[162:165], v[98:101]
	v_mfma_f32_16x16x32_bf16 v[90:93], v[208:211], v[170:173], v[90:93]
	v_mfma_f32_16x16x32_bf16 v[82:85], v[228:231], v[170:173], v[82:85]
	v_mfma_f32_16x16x32_bf16 v[78:81], v[208:211], v[192:195], v[78:81]
	v_mfma_f32_16x16x32_bf16 v[74:77], v[228:231], v[192:195], v[74:77]
	v_mfma_f32_16x16x32_bf16 v[70:73], v[208:211], v[200:203], v[70:73]
	v_mfma_f32_16x16x32_bf16 v[66:69], v[228:231], v[200:203], v[66:69]
	s_setprio 0
	s_mov_b32 m0, s42
	v_lshl_add_u64 v[178:179], v[232:233], 0, s[78:79]
	s_barrier
	ds_read_b128 v[158:161], v140 offset:49152
	ds_read_b128 v[162:165], v140 offset:50176
	ds_read_b128 v[166:169], v140 offset:51200
	ds_read_b128 v[170:173], v140 offset:52224
	ds_read_b128 v[174:177], v140 offset:53248
	ds_read_b128 v[192:195], v140 offset:54272
	ds_read_b128 v[196:199], v140 offset:55296
	ds_read_b128 v[200:203], v140 offset:56320
	global_load_lds_dwordx4 v[178:179], off
	v_lshl_add_u64 v[178:179], v[234:235], 0, s[78:79]
	s_mov_b32 m0, s43
	s_nop 0
	global_load_lds_dwordx4 v[178:179], off
	s_waitcnt vmcnt(10)
	s_barrier
	s_waitcnt lgkmcnt(0)
	s_setprio 1
	s_waitcnt lgkmcnt(0)
	v_mfma_f32_16x16x32_bf16 v[62:65], v[142:145], v[158:161], v[62:65]
	v_mfma_f32_16x16x32_bf16 v[58:61], v[150:153], v[158:161], v[58:61]
	v_mfma_f32_16x16x32_bf16 v[54:57], v[142:145], v[166:169], v[54:57]
	v_mfma_f32_16x16x32_bf16 v[50:53], v[150:153], v[166:169], v[50:53]
	v_mfma_f32_16x16x32_bf16 v[46:49], v[142:145], v[174:177], v[46:49]
	v_mfma_f32_16x16x32_bf16 v[38:41], v[150:153], v[174:177], v[38:41]
	v_mfma_f32_16x16x32_bf16 v[30:33], v[142:145], v[196:199], v[30:33]
	v_mfma_f32_16x16x32_bf16 v[22:25], v[150:153], v[196:199], v[22:25]
	v_mfma_f32_16x16x32_bf16 v[62:65], v[146:149], v[162:165], v[62:65]
	v_mfma_f32_16x16x32_bf16 v[58:61], v[154:157], v[162:165], v[58:61]
	v_mfma_f32_16x16x32_bf16 v[54:57], v[146:149], v[170:173], v[54:57]
	v_mfma_f32_16x16x32_bf16 v[50:53], v[154:157], v[170:173], v[50:53]
	v_mfma_f32_16x16x32_bf16 v[46:49], v[146:149], v[192:195], v[46:49]
	v_mfma_f32_16x16x32_bf16 v[38:41], v[154:157], v[192:195], v[38:41]
	v_mfma_f32_16x16x32_bf16 v[30:33], v[146:149], v[200:203], v[30:33]
	v_mfma_f32_16x16x32_bf16 v[22:25], v[154:157], v[200:203], v[22:25]
	s_setprio 0
	s_barrier
	s_add_u32 s22, s82, 0x80080
	s_addc_u32 s23, s83, 0
	s_add_i32 s52, s53, s26
	v_lshl_add_u64 v[142:143], s[22:23], 0, v[132:133]
	s_mov_b32 m0, s52
	s_nop 0
	global_load_lds_dwordx4 v[142:143], off
	v_lshl_add_u64 v[142:143], s[22:23], 0, v[130:131]
	s_add_i32 m0, s52, 0x2000
	s_nop 0
	global_load_lds_dwordx4 v[142:143], off
	v_add_u32_e32 v141, 0x10000, v138
	ds_read_b128 v[142:145], v141
	ds_read_b128 v[146:149], v141 offset:1024
	ds_read_b128 v[150:153], v141 offset:2048
	ds_read_b128 v[154:157], v141 offset:3072
	s_waitcnt vmcnt(6)
	s_barrier
	s_setprio 1
	v_mfma_f32_16x16x32_bf16 v[42:45], v[204:207], v[158:161], v[42:45]
	v_mfma_f32_16x16x32_bf16 v[34:37], v[224:227], v[158:161], v[34:37]
	v_mfma_f32_16x16x32_bf16 v[26:29], v[204:207], v[166:169], v[26:29]
	v_mfma_f32_16x16x32_bf16 v[18:21], v[224:227], v[166:169], v[18:21]
	v_mfma_f32_16x16x32_bf16 v[14:17], v[204:207], v[174:177], v[14:17]
	v_mfma_f32_16x16x32_bf16 v[10:13], v[224:227], v[174:177], v[10:13]
	v_mfma_f32_16x16x32_bf16 v[6:9], v[204:207], v[196:199], v[6:9]
	v_mfma_f32_16x16x32_bf16 v[2:5], v[224:227], v[196:199], v[2:5]
	v_mfma_f32_16x16x32_bf16 v[42:45], v[208:211], v[162:165], v[42:45]
	v_mfma_f32_16x16x32_bf16 v[34:37], v[228:231], v[162:165], v[34:37]
	v_mfma_f32_16x16x32_bf16 v[26:29], v[208:211], v[170:173], v[26:29]
	v_mfma_f32_16x16x32_bf16 v[18:21], v[228:231], v[170:173], v[18:21]
	v_mfma_f32_16x16x32_bf16 v[14:17], v[208:211], v[192:195], v[14:17]
	v_mfma_f32_16x16x32_bf16 v[10:13], v[228:231], v[192:195], v[10:13]
	v_mfma_f32_16x16x32_bf16 v[6:9], v[208:211], v[200:203], v[6:9]
	v_mfma_f32_16x16x32_bf16 v[2:5], v[228:231], v[200:203], v[2:5]
	s_setprio 0
	s_add_i32 s51, s51, 2
	s_add_u32 s80, s80, 0x100
	s_addc_u32 s81, s81, 0
	s_add_u32 s49, s49, 0x100
	s_addc_u32 s50, s50, 0
	s_cmp_gt_u32 s51, 29
	s_barrier
	s_cbranch_scc0 .LBB0_240
	s_waitcnt lgkmcnt(0)
	v_readlane_b32 s48, v254, 40
	v_lshl_or_b32 v142, s45, 8, v139
	v_readlane_b32 s52, v254, 44
	v_readlane_b32 s53, v254, 45
	v_lshl_add_u32 v141, s46, 8, v1
	v_ashrrev_i32_e32 v143, 31, v142
	v_mov_b64_e32 v[144:145], s[52:53]
	s_movk_i32 s19, 0x1400
	v_mad_i64_i32 v[146:147], s[22:23], v141, s19, v[144:145]
	v_lshlrev_b64 v[142:143], 2, v[142:143]
	v_lshl_add_u64 v[146:147], v[146:147], 0, v[142:143]
	global_store_dwordx4 v[146:147], v[126:129], off
	global_store_dwordx4 v[146:147], v[122:125], off offset:64
	global_store_dwordx4 v[146:147], v[106:109], off offset:512
	global_store_dwordx4 v[146:147], v[98:101], off offset:576
	s_movk_i32 s94, 0x1400
	s_and_b64 vcc, exec, s[0:1]
	v_or_b32_e32 v98, 16, v141
	v_mad_i64_i32 v[98:99], s[22:23], v98, s19, v[144:145]
	v_lshl_add_u64 v[98:99], v[98:99], 0, v[142:143]
	global_store_dwordx4 v[98:99], v[118:121], off
	global_store_dwordx4 v[98:99], v[114:117], off offset:64
	global_store_dwordx4 v[98:99], v[90:93], off offset:512
	global_store_dwordx4 v[98:99], v[82:85], off offset:576
	s_mov_b32 s45, s18
	s_mov_b32 s46, s20
	v_or_b32_e32 v82, 32, v141
	v_mad_i64_i32 v[82:83], s[22:23], v82, s19, v[144:145]
	v_lshl_add_u64 v[82:83], v[82:83], 0, v[142:143]
	global_store_dwordx4 v[82:83], v[110:113], off
	global_store_dwordx4 v[82:83], v[102:105], off offset:64
	global_store_dwordx4 v[82:83], v[78:81], off offset:512
	global_store_dwordx4 v[82:83], v[74:77], off offset:576
	s_mov_b64 s[80:81], s[30:31]
	v_readlane_b32 s49, v254, 41
	v_or_b32_e32 v74, 48, v141
	v_mad_i64_i32 v[74:75], s[22:23], v74, s19, v[144:145]
	v_lshl_add_u64 v[74:75], v[74:75], 0, v[142:143]
	global_store_dwordx4 v[74:75], v[94:97], off
	global_store_dwordx4 v[74:75], v[86:89], off offset:64
	global_store_dwordx4 v[74:75], v[70:73], off offset:512
	global_store_dwordx4 v[74:75], v[66:69], off offset:576
	v_readlane_b32 s50, v254, 42
	v_readlane_b32 s51, v254, 43
	v_add_u32_e32 v66, 0x80, v141
	v_mad_i64_i32 v[66:67], s[22:23], v66, s19, v[144:145]
	v_lshl_add_u64 v[66:67], v[66:67], 0, v[142:143]
	global_store_dwordx4 v[66:67], v[62:65], off
	global_store_dwordx4 v[66:67], v[58:61], off offset:64
	global_store_dwordx4 v[66:67], v[42:45], off offset:512
	global_store_dwordx4 v[66:67], v[34:37], off offset:576
	v_readlane_b32 s54, v254, 46
	v_readlane_b32 s55, v254, 47
	v_add_u32_e32 v34, 0x90, v141
	v_mad_i64_i32 v[34:35], s[22:23], v34, s19, v[144:145]
	v_lshl_add_u64 v[34:35], v[34:35], 0, v[142:143]
	global_store_dwordx4 v[34:35], v[54:57], off
	global_store_dwordx4 v[34:35], v[50:53], off offset:64
	global_store_dwordx4 v[34:35], v[26:29], off offset:512
	global_store_dwordx4 v[34:35], v[18:21], off offset:576
	v_readlane_b32 s56, v254, 48
	v_readlane_b32 s57, v254, 49
	v_add_u32_e32 v18, 0xa0, v141
	v_mad_i64_i32 v[18:19], s[22:23], v18, s19, v[144:145]
	v_lshl_add_u64 v[18:19], v[18:19], 0, v[142:143]
	global_store_dwordx4 v[18:19], v[46:49], off
	global_store_dwordx4 v[18:19], v[38:41], off offset:64
	global_store_dwordx4 v[18:19], v[14:17], off offset:512
	global_store_dwordx4 v[18:19], v[10:13], off offset:576
	v_readlane_b32 s58, v254, 50
	v_readlane_b32 s59, v254, 51
	v_add_u32_e32 v10, 0xb0, v141
	v_mad_i64_i32 v[10:11], s[22:23], v10, s19, v[144:145]
	v_lshl_add_u64 v[10:11], v[10:11], 0, v[142:143]
	s_mov_b64 s[22:23], s[38:39]
	v_readlane_b32 s60, v254, 52
	v_readlane_b32 s61, v254, 53
	v_readlane_b32 s62, v254, 54
	v_readlane_b32 s63, v254, 55
	global_store_dwordx4 v[10:11], v[30:33], off
	global_store_dwordx4 v[10:11], v[22:25], off offset:64
	global_store_dwordx4 v[10:11], v[6:9], off offset:512
	global_store_dwordx4 v[10:11], v[2:5], off offset:576
	s_cbranch_vccz .LBB0_237
	s_waitcnt vmcnt(0)
	v_readlane_b32 s44, v255, 30
	s_cmpk_gt_u32 s25, 0xff
	v_readlane_b32 s45, v255, 31
	v_readlane_b32 s42, v255, 32
	s_cbranch_scc1 .LBB0_244
	s_barrier

.LBB0_356:
	s_ashr_i32 s31, s30, 31
	v_readlane_b32 s52, v254, 40
	s_lshl_b64 s[48:49], s[30:31], 18
	v_readlane_b32 s60, v254, 48
	v_cmp_lt_i64_e32 vcc, s[80:81], v[184:185]
	v_readlane_b32 s61, v254, 49
	s_add_u32 s80, s60, s48
	s_addc_u32 s81, s61, s49
	v_readlane_b32 s53, v254, 41
	v_readlane_b32 s54, v254, 42
	v_readlane_b32 s55, v254, 43
	v_readlane_b32 s56, v254, 44
	v_readlane_b32 s57, v254, 45
	v_readlane_b32 s58, v254, 46
	v_readlane_b32 s59, v254, 47
	v_readlane_b32 s62, v254, 50
	v_readlane_b32 s63, v254, 51
	v_readlane_b32 s64, v254, 52
	v_readlane_b32 s65, v254, 53
	v_readlane_b32 s66, v254, 54
	v_readlane_b32 s67, v254, 55
	s_and_b64 s[48:49], vcc, exec
	s_cselect_b32 s31, s81, s21
	s_cselect_b32 s47, s80, s20
	s_ashr_i32 s19, s18, 31
	v_readlane_b32 s52, v253, 50
	s_lshl_b64 s[48:49], s[18:19], 18
	v_readlane_b32 s56, v253, 54
	v_readlane_b32 s57, v253, 55
	s_add_u32 s82, s56, s48
	s_addc_u32 s83, s57, s49
	s_and_b64 s[48:49], vcc, exec
	s_cselect_b32 s19, s83, s23
	s_cselect_b32 s48, s82, s22
	s_add_u32 s20, s20, 0x20080
	s_addc_u32 s21, s21, 0
	s_add_u32 s49, s22, 0x100
	v_mov_b32_e32 v2, 0
	s_addc_u32 s50, s23, 0
	s_mov_b32 s51, -2
	v_mov_b32_e32 v3, v2
	v_mov_b32_e32 v4, v2
	v_mov_b32_e32 v5, v2
	v_mov_b32_e32 v6, v2
	v_mov_b32_e32 v7, v2
	v_mov_b32_e32 v8, v2
	v_mov_b32_e32 v9, v2
	v_mov_b32_e32 v10, v2
	v_mov_b32_e32 v11, v2
	v_mov_b32_e32 v12, v2
	v_mov_b32_e32 v13, v2
	v_mov_b32_e32 v14, v2
	v_mov_b32_e32 v15, v2
	v_mov_b32_e32 v16, v2
	v_mov_b32_e32 v17, v2
	v_mov_b32_e32 v26, v2
	v_mov_b32_e32 v27, v2
	v_mov_b32_e32 v28, v2
	v_mov_b32_e32 v29, v2
	v_mov_b32_e32 v30, v2
	v_mov_b32_e32 v31, v2
	v_mov_b32_e32 v32, v2
	v_mov_b32_e32 v33, v2
	v_mov_b32_e32 v42, v2
	v_mov_b32_e32 v43, v2
	v_mov_b32_e32 v44, v2
	v_mov_b32_e32 v45, v2
	v_mov_b32_e32 v46, v2
	v_mov_b32_e32 v47, v2
	v_mov_b32_e32 v48, v2
	v_mov_b32_e32 v49, v2
	v_mov_b32_e32 v18, v2
	v_mov_b32_e32 v19, v2
	v_mov_b32_e32 v20, v2
	v_mov_b32_e32 v21, v2
	v_mov_b32_e32 v22, v2
	v_mov_b32_e32 v23, v2
	v_mov_b32_e32 v24, v2
	v_mov_b32_e32 v25, v2
	v_mov_b32_e32 v34, v2
	v_mov_b32_e32 v35, v2
	v_mov_b32_e32 v36, v2
	v_mov_b32_e32 v37, v2
	v_mov_b32_e32 v38, v2
	v_mov_b32_e32 v39, v2
	v_mov_b32_e32 v40, v2
	v_mov_b32_e32 v41, v2
	v_mov_b32_e32 v50, v2
	v_mov_b32_e32 v51, v2
	v_mov_b32_e32 v52, v2
	v_mov_b32_e32 v53, v2
	v_mov_b32_e32 v54, v2
	v_mov_b32_e32 v55, v2
	v_mov_b32_e32 v56, v2
	v_mov_b32_e32 v57, v2
	v_mov_b32_e32 v58, v2
	v_mov_b32_e32 v59, v2
	v_mov_b32_e32 v60, v2
	v_mov_b32_e32 v61, v2
	v_mov_b32_e32 v62, v2
	v_mov_b32_e32 v63, v2
	v_mov_b32_e32 v64, v2
	v_mov_b32_e32 v65, v2
	v_mov_b32_e32 v66, v2
	v_mov_b32_e32 v67, v2
	v_mov_b32_e32 v68, v2
	v_mov_b32_e32 v69, v2
	v_mov_b32_e32 v70, v2
	v_mov_b32_e32 v71, v2
	v_mov_b32_e32 v72, v2
	v_mov_b32_e32 v73, v2
	v_mov_b32_e32 v74, v2
	v_mov_b32_e32 v75, v2
	v_mov_b32_e32 v76, v2
	v_mov_b32_e32 v77, v2
	v_mov_b32_e32 v78, v2
	v_mov_b32_e32 v79, v2
	v_mov_b32_e32 v80, v2
	v_mov_b32_e32 v81, v2
	v_mov_b32_e32 v90, v2
	v_mov_b32_e32 v91, v2
	v_mov_b32_e32 v92, v2
	v_mov_b32_e32 v93, v2
	v_mov_b32_e32 v94, v2
	v_mov_b32_e32 v95, v2
	v_mov_b32_e32 v96, v2
	v_mov_b32_e32 v97, v2
	v_mov_b32_e32 v106, v2
	v_mov_b32_e32 v107, v2
	v_mov_b32_e32 v108, v2
	v_mov_b32_e32 v109, v2
	v_mov_b32_e32 v110, v2
	v_mov_b32_e32 v111, v2
	v_mov_b32_e32 v112, v2
	v_mov_b32_e32 v113, v2
	v_mov_b32_e32 v82, v2
	v_mov_b32_e32 v83, v2
	v_mov_b32_e32 v84, v2
	v_mov_b32_e32 v85, v2
	v_mov_b32_e32 v86, v2
	v_mov_b32_e32 v87, v2
	v_mov_b32_e32 v88, v2
	v_mov_b32_e32 v89, v2
	v_mov_b32_e32 v98, v2
	v_mov_b32_e32 v99, v2
	v_mov_b32_e32 v100, v2
	v_mov_b32_e32 v101, v2
	v_mov_b32_e32 v102, v2
	v_mov_b32_e32 v103, v2
	v_mov_b32_e32 v104, v2
	v_mov_b32_e32 v105, v2
	v_mov_b32_e32 v114, v2
	v_mov_b32_e32 v115, v2
	v_mov_b32_e32 v116, v2
	v_mov_b32_e32 v117, v2
	v_mov_b32_e32 v118, v2
	v_mov_b32_e32 v119, v2
	v_mov_b32_e32 v120, v2
	v_mov_b32_e32 v121, v2
	v_mov_b32_e32 v122, v2
	v_mov_b32_e32 v123, v2
	v_mov_b32_e32 v124, v2
	v_mov_b32_e32 v125, v2
	v_mov_b32_e32 v126, v2
	v_mov_b32_e32 v127, v2
	v_mov_b32_e32 v128, v2
	v_mov_b32_e32 v129, v2
	v_readlane_b32 s53, v253, 51
	v_readlane_b32 s54, v253, 52
	v_readlane_b32 s55, v253, 53
	v_readlane_b32 s58, v253, 56
	v_readlane_b32 s59, v253, 57
	v_readlane_b32 s60, v253, 58
	v_readlane_b32 s61, v253, 59
	v_readlane_b32 s62, v253, 60
	v_readlane_b32 s63, v253, 61
	v_readlane_b32 s64, v253, 62
	v_readlane_b32 s65, v253, 63
	v_readlane_b32 s66, v254, 0
	v_readlane_b32 s67, v254, 1
	v_add_u32_e32 v145, 0x10000, v142
	ds_read_b128 v[146:149], v145
	ds_read_b128 v[150:153], v145 offset:1024
	ds_read_b128 v[154:157], v145 offset:2048
	ds_read_b128 v[158:161], v145 offset:3072
.LBB0_357:
	s_add_u32 s22, s20, 0xfffe0080
	s_addc_u32 s23, s21, -1
	s_add_i32 s52, 0, 0x10000
	s_cmp_eq_u32 s51, 4
	s_cselect_b32 s23, s31, s23
	s_cselect_b32 s22, s47, s22
	s_cselect_b32 s85, s19, s50
	s_cselect_b32 s84, s48, s49
	v_lshl_add_u64 v[178:179], s[20:21], 0, v[138:139]
	s_add_i32 m0, s27, 0xc000
	ds_read_b128 v[162:165], v144
	ds_read_b128 v[166:169], v144 offset:1024
	ds_read_b128 v[170:173], v144 offset:2048
	ds_read_b128 v[174:177], v144 offset:3072
	ds_read_b128 v[192:195], v144 offset:4096
	ds_read_b128 v[196:199], v144 offset:5120
	ds_read_b128 v[200:203], v144 offset:6144
	ds_read_b128 v[204:207], v144 offset:7168
	global_load_lds_dwordx4 v[178:179], off
	v_lshl_add_u64 v[178:179], s[20:21], 0, v[140:141]
	s_add_i32 m0, s27, 0xe000
	s_nop 0
	global_load_lds_dwordx4 v[178:179], off
	s_waitcnt lgkmcnt(8)
	s_barrier
	s_waitcnt lgkmcnt(0)
	s_setprio 1
	s_waitcnt lgkmcnt(0)
	v_mfma_f32_16x16x32_bf16 v[126:129], v[146:149], v[162:165], v[126:129]
	v_mfma_f32_16x16x32_bf16 v[122:125], v[154:157], v[162:165], v[122:125]
	v_mfma_f32_16x16x32_bf16 v[118:121], v[146:149], v[170:173], v[118:121]
	v_mfma_f32_16x16x32_bf16 v[114:117], v[154:157], v[170:173], v[114:117]
	v_mfma_f32_16x16x32_bf16 v[102:105], v[146:149], v[192:195], v[102:105]
	v_mfma_f32_16x16x32_bf16 v[98:101], v[154:157], v[192:195], v[98:101]
	v_mfma_f32_16x16x32_bf16 v[86:89], v[146:149], v[200:203], v[86:89]
	v_mfma_f32_16x16x32_bf16 v[82:85], v[154:157], v[200:203], v[82:85]
	v_mfma_f32_16x16x32_bf16 v[126:129], v[150:153], v[166:169], v[126:129]
	v_mfma_f32_16x16x32_bf16 v[122:125], v[158:161], v[166:169], v[122:125]
	v_mfma_f32_16x16x32_bf16 v[118:121], v[150:153], v[174:177], v[118:121]
	v_mfma_f32_16x16x32_bf16 v[114:117], v[158:161], v[174:177], v[114:117]
	v_mfma_f32_16x16x32_bf16 v[102:105], v[150:153], v[196:199], v[102:105]
	v_mfma_f32_16x16x32_bf16 v[98:101], v[158:161], v[196:199], v[98:101]
	v_mfma_f32_16x16x32_bf16 v[86:89], v[150:153], v[204:207], v[86:89]
	v_mfma_f32_16x16x32_bf16 v[82:85], v[158:161], v[204:207], v[82:85]
	s_setprio 0
	s_barrier
	s_add_i32 s54, 0, 0x14000
	s_add_i32 s52, s52, s26
	v_add_u32_e32 v145, s54, v142
	v_lshl_add_u64 v[178:179], s[84:85], 0, v[134:135]
	s_mov_b32 m0, s52
	ds_read_b128 v[208:211], v145
	ds_read_b128 v[224:227], v145 offset:1024
	ds_read_b128 v[228:231], v145 offset:2048
	ds_read_b128 v[232:235], v145 offset:3072
	global_load_lds_dwordx4 v[178:179], off
	v_lshl_add_u64 v[212:213], s[84:85], 0, v[130:131]
	s_add_i32 m0, s52, 0x2000
	s_nop 0
	global_load_lds_dwordx4 v[212:213], off
	s_barrier
	s_waitcnt lgkmcnt(0)
	s_setprio 1
	s_waitcnt lgkmcnt(0)
	v_mfma_f32_16x16x32_bf16 v[110:113], v[208:211], v[162:165], v[110:113]
	v_mfma_f32_16x16x32_bf16 v[106:109], v[228:231], v[162:165], v[106:109]
	v_mfma_f32_16x16x32_bf16 v[94:97], v[208:211], v[170:173], v[94:97]
	v_mfma_f32_16x16x32_bf16 v[90:93], v[228:231], v[170:173], v[90:93]
	v_mfma_f32_16x16x32_bf16 v[78:81], v[208:211], v[192:195], v[78:81]
	v_mfma_f32_16x16x32_bf16 v[74:77], v[228:231], v[192:195], v[74:77]
	v_mfma_f32_16x16x32_bf16 v[70:73], v[208:211], v[200:203], v[70:73]
	v_mfma_f32_16x16x32_bf16 v[66:69], v[228:231], v[200:203], v[66:69]
	v_mfma_f32_16x16x32_bf16 v[110:113], v[224:227], v[166:169], v[110:113]
	v_mfma_f32_16x16x32_bf16 v[106:109], v[232:235], v[166:169], v[106:109]
	v_mfma_f32_16x16x32_bf16 v[94:97], v[224:227], v[174:177], v[94:97]
	v_mfma_f32_16x16x32_bf16 v[90:93], v[232:235], v[174:177], v[90:93]
	v_mfma_f32_16x16x32_bf16 v[78:81], v[224:227], v[196:199], v[78:81]
	v_mfma_f32_16x16x32_bf16 v[74:77], v[232:235], v[196:199], v[74:77]
	v_mfma_f32_16x16x32_bf16 v[70:73], v[224:227], v[204:207], v[70:73]
	v_mfma_f32_16x16x32_bf16 v[66:69], v[232:235], v[204:207], v[66:69]
	s_setprio 0
	s_mov_b32 m0, s27
	v_lshl_add_u64 v[236:237], s[22:23], 0, v[136:137]
	s_barrier
	ds_read_b128 v[162:165], v144 offset:16384
	ds_read_b128 v[166:169], v144 offset:17408
	ds_read_b128 v[170:173], v144 offset:18432
	ds_read_b128 v[174:177], v144 offset:19456
	ds_read_b128 v[192:195], v144 offset:20480
	ds_read_b128 v[196:199], v144 offset:21504
	ds_read_b128 v[200:203], v144 offset:22528
	ds_read_b128 v[204:207], v144 offset:23552
	global_load_lds_dwordx4 v[236:237], off
	v_lshl_add_u64 v[238:239], s[22:23], 0, v[132:133]
	s_mov_b32 m0, s28
	s_nop 0
	global_load_lds_dwordx4 v[238:239], off
	s_waitcnt vmcnt(10)
	s_barrier
	s_waitcnt lgkmcnt(0)
	s_setprio 1
	s_waitcnt lgkmcnt(0)
	v_mfma_f32_16x16x32_bf16 v[62:65], v[146:149], v[162:165], v[62:65]
	v_mfma_f32_16x16x32_bf16 v[58:61], v[154:157], v[162:165], v[58:61]
	v_mfma_f32_16x16x32_bf16 v[54:57], v[146:149], v[170:173], v[54:57]
	v_mfma_f32_16x16x32_bf16 v[50:53], v[154:157], v[170:173], v[50:53]
	v_mfma_f32_16x16x32_bf16 v[38:41], v[146:149], v[192:195], v[38:41]
	v_mfma_f32_16x16x32_bf16 v[34:37], v[154:157], v[192:195], v[34:37]
	v_mfma_f32_16x16x32_bf16 v[22:25], v[146:149], v[200:203], v[22:25]
	v_mfma_f32_16x16x32_bf16 v[18:21], v[154:157], v[200:203], v[18:21]
	v_mfma_f32_16x16x32_bf16 v[62:65], v[150:153], v[166:169], v[62:65]
	v_mfma_f32_16x16x32_bf16 v[58:61], v[158:161], v[166:169], v[58:61]
	v_mfma_f32_16x16x32_bf16 v[54:57], v[150:153], v[174:177], v[54:57]
	v_mfma_f32_16x16x32_bf16 v[50:53], v[158:161], v[174:177], v[50:53]
	v_mfma_f32_16x16x32_bf16 v[38:41], v[150:153], v[196:199], v[38:41]
	v_mfma_f32_16x16x32_bf16 v[34:37], v[158:161], v[196:199], v[34:37]
	v_mfma_f32_16x16x32_bf16 v[22:25], v[150:153], v[204:207], v[22:25]
	v_mfma_f32_16x16x32_bf16 v[18:21], v[158:161], v[204:207], v[18:21]
	s_setprio 0
	s_barrier
	s_add_u32 s52, s84, 0x20000
	s_addc_u32 s53, s85, 0
	s_add_i32 s54, s54, s26
	v_lshl_add_u64 v[146:147], s[52:53], 0, v[134:135]
	s_mov_b32 m0, s54
	s_nop 0
	global_load_lds_dwordx4 v[146:147], off
	v_lshl_add_u64 v[146:147], s[52:53], 0, v[130:131]
	s_add_i32 m0, s54, 0x2000
	s_nop 0
	global_load_lds_dwordx4 v[146:147], off
	v_add_u32_e32 v145, 0x18000, v142
	ds_read_b128 v[146:149], v145
	ds_read_b128 v[150:153], v145 offset:1024
	ds_read_b128 v[154:157], v145 offset:2048
	ds_read_b128 v[158:161], v145 offset:3072
	s_waitcnt vmcnt(6)
	s_barrier
	s_setprio 1
	v_mfma_f32_16x16x32_bf16 v[46:49], v[208:211], v[162:165], v[46:49]
	v_mfma_f32_16x16x32_bf16 v[42:45], v[228:231], v[162:165], v[42:45]
	v_mfma_f32_16x16x32_bf16 v[30:33], v[208:211], v[170:173], v[30:33]
	v_mfma_f32_16x16x32_bf16 v[26:29], v[228:231], v[170:173], v[26:29]
	v_mfma_f32_16x16x32_bf16 v[14:17], v[208:211], v[192:195], v[14:17]
	v_mfma_f32_16x16x32_bf16 v[10:13], v[228:231], v[192:195], v[10:13]
	v_mfma_f32_16x16x32_bf16 v[6:9], v[208:211], v[200:203], v[6:9]
	v_mfma_f32_16x16x32_bf16 v[2:5], v[228:231], v[200:203], v[2:5]
	v_mfma_f32_16x16x32_bf16 v[46:49], v[224:227], v[166:169], v[46:49]
	v_mfma_f32_16x16x32_bf16 v[42:45], v[232:235], v[166:169], v[42:45]
	v_mfma_f32_16x16x32_bf16 v[30:33], v[224:227], v[174:177], v[30:33]
	v_mfma_f32_16x16x32_bf16 v[26:29], v[232:235], v[174:177], v[26:29]
	v_mfma_f32_16x16x32_bf16 v[14:17], v[224:227], v[196:199], v[14:17]
	v_mfma_f32_16x16x32_bf16 v[10:13], v[232:235], v[196:199], v[10:13]
	v_mfma_f32_16x16x32_bf16 v[6:9], v[224:227], v[204:207], v[6:9]
	v_mfma_f32_16x16x32_bf16 v[2:5], v[232:235], v[204:207], v[2:5]
	s_setprio 0
	s_add_i32 s52, 0, 0x18000
	s_barrier
	s_add_u32 s22, s22, 0x20000
	s_addc_u32 s23, s23, 0
	s_mov_b32 m0, s29
	v_lshl_add_u64 v[208:209], s[22:23], 0, v[136:137]
	ds_read_b128 v[162:165], v144 offset:32768
	ds_read_b128 v[166:169], v144 offset:33792
	ds_read_b128 v[170:173], v144 offset:34816
	ds_read_b128 v[174:177], v144 offset:35840
	ds_read_b128 v[192:195], v144 offset:36864
	ds_read_b128 v[196:199], v144 offset:37888
	ds_read_b128 v[200:203], v144 offset:38912
	ds_read_b128 v[204:207], v144 offset:39936
	global_load_lds_dwordx4 v[208:209], off
	v_lshl_add_u64 v[208:209], s[22:23], 0, v[132:133]
	s_mov_b32 m0, s36
	s_nop 0
	global_load_lds_dwordx4 v[208:209], off
	s_waitcnt lgkmcnt(8)
	s_barrier
	s_waitcnt lgkmcnt(0)
	s_setprio 1
	s_waitcnt lgkmcnt(0)
	v_mfma_f32_16x16x32_bf16 v[126:129], v[146:149], v[162:165], v[126:129]
	v_mfma_f32_16x16x32_bf16 v[122:125], v[154:157], v[162:165], v[122:125]
	v_mfma_f32_16x16x32_bf16 v[118:121], v[146:149], v[170:173], v[118:121]
	v_mfma_f32_16x16x32_bf16 v[114:117], v[154:157], v[170:173], v[114:117]
	v_mfma_f32_16x16x32_bf16 v[102:105], v[146:149], v[192:195], v[102:105]
	v_mfma_f32_16x16x32_bf16 v[98:101], v[154:157], v[192:195], v[98:101]
	v_mfma_f32_16x16x32_bf16 v[86:89], v[146:149], v[200:203], v[86:89]
	v_mfma_f32_16x16x32_bf16 v[82:85], v[154:157], v[200:203], v[82:85]
	v_mfma_f32_16x16x32_bf16 v[126:129], v[150:153], v[166:169], v[126:129]
	v_mfma_f32_16x16x32_bf16 v[122:125], v[158:161], v[166:169], v[122:125]
	v_mfma_f32_16x16x32_bf16 v[118:121], v[150:153], v[174:177], v[118:121]
	v_mfma_f32_16x16x32_bf16 v[114:117], v[158:161], v[174:177], v[114:117]
	v_mfma_f32_16x16x32_bf16 v[102:105], v[150:153], v[196:199], v[102:105]
	v_mfma_f32_16x16x32_bf16 v[98:101], v[158:161], v[196:199], v[98:101]
	v_mfma_f32_16x16x32_bf16 v[86:89], v[150:153], v[204:207], v[86:89]
	v_mfma_f32_16x16x32_bf16 v[82:85], v[158:161], v[204:207], v[82:85]
	s_setprio 0
	s_barrier
	s_add_i32 s53, 0, 0x1c000
	s_add_i32 s22, s52, s26
	v_add_u32_e32 v145, s53, v142
	v_lshl_add_u64 v[178:179], v[178:179], 0, s[78:79]
	s_mov_b32 m0, s22
	ds_read_b128 v[208:211], v145
	ds_read_b128 v[224:227], v145 offset:1024
	ds_read_b128 v[228:231], v145 offset:2048
	ds_read_b128 v[232:235], v145 offset:3072
	global_load_lds_dwordx4 v[178:179], off
	v_lshl_add_u64 v[178:179], v[212:213], 0, s[78:79]
	s_add_i32 m0, s22, 0x2000
	s_nop 0
	global_load_lds_dwordx4 v[178:179], off
	s_barrier
	s_waitcnt lgkmcnt(0)
	s_setprio 1
	s_waitcnt lgkmcnt(0)
	v_mfma_f32_16x16x32_bf16 v[110:113], v[208:211], v[162:165], v[110:113]
	v_mfma_f32_16x16x32_bf16 v[106:109], v[228:231], v[162:165], v[106:109]
	v_mfma_f32_16x16x32_bf16 v[94:97], v[208:211], v[170:173], v[94:97]
	v_mfma_f32_16x16x32_bf16 v[90:93], v[228:231], v[170:173], v[90:93]
	v_mfma_f32_16x16x32_bf16 v[78:81], v[208:211], v[192:195], v[78:81]
	v_mfma_f32_16x16x32_bf16 v[74:77], v[228:231], v[192:195], v[74:77]
	v_mfma_f32_16x16x32_bf16 v[70:73], v[208:211], v[200:203], v[70:73]
	v_mfma_f32_16x16x32_bf16 v[66:69], v[228:231], v[200:203], v[66:69]
	v_mfma_f32_16x16x32_bf16 v[110:113], v[224:227], v[166:169], v[110:113]
	v_mfma_f32_16x16x32_bf16 v[106:109], v[232:235], v[166:169], v[106:109]
	v_mfma_f32_16x16x32_bf16 v[94:97], v[224:227], v[174:177], v[94:97]
	v_mfma_f32_16x16x32_bf16 v[90:93], v[232:235], v[174:177], v[90:93]
	v_mfma_f32_16x16x32_bf16 v[78:81], v[224:227], v[196:199], v[78:81]
	v_mfma_f32_16x16x32_bf16 v[74:77], v[232:235], v[196:199], v[74:77]
	v_mfma_f32_16x16x32_bf16 v[70:73], v[224:227], v[204:207], v[70:73]
	v_mfma_f32_16x16x32_bf16 v[66:69], v[232:235], v[204:207], v[66:69]
	s_setprio 0
	s_mov_b32 m0, s42
	v_lshl_add_u64 v[178:179], v[236:237], 0, s[78:79]
	s_barrier
	ds_read_b128 v[162:165], v144 offset:49152
	ds_read_b128 v[166:169], v144 offset:50176
	ds_read_b128 v[170:173], v144 offset:51200
	ds_read_b128 v[174:177], v144 offset:52224
	ds_read_b128 v[192:195], v144 offset:53248
	ds_read_b128 v[196:199], v144 offset:54272
	ds_read_b128 v[200:203], v144 offset:55296
	ds_read_b128 v[204:207], v144 offset:56320
	global_load_lds_dwordx4 v[178:179], off
	v_lshl_add_u64 v[178:179], v[238:239], 0, s[78:79]
	s_mov_b32 m0, s43
	s_nop 0
	global_load_lds_dwordx4 v[178:179], off
	s_waitcnt vmcnt(10)
	s_barrier
	s_waitcnt lgkmcnt(0)
	s_setprio 1
	s_waitcnt lgkmcnt(0)
	v_mfma_f32_16x16x32_bf16 v[62:65], v[146:149], v[162:165], v[62:65]
	v_mfma_f32_16x16x32_bf16 v[58:61], v[154:157], v[162:165], v[58:61]
	v_mfma_f32_16x16x32_bf16 v[54:57], v[146:149], v[170:173], v[54:57]
	v_mfma_f32_16x16x32_bf16 v[50:53], v[154:157], v[170:173], v[50:53]
	v_mfma_f32_16x16x32_bf16 v[38:41], v[146:149], v[192:195], v[38:41]
	v_mfma_f32_16x16x32_bf16 v[34:37], v[154:157], v[192:195], v[34:37]
	v_mfma_f32_16x16x32_bf16 v[22:25], v[146:149], v[200:203], v[22:25]
	v_mfma_f32_16x16x32_bf16 v[18:21], v[154:157], v[200:203], v[18:21]
	v_mfma_f32_16x16x32_bf16 v[62:65], v[150:153], v[166:169], v[62:65]
	v_mfma_f32_16x16x32_bf16 v[58:61], v[158:161], v[166:169], v[58:61]
	v_mfma_f32_16x16x32_bf16 v[54:57], v[150:153], v[174:177], v[54:57]
	v_mfma_f32_16x16x32_bf16 v[50:53], v[158:161], v[174:177], v[50:53]
	v_mfma_f32_16x16x32_bf16 v[38:41], v[150:153], v[196:199], v[38:41]
	v_mfma_f32_16x16x32_bf16 v[34:37], v[158:161], v[196:199], v[34:37]
	v_mfma_f32_16x16x32_bf16 v[22:25], v[150:153], v[204:207], v[22:25]
	v_mfma_f32_16x16x32_bf16 v[18:21], v[158:161], v[204:207], v[18:21]
	s_setprio 0
	s_barrier
	s_add_u32 s22, s84, 0x20080
	s_addc_u32 s23, s85, 0
	s_add_i32 s52, s53, s26
	v_lshl_add_u64 v[146:147], s[22:23], 0, v[134:135]
	s_mov_b32 m0, s52
	s_nop 0
	global_load_lds_dwordx4 v[146:147], off
	v_lshl_add_u64 v[146:147], s[22:23], 0, v[130:131]
	s_add_i32 m0, s52, 0x2000
	s_nop 0
	global_load_lds_dwordx4 v[146:147], off
	v_add_u32_e32 v145, 0x10000, v142
	ds_read_b128 v[146:149], v145
	ds_read_b128 v[150:153], v145 offset:1024
	ds_read_b128 v[154:157], v145 offset:2048
	ds_read_b128 v[158:161], v145 offset:3072
	s_waitcnt vmcnt(6)
	s_barrier
	s_setprio 1
	v_mfma_f32_16x16x32_bf16 v[46:49], v[208:211], v[162:165], v[46:49]
	v_mfma_f32_16x16x32_bf16 v[42:45], v[228:231], v[162:165], v[42:45]
	v_mfma_f32_16x16x32_bf16 v[30:33], v[208:211], v[170:173], v[30:33]
	v_mfma_f32_16x16x32_bf16 v[26:29], v[228:231], v[170:173], v[26:29]
	v_mfma_f32_16x16x32_bf16 v[14:17], v[208:211], v[192:195], v[14:17]
	v_mfma_f32_16x16x32_bf16 v[10:13], v[228:231], v[192:195], v[10:13]
	v_mfma_f32_16x16x32_bf16 v[6:9], v[208:211], v[200:203], v[6:9]
	v_mfma_f32_16x16x32_bf16 v[2:5], v[228:231], v[200:203], v[2:5]
	v_mfma_f32_16x16x32_bf16 v[46:49], v[224:227], v[166:169], v[46:49]
	v_mfma_f32_16x16x32_bf16 v[42:45], v[232:235], v[166:169], v[42:45]
	v_mfma_f32_16x16x32_bf16 v[30:33], v[224:227], v[174:177], v[30:33]
	v_mfma_f32_16x16x32_bf16 v[26:29], v[232:235], v[174:177], v[26:29]
	v_mfma_f32_16x16x32_bf16 v[14:17], v[224:227], v[196:199], v[14:17]
	v_mfma_f32_16x16x32_bf16 v[10:13], v[232:235], v[196:199], v[10:13]
	v_mfma_f32_16x16x32_bf16 v[6:9], v[224:227], v[204:207], v[6:9]
	v_mfma_f32_16x16x32_bf16 v[2:5], v[232:235], v[204:207], v[2:5]
	s_setprio 0
	s_add_i32 s51, s51, 2
	s_add_u32 s20, s20, 0x100
	s_addc_u32 s21, s21, 0
	s_add_u32 s49, s49, 0x100
	s_addc_u32 s50, s50, 0
	s_cmp_gt_u32 s51, 5
	s_barrier
	s_cbranch_scc0 .LBB0_357
	s_waitcnt lgkmcnt(0)
	v_lshl_add_u32 v146, s46, 8, v1
	v_lshl_or_b32 v148, s45, 8, v143
	v_ashrrev_i32_e32 v147, 31, v146
	v_readlane_b32 s48, v254, 40
	v_ashrrev_i32_e32 v149, 31, v148
	v_lshlrev_b64 v[150:151], 12, v[146:147]
	v_readlane_b32 s60, v254, 52
	v_readlane_b32 s61, v254, 53
	v_lshlrev_b64 v[148:149], 1, v[148:149]
	s_mov_b32 s19, 0x80000
	v_lshl_add_u64 v[150:151], s[60:61], 0, v[150:151]
	v_lshl_add_u64 v[150:151], v[150:151], 0, v[148:149]
	s_mov_b64 s[20:21], 0x80000
	v_cvt_pk_bf16_f32 v62, v62, v63
	v_cvt_pk_bf16_f32 v63, v64, v65
	v_cvt_pk_bf16_f32 v64, v58, v59
	v_add_co_u32_e32 v58, vcc, s19, v150
	v_cvt_pk_bf16_f32 v70, v70, v71
	v_cvt_pk_bf16_f32 v71, v72, v73
	v_cvt_pk_bf16_f32 v72, v66, v67
	v_lshl_add_u64 v[66:67], v[150:151], 0, s[20:21]
	v_addc_co_u32_e32 v59, vcc, 0, v151, vcc
	v_cvt_pk_bf16_f32 v46, v46, v47
	v_cvt_pk_bf16_f32 v47, v48, v49
	v_cvt_pk_bf16_f32 v48, v42, v43
	v_cvt_pk_bf16_f32 v49, v44, v45
	s_mov_b32 s19, 0x90000
	v_cvt_pk_bf16_f32 v110, v110, v111
	v_cvt_pk_bf16_f32 v111, v112, v113
	v_cvt_pk_bf16_f32 v112, v106, v107
	v_or_b32_e32 v106, 16, v146
	global_store_dwordx4 v[66:67], v[46:49], off offset:256
	s_mov_b64 s[20:21], 0x90000
	v_ashrrev_i32_e32 v107, 31, v106
	v_add_co_u32_e32 v48, vcc, s19, v150
	v_cvt_pk_bf16_f32 v94, v94, v95
	v_cvt_pk_bf16_f32 v95, v96, v97
	v_cvt_pk_bf16_f32 v96, v90, v91
	v_or_b32_e32 v90, 32, v146
	v_lshl_add_u64 v[46:47], v[150:151], 0, s[20:21]
	v_addc_co_u32_e32 v49, vcc, 0, v151, vcc
	v_cvt_pk_bf16_f32 v30, v30, v31
	v_cvt_pk_bf16_f32 v31, v32, v33
	v_cvt_pk_bf16_f32 v32, v26, v27
	v_cvt_pk_bf16_f32 v33, v28, v29
	s_mov_b32 s19, 0xa0000
	v_lshlrev_b64 v[106:107], 12, v[106:107]
	v_ashrrev_i32_e32 v91, 31, v90
	v_cvt_pk_bf16_f32 v78, v78, v79
	v_cvt_pk_bf16_f32 v79, v80, v81
	v_cvt_pk_bf16_f32 v80, v74, v75
	v_or_b32_e32 v74, 48, v146
	global_store_dwordx4 v[46:47], v[30:33], off offset:256
	s_mov_b64 s[20:21], 0xa0000
	v_cvt_pk_bf16_f32 v113, v108, v109
	v_add_co_u32_e32 v32, vcc, s19, v150
	v_lshl_add_u64 v[106:107], s[60:61], 0, v[106:107]
	v_lshlrev_b64 v[90:91], 12, v[90:91]
	v_ashrrev_i32_e32 v75, 31, v74
	v_lshl_add_u64 v[30:31], v[150:151], 0, s[20:21]
	v_addc_co_u32_e32 v33, vcc, 0, v151, vcc
	v_cvt_pk_bf16_f32 v14, v14, v15
	v_cvt_pk_bf16_f32 v15, v16, v17
	v_cvt_pk_bf16_f32 v16, v10, v11
	v_cvt_pk_bf16_f32 v17, v12, v13
	s_mov_b32 s19, 0xb0000
	global_store_dwordx4 v[150:151], v[110:113], off offset:256
	v_cvt_pk_bf16_f32 v97, v92, v93
	v_lshl_add_u64 v[90:91], s[60:61], 0, v[90:91]
	v_lshl_add_u64 v[110:111], v[106:107], 0, v[148:149]
	v_lshlrev_b64 v[74:75], 12, v[74:75]
	global_store_dwordx4 v[30:31], v[14:17], off offset:256
	global_store_dwordx4 v[110:111], v[94:97], off offset:256
	v_cvt_pk_bf16_f32 v81, v76, v77
	v_add_co_u32_e32 v16, vcc, s19, v150
	v_lshl_add_u64 v[94:95], v[90:91], 0, v[148:149]
	v_lshl_add_u64 v[74:75], s[60:61], 0, v[74:75]
	s_mov_b64 s[20:21], 0xb0000
	v_addc_co_u32_e32 v17, vcc, 0, v151, vcc
	v_cvt_pk_bf16_f32 v126, v126, v127
	v_cvt_pk_bf16_f32 v127, v128, v129
	v_cvt_pk_bf16_f32 v128, v122, v123
	v_cvt_pk_bf16_f32 v129, v124, v125
	v_cvt_pk_bf16_f32 v106, v118, v119
	v_cvt_pk_bf16_f32 v107, v120, v121
	v_cvt_pk_bf16_f32 v108, v114, v115
	v_cvt_pk_bf16_f32 v109, v116, v117
	v_cvt_pk_bf16_f32 v90, v102, v103
	v_cvt_pk_bf16_f32 v91, v104, v105
	v_cvt_pk_bf16_f32 v92, v98, v99
	v_cvt_pk_bf16_f32 v93, v100, v101
	global_store_dwordx4 v[94:95], v[78:81], off offset:256
	v_cvt_pk_bf16_f32 v76, v82, v83
	v_cvt_pk_bf16_f32 v77, v84, v85
	v_lshl_add_u64 v[78:79], v[74:75], 0, v[148:149]
	v_cvt_pk_bf16_f32 v74, v86, v87
	v_cvt_pk_bf16_f32 v75, v88, v89
	v_cvt_pk_bf16_f32 v73, v68, v69
	v_cvt_pk_bf16_f32 v65, v60, v61
	v_cvt_pk_bf16_f32 v42, v54, v55
	v_cvt_pk_bf16_f32 v43, v56, v57
	v_cvt_pk_bf16_f32 v44, v50, v51
	v_cvt_pk_bf16_f32 v45, v52, v53
	v_cvt_pk_bf16_f32 v26, v38, v39
	v_cvt_pk_bf16_f32 v27, v40, v41
	v_cvt_pk_bf16_f32 v28, v34, v35
	v_cvt_pk_bf16_f32 v29, v36, v37
	v_lshl_add_u64 v[14:15], v[150:151], 0, s[20:21]
	v_cvt_pk_bf16_f32 v10, v22, v23
	v_cvt_pk_bf16_f32 v11, v24, v25
	v_cvt_pk_bf16_f32 v12, v18, v19
	v_cvt_pk_bf16_f32 v13, v20, v21
	v_cvt_pk_bf16_f32 v6, v6, v7
	v_cvt_pk_bf16_f32 v7, v8, v9
	v_cvt_pk_bf16_f32 v8, v2, v3
	v_cvt_pk_bf16_f32 v9, v4, v5
	s_and_b64 vcc, exec, s[38:39]
	s_mov_b32 s45, s18
	s_mov_b32 s46, s30
	s_mov_b64 s[22:23], s[82:83]
	s_mov_b64 s[20:21], s[80:81]
	s_mov_b32 s64, 0x800000
	s_movk_i32 s65, 0x1fff
	v_readlane_b32 s49, v254, 41
	v_readlane_b32 s50, v254, 42
	v_readlane_b32 s51, v254, 43
	v_readlane_b32 s52, v254, 44
	v_readlane_b32 s53, v254, 45
	v_readlane_b32 s54, v254, 46
	v_readlane_b32 s55, v254, 47
	v_readlane_b32 s56, v254, 48
	v_readlane_b32 s57, v254, 49
	v_readlane_b32 s58, v254, 50
	v_readlane_b32 s59, v254, 51
	v_readlane_b32 s62, v254, 54
	v_readlane_b32 s63, v254, 55
	global_store_dwordx4 v[150:151], v[126:129], off
	global_store_dwordx4 v[110:111], v[106:109], off
	global_store_dwordx4 v[94:95], v[90:93], off
	global_store_dwordx4 v[78:79], v[74:77], off
	global_store_dwordx4 v[78:79], v[70:73], off offset:256
	global_store_dwordx4 v[58:59], v[62:65], off
	global_store_dwordx4 v[48:49], v[42:45], off
	global_store_dwordx4 v[32:33], v[26:29], off
	global_store_dwordx4 v[16:17], v[10:13], off
	global_store_dwordx4 v[14:15], v[6:9], off offset:256
	s_cbranch_vccz .LBB0_350
	s_waitcnt vmcnt(0)
	v_readlane_b32 s44, v255, 30
	s_mov_b32 s66, s90
	s_cmpk_gt_u32 s25, 0xff
	v_readlane_b32 s45, v255, 31
	v_readlane_b32 s42, v255, 32
	s_cbranch_scc1 .LBB0_361
	s_barrier

.LBB0_372:
	s_ashr_i32 s31, s30, 31
	v_readlane_b32 s48, v253, 50
	v_cmp_lt_i64_e32 vcc, s[38:39], v[184:185]
	s_lshl_b64 s[38:39], s[30:31], 18
	v_readlane_b32 s54, v253, 56
	v_readlane_b32 s55, v253, 57
	s_add_u32 s38, s54, s38
	v_readlane_b32 s49, v253, 51
	s_addc_u32 s39, s55, s39
	v_readlane_b32 s52, v253, 54
	v_readlane_b32 s53, v253, 55
	v_readlane_b32 s56, v253, 58
	v_readlane_b32 s57, v253, 59
	v_readlane_b32 s58, v253, 60
	v_readlane_b32 s59, v253, 61
	v_readlane_b32 s60, v253, 62
	v_readlane_b32 s61, v253, 63
	v_readlane_b32 s62, v254, 0
	v_readlane_b32 s63, v254, 1
	s_and_b64 s[48:49], vcc, exec
	s_cselect_b32 s31, s39, s21
	s_cselect_b32 s47, s38, s20
	s_ashr_i32 s19, s18, 31
	v_readlane_b32 s52, v254, 40
	s_lshl_b64 s[48:49], s[18:19], 18
	v_readlane_b32 s60, v254, 48
	v_readlane_b32 s61, v254, 49
	s_add_u32 s80, s60, s48
	s_addc_u32 s81, s61, s49
	s_and_b64 s[48:49], vcc, exec
	s_cselect_b32 s19, s81, s23
	s_cselect_b32 s48, s80, s22
	s_add_u32 s20, s20, 0x20080
	s_addc_u32 s21, s21, 0
	v_readlane_b32 s50, v253, 52
	v_readlane_b32 s51, v253, 53
	s_add_u32 s49, s22, 0x100
	v_mov_b32_e32 v2, 0
	s_addc_u32 s50, s23, 0
	s_mov_b32 s51, -2
	v_mov_b32_e32 v3, v2
	v_mov_b32_e32 v4, v2
	v_mov_b32_e32 v5, v2
	v_mov_b32_e32 v6, v2
	v_mov_b32_e32 v7, v2
	v_mov_b32_e32 v8, v2
	v_mov_b32_e32 v9, v2
	v_mov_b32_e32 v10, v2
	v_mov_b32_e32 v11, v2
	v_mov_b32_e32 v12, v2
	v_mov_b32_e32 v13, v2
	v_mov_b32_e32 v14, v2
	v_mov_b32_e32 v15, v2
	v_mov_b32_e32 v16, v2
	v_mov_b32_e32 v17, v2
	v_mov_b32_e32 v26, v2
	v_mov_b32_e32 v27, v2
	v_mov_b32_e32 v28, v2
	v_mov_b32_e32 v29, v2
	v_mov_b32_e32 v30, v2
	v_mov_b32_e32 v31, v2
	v_mov_b32_e32 v32, v2
	v_mov_b32_e32 v33, v2
	v_mov_b32_e32 v42, v2
	v_mov_b32_e32 v43, v2
	v_mov_b32_e32 v44, v2
	v_mov_b32_e32 v45, v2
	v_mov_b32_e32 v46, v2
	v_mov_b32_e32 v47, v2
	v_mov_b32_e32 v48, v2
	v_mov_b32_e32 v49, v2
	v_mov_b32_e32 v18, v2
	v_mov_b32_e32 v19, v2
	v_mov_b32_e32 v20, v2
	v_mov_b32_e32 v21, v2
	v_mov_b32_e32 v22, v2
	v_mov_b32_e32 v23, v2
	v_mov_b32_e32 v24, v2
	v_mov_b32_e32 v25, v2
	v_mov_b32_e32 v34, v2
	v_mov_b32_e32 v35, v2
	v_mov_b32_e32 v36, v2
	v_mov_b32_e32 v37, v2
	v_mov_b32_e32 v38, v2
	v_mov_b32_e32 v39, v2
	v_mov_b32_e32 v40, v2
	v_mov_b32_e32 v41, v2
	v_mov_b32_e32 v50, v2
	v_mov_b32_e32 v51, v2
	v_mov_b32_e32 v52, v2
	v_mov_b32_e32 v53, v2
	v_mov_b32_e32 v54, v2
	v_mov_b32_e32 v55, v2
	v_mov_b32_e32 v56, v2
	v_mov_b32_e32 v57, v2
	v_mov_b32_e32 v58, v2
	v_mov_b32_e32 v59, v2
	v_mov_b32_e32 v60, v2
	v_mov_b32_e32 v61, v2
	v_mov_b32_e32 v62, v2
	v_mov_b32_e32 v63, v2
	v_mov_b32_e32 v64, v2
	v_mov_b32_e32 v65, v2
	v_mov_b32_e32 v66, v2
	v_mov_b32_e32 v67, v2
	v_mov_b32_e32 v68, v2
	v_mov_b32_e32 v69, v2
	v_mov_b32_e32 v70, v2
	v_mov_b32_e32 v71, v2
	v_mov_b32_e32 v72, v2
	v_mov_b32_e32 v73, v2
	v_mov_b32_e32 v74, v2
	v_mov_b32_e32 v75, v2
	v_mov_b32_e32 v76, v2
	v_mov_b32_e32 v77, v2
	v_mov_b32_e32 v78, v2
	v_mov_b32_e32 v79, v2
	v_mov_b32_e32 v80, v2
	v_mov_b32_e32 v81, v2
	v_mov_b32_e32 v90, v2
	v_mov_b32_e32 v91, v2
	v_mov_b32_e32 v92, v2
	v_mov_b32_e32 v93, v2
	v_mov_b32_e32 v94, v2
	v_mov_b32_e32 v95, v2
	v_mov_b32_e32 v96, v2
	v_mov_b32_e32 v97, v2
	v_mov_b32_e32 v106, v2
	v_mov_b32_e32 v107, v2
	v_mov_b32_e32 v108, v2
	v_mov_b32_e32 v109, v2
	v_mov_b32_e32 v110, v2
	v_mov_b32_e32 v111, v2
	v_mov_b32_e32 v112, v2
	v_mov_b32_e32 v113, v2
	v_mov_b32_e32 v82, v2
	v_mov_b32_e32 v83, v2
	v_mov_b32_e32 v84, v2
	v_mov_b32_e32 v85, v2
	v_mov_b32_e32 v86, v2
	v_mov_b32_e32 v87, v2
	v_mov_b32_e32 v88, v2
	v_mov_b32_e32 v89, v2
	v_mov_b32_e32 v98, v2
	v_mov_b32_e32 v99, v2
	v_mov_b32_e32 v100, v2
	v_mov_b32_e32 v101, v2
	v_mov_b32_e32 v102, v2
	v_mov_b32_e32 v103, v2
	v_mov_b32_e32 v104, v2
	v_mov_b32_e32 v105, v2
	v_mov_b32_e32 v114, v2
	v_mov_b32_e32 v115, v2
	v_mov_b32_e32 v116, v2
	v_mov_b32_e32 v117, v2
	v_mov_b32_e32 v118, v2
	v_mov_b32_e32 v119, v2
	v_mov_b32_e32 v120, v2
	v_mov_b32_e32 v121, v2
	v_mov_b32_e32 v122, v2
	v_mov_b32_e32 v123, v2
	v_mov_b32_e32 v124, v2
	v_mov_b32_e32 v125, v2
	v_mov_b32_e32 v126, v2
	v_mov_b32_e32 v127, v2
	v_mov_b32_e32 v128, v2
	v_mov_b32_e32 v129, v2
	v_readlane_b32 s53, v254, 41
	v_readlane_b32 s54, v254, 42
	v_readlane_b32 s55, v254, 43
	v_readlane_b32 s56, v254, 44
	v_readlane_b32 s57, v254, 45
	v_readlane_b32 s58, v254, 46
	v_readlane_b32 s59, v254, 47
	v_readlane_b32 s62, v254, 50
	v_readlane_b32 s63, v254, 51
	v_readlane_b32 s64, v254, 52
	v_readlane_b32 s65, v254, 53
	v_readlane_b32 s66, v254, 54
	v_readlane_b32 s67, v254, 55
	v_add_u32_e32 v145, 0x10000, v142
	ds_read_b128 v[146:149], v145
	ds_read_b128 v[150:153], v145 offset:1024
	ds_read_b128 v[154:157], v145 offset:2048
	ds_read_b128 v[158:161], v145 offset:3072
.LBB0_373:
	s_add_u32 s22, s20, 0xfffe0080
	s_addc_u32 s23, s21, -1
	s_add_i32 s52, 0, 0x10000
	s_cmp_eq_u32 s51, 4
	s_cselect_b32 s23, s31, s23
	s_cselect_b32 s22, s47, s22
	s_cselect_b32 s83, s19, s50
	s_cselect_b32 s82, s48, s49
	v_lshl_add_u64 v[178:179], s[20:21], 0, v[138:139]
	s_add_i32 m0, s27, 0xc000
	ds_read_b128 v[162:165], v144
	ds_read_b128 v[166:169], v144 offset:1024
	ds_read_b128 v[170:173], v144 offset:2048
	ds_read_b128 v[174:177], v144 offset:3072
	ds_read_b128 v[192:195], v144 offset:4096
	ds_read_b128 v[196:199], v144 offset:5120
	ds_read_b128 v[200:203], v144 offset:6144
	ds_read_b128 v[204:207], v144 offset:7168
	global_load_lds_dwordx4 v[178:179], off
	v_lshl_add_u64 v[178:179], s[20:21], 0, v[140:141]
	s_add_i32 m0, s27, 0xe000
	s_nop 0
	global_load_lds_dwordx4 v[178:179], off
	s_waitcnt lgkmcnt(8)
	s_barrier
	s_waitcnt lgkmcnt(0)
	s_setprio 1
	s_waitcnt lgkmcnt(0)
	v_mfma_f32_16x16x32_bf16 v[126:129], v[146:149], v[162:165], v[126:129]
	v_mfma_f32_16x16x32_bf16 v[122:125], v[154:157], v[162:165], v[122:125]
	v_mfma_f32_16x16x32_bf16 v[118:121], v[146:149], v[170:173], v[118:121]
	v_mfma_f32_16x16x32_bf16 v[114:117], v[154:157], v[170:173], v[114:117]
	v_mfma_f32_16x16x32_bf16 v[102:105], v[146:149], v[192:195], v[102:105]
	v_mfma_f32_16x16x32_bf16 v[98:101], v[154:157], v[192:195], v[98:101]
	v_mfma_f32_16x16x32_bf16 v[86:89], v[146:149], v[200:203], v[86:89]
	v_mfma_f32_16x16x32_bf16 v[82:85], v[154:157], v[200:203], v[82:85]
	v_mfma_f32_16x16x32_bf16 v[126:129], v[150:153], v[166:169], v[126:129]
	v_mfma_f32_16x16x32_bf16 v[122:125], v[158:161], v[166:169], v[122:125]
	v_mfma_f32_16x16x32_bf16 v[118:121], v[150:153], v[174:177], v[118:121]
	v_mfma_f32_16x16x32_bf16 v[114:117], v[158:161], v[174:177], v[114:117]
	v_mfma_f32_16x16x32_bf16 v[102:105], v[150:153], v[196:199], v[102:105]
	v_mfma_f32_16x16x32_bf16 v[98:101], v[158:161], v[196:199], v[98:101]
	v_mfma_f32_16x16x32_bf16 v[86:89], v[150:153], v[204:207], v[86:89]
	v_mfma_f32_16x16x32_bf16 v[82:85], v[158:161], v[204:207], v[82:85]
	s_setprio 0
	s_barrier
	s_add_i32 s54, 0, 0x14000
	s_add_i32 s52, s52, s26
	v_add_u32_e32 v145, s54, v142
	v_lshl_add_u64 v[178:179], s[82:83], 0, v[134:135]
	s_mov_b32 m0, s52
	ds_read_b128 v[208:211], v145
	ds_read_b128 v[224:227], v145 offset:1024
	ds_read_b128 v[228:231], v145 offset:2048
	ds_read_b128 v[232:235], v145 offset:3072
	global_load_lds_dwordx4 v[178:179], off
	v_lshl_add_u64 v[212:213], s[82:83], 0, v[130:131]
	s_add_i32 m0, s52, 0x2000
	s_nop 0
	global_load_lds_dwordx4 v[212:213], off
	s_barrier
	s_waitcnt lgkmcnt(0)
	s_setprio 1
	s_waitcnt lgkmcnt(0)
	v_mfma_f32_16x16x32_bf16 v[110:113], v[208:211], v[162:165], v[110:113]
	v_mfma_f32_16x16x32_bf16 v[106:109], v[228:231], v[162:165], v[106:109]
	v_mfma_f32_16x16x32_bf16 v[94:97], v[208:211], v[170:173], v[94:97]
	v_mfma_f32_16x16x32_bf16 v[90:93], v[228:231], v[170:173], v[90:93]
	v_mfma_f32_16x16x32_bf16 v[78:81], v[208:211], v[192:195], v[78:81]
	v_mfma_f32_16x16x32_bf16 v[74:77], v[228:231], v[192:195], v[74:77]
	v_mfma_f32_16x16x32_bf16 v[70:73], v[208:211], v[200:203], v[70:73]
	v_mfma_f32_16x16x32_bf16 v[66:69], v[228:231], v[200:203], v[66:69]
	v_mfma_f32_16x16x32_bf16 v[110:113], v[224:227], v[166:169], v[110:113]
	v_mfma_f32_16x16x32_bf16 v[106:109], v[232:235], v[166:169], v[106:109]
	v_mfma_f32_16x16x32_bf16 v[94:97], v[224:227], v[174:177], v[94:97]
	v_mfma_f32_16x16x32_bf16 v[90:93], v[232:235], v[174:177], v[90:93]
	v_mfma_f32_16x16x32_bf16 v[78:81], v[224:227], v[196:199], v[78:81]
	v_mfma_f32_16x16x32_bf16 v[74:77], v[232:235], v[196:199], v[74:77]
	v_mfma_f32_16x16x32_bf16 v[70:73], v[224:227], v[204:207], v[70:73]
	v_mfma_f32_16x16x32_bf16 v[66:69], v[232:235], v[204:207], v[66:69]
	s_setprio 0
	s_mov_b32 m0, s27
	v_lshl_add_u64 v[236:237], s[22:23], 0, v[136:137]
	s_barrier
	ds_read_b128 v[162:165], v144 offset:16384
	ds_read_b128 v[166:169], v144 offset:17408
	ds_read_b128 v[170:173], v144 offset:18432
	ds_read_b128 v[174:177], v144 offset:19456
	ds_read_b128 v[192:195], v144 offset:20480
	ds_read_b128 v[196:199], v144 offset:21504
	ds_read_b128 v[200:203], v144 offset:22528
	ds_read_b128 v[204:207], v144 offset:23552
	global_load_lds_dwordx4 v[236:237], off
	v_lshl_add_u64 v[238:239], s[22:23], 0, v[132:133]
	s_mov_b32 m0, s28
	s_nop 0
	global_load_lds_dwordx4 v[238:239], off
	s_waitcnt vmcnt(10)
	s_barrier
	s_waitcnt lgkmcnt(0)
	s_setprio 1
	s_waitcnt lgkmcnt(0)
	v_mfma_f32_16x16x32_bf16 v[62:65], v[146:149], v[162:165], v[62:65]
	v_mfma_f32_16x16x32_bf16 v[58:61], v[154:157], v[162:165], v[58:61]
	v_mfma_f32_16x16x32_bf16 v[54:57], v[146:149], v[170:173], v[54:57]
	v_mfma_f32_16x16x32_bf16 v[50:53], v[154:157], v[170:173], v[50:53]
	v_mfma_f32_16x16x32_bf16 v[38:41], v[146:149], v[192:195], v[38:41]
	v_mfma_f32_16x16x32_bf16 v[34:37], v[154:157], v[192:195], v[34:37]
	v_mfma_f32_16x16x32_bf16 v[22:25], v[146:149], v[200:203], v[22:25]
	v_mfma_f32_16x16x32_bf16 v[18:21], v[154:157], v[200:203], v[18:21]
	v_mfma_f32_16x16x32_bf16 v[62:65], v[150:153], v[166:169], v[62:65]
	v_mfma_f32_16x16x32_bf16 v[58:61], v[158:161], v[166:169], v[58:61]
	v_mfma_f32_16x16x32_bf16 v[54:57], v[150:153], v[174:177], v[54:57]
	v_mfma_f32_16x16x32_bf16 v[50:53], v[158:161], v[174:177], v[50:53]
	v_mfma_f32_16x16x32_bf16 v[38:41], v[150:153], v[196:199], v[38:41]
	v_mfma_f32_16x16x32_bf16 v[34:37], v[158:161], v[196:199], v[34:37]
	v_mfma_f32_16x16x32_bf16 v[22:25], v[150:153], v[204:207], v[22:25]
	v_mfma_f32_16x16x32_bf16 v[18:21], v[158:161], v[204:207], v[18:21]
	s_setprio 0
	s_barrier
	s_add_u32 s52, s82, 0x20000
	s_addc_u32 s53, s83, 0
	s_add_i32 s54, s54, s26
	v_lshl_add_u64 v[146:147], s[52:53], 0, v[134:135]
	s_mov_b32 m0, s54
	s_nop 0
	global_load_lds_dwordx4 v[146:147], off
	v_lshl_add_u64 v[146:147], s[52:53], 0, v[130:131]
	s_add_i32 m0, s54, 0x2000
	s_nop 0
	global_load_lds_dwordx4 v[146:147], off
	v_add_u32_e32 v145, 0x18000, v142
	ds_read_b128 v[146:149], v145
	ds_read_b128 v[150:153], v145 offset:1024
	ds_read_b128 v[154:157], v145 offset:2048
	ds_read_b128 v[158:161], v145 offset:3072
	s_waitcnt vmcnt(6)
	s_barrier
	s_setprio 1
	v_mfma_f32_16x16x32_bf16 v[46:49], v[208:211], v[162:165], v[46:49]
	v_mfma_f32_16x16x32_bf16 v[42:45], v[228:231], v[162:165], v[42:45]
	v_mfma_f32_16x16x32_bf16 v[30:33], v[208:211], v[170:173], v[30:33]
	v_mfma_f32_16x16x32_bf16 v[26:29], v[228:231], v[170:173], v[26:29]
	v_mfma_f32_16x16x32_bf16 v[14:17], v[208:211], v[192:195], v[14:17]
	v_mfma_f32_16x16x32_bf16 v[10:13], v[228:231], v[192:195], v[10:13]
	v_mfma_f32_16x16x32_bf16 v[6:9], v[208:211], v[200:203], v[6:9]
	v_mfma_f32_16x16x32_bf16 v[2:5], v[228:231], v[200:203], v[2:5]
	v_mfma_f32_16x16x32_bf16 v[46:49], v[224:227], v[166:169], v[46:49]
	v_mfma_f32_16x16x32_bf16 v[42:45], v[232:235], v[166:169], v[42:45]
	v_mfma_f32_16x16x32_bf16 v[30:33], v[224:227], v[174:177], v[30:33]
	v_mfma_f32_16x16x32_bf16 v[26:29], v[232:235], v[174:177], v[26:29]
	v_mfma_f32_16x16x32_bf16 v[14:17], v[224:227], v[196:199], v[14:17]
	v_mfma_f32_16x16x32_bf16 v[10:13], v[232:235], v[196:199], v[10:13]
	v_mfma_f32_16x16x32_bf16 v[6:9], v[224:227], v[204:207], v[6:9]
	v_mfma_f32_16x16x32_bf16 v[2:5], v[232:235], v[204:207], v[2:5]
	s_setprio 0
	s_add_i32 s52, 0, 0x18000
	s_barrier
	s_add_u32 s22, s22, 0x20000
	s_addc_u32 s23, s23, 0
	s_mov_b32 m0, s29
	v_lshl_add_u64 v[208:209], s[22:23], 0, v[136:137]
	ds_read_b128 v[162:165], v144 offset:32768
	ds_read_b128 v[166:169], v144 offset:33792
	ds_read_b128 v[170:173], v144 offset:34816
	ds_read_b128 v[174:177], v144 offset:35840
	ds_read_b128 v[192:195], v144 offset:36864
	ds_read_b128 v[196:199], v144 offset:37888
	ds_read_b128 v[200:203], v144 offset:38912
	ds_read_b128 v[204:207], v144 offset:39936
	global_load_lds_dwordx4 v[208:209], off
	v_lshl_add_u64 v[208:209], s[22:23], 0, v[132:133]
	s_mov_b32 m0, s36
	s_nop 0
	global_load_lds_dwordx4 v[208:209], off
	s_waitcnt lgkmcnt(8)
	s_barrier
	s_waitcnt lgkmcnt(0)
	s_setprio 1
	s_waitcnt lgkmcnt(0)
	v_mfma_f32_16x16x32_bf16 v[126:129], v[146:149], v[162:165], v[126:129]
	v_mfma_f32_16x16x32_bf16 v[122:125], v[154:157], v[162:165], v[122:125]
	v_mfma_f32_16x16x32_bf16 v[118:121], v[146:149], v[170:173], v[118:121]
	v_mfma_f32_16x16x32_bf16 v[114:117], v[154:157], v[170:173], v[114:117]
	v_mfma_f32_16x16x32_bf16 v[102:105], v[146:149], v[192:195], v[102:105]
	v_mfma_f32_16x16x32_bf16 v[98:101], v[154:157], v[192:195], v[98:101]
	v_mfma_f32_16x16x32_bf16 v[86:89], v[146:149], v[200:203], v[86:89]
	v_mfma_f32_16x16x32_bf16 v[82:85], v[154:157], v[200:203], v[82:85]
	v_mfma_f32_16x16x32_bf16 v[126:129], v[150:153], v[166:169], v[126:129]
	v_mfma_f32_16x16x32_bf16 v[122:125], v[158:161], v[166:169], v[122:125]
	v_mfma_f32_16x16x32_bf16 v[118:121], v[150:153], v[174:177], v[118:121]
	v_mfma_f32_16x16x32_bf16 v[114:117], v[158:161], v[174:177], v[114:117]
	v_mfma_f32_16x16x32_bf16 v[102:105], v[150:153], v[196:199], v[102:105]
	v_mfma_f32_16x16x32_bf16 v[98:101], v[158:161], v[196:199], v[98:101]
	v_mfma_f32_16x16x32_bf16 v[86:89], v[150:153], v[204:207], v[86:89]
	v_mfma_f32_16x16x32_bf16 v[82:85], v[158:161], v[204:207], v[82:85]
	s_setprio 0
	s_barrier
	s_add_i32 s53, 0, 0x1c000
	s_add_i32 s22, s52, s26
	v_add_u32_e32 v145, s53, v142
	v_lshl_add_u64 v[178:179], v[178:179], 0, s[78:79]
	s_mov_b32 m0, s22
	ds_read_b128 v[208:211], v145
	ds_read_b128 v[224:227], v145 offset:1024
	ds_read_b128 v[228:231], v145 offset:2048
	ds_read_b128 v[232:235], v145 offset:3072
	global_load_lds_dwordx4 v[178:179], off
	v_lshl_add_u64 v[178:179], v[212:213], 0, s[78:79]
	s_add_i32 m0, s22, 0x2000
	s_nop 0
	global_load_lds_dwordx4 v[178:179], off
	s_barrier
	s_waitcnt lgkmcnt(0)
	s_setprio 1
	s_waitcnt lgkmcnt(0)
	v_mfma_f32_16x16x32_bf16 v[110:113], v[208:211], v[162:165], v[110:113]
	v_mfma_f32_16x16x32_bf16 v[106:109], v[228:231], v[162:165], v[106:109]
	v_mfma_f32_16x16x32_bf16 v[94:97], v[208:211], v[170:173], v[94:97]
	v_mfma_f32_16x16x32_bf16 v[90:93], v[228:231], v[170:173], v[90:93]
	v_mfma_f32_16x16x32_bf16 v[78:81], v[208:211], v[192:195], v[78:81]
	v_mfma_f32_16x16x32_bf16 v[74:77], v[228:231], v[192:195], v[74:77]
	v_mfma_f32_16x16x32_bf16 v[70:73], v[208:211], v[200:203], v[70:73]
	v_mfma_f32_16x16x32_bf16 v[66:69], v[228:231], v[200:203], v[66:69]
	v_mfma_f32_16x16x32_bf16 v[110:113], v[224:227], v[166:169], v[110:113]
	v_mfma_f32_16x16x32_bf16 v[106:109], v[232:235], v[166:169], v[106:109]
	v_mfma_f32_16x16x32_bf16 v[94:97], v[224:227], v[174:177], v[94:97]
	v_mfma_f32_16x16x32_bf16 v[90:93], v[232:235], v[174:177], v[90:93]
	v_mfma_f32_16x16x32_bf16 v[78:81], v[224:227], v[196:199], v[78:81]
	v_mfma_f32_16x16x32_bf16 v[74:77], v[232:235], v[196:199], v[74:77]
	v_mfma_f32_16x16x32_bf16 v[70:73], v[224:227], v[204:207], v[70:73]
	v_mfma_f32_16x16x32_bf16 v[66:69], v[232:235], v[204:207], v[66:69]
	s_setprio 0
	s_mov_b32 m0, s42
	v_lshl_add_u64 v[178:179], v[236:237], 0, s[78:79]
	s_barrier
	ds_read_b128 v[162:165], v144 offset:49152
	ds_read_b128 v[166:169], v144 offset:50176
	ds_read_b128 v[170:173], v144 offset:51200
	ds_read_b128 v[174:177], v144 offset:52224
	ds_read_b128 v[192:195], v144 offset:53248
	ds_read_b128 v[196:199], v144 offset:54272
	ds_read_b128 v[200:203], v144 offset:55296
	ds_read_b128 v[204:207], v144 offset:56320
	global_load_lds_dwordx4 v[178:179], off
	v_lshl_add_u64 v[178:179], v[238:239], 0, s[78:79]
	s_mov_b32 m0, s43
	s_nop 0
	global_load_lds_dwordx4 v[178:179], off
	s_waitcnt vmcnt(10)
	s_barrier
	s_waitcnt lgkmcnt(0)
	s_setprio 1
	s_waitcnt lgkmcnt(0)
	v_mfma_f32_16x16x32_bf16 v[62:65], v[146:149], v[162:165], v[62:65]
	v_mfma_f32_16x16x32_bf16 v[58:61], v[154:157], v[162:165], v[58:61]
	v_mfma_f32_16x16x32_bf16 v[54:57], v[146:149], v[170:173], v[54:57]
	v_mfma_f32_16x16x32_bf16 v[50:53], v[154:157], v[170:173], v[50:53]
	v_mfma_f32_16x16x32_bf16 v[38:41], v[146:149], v[192:195], v[38:41]
	v_mfma_f32_16x16x32_bf16 v[34:37], v[154:157], v[192:195], v[34:37]
	v_mfma_f32_16x16x32_bf16 v[22:25], v[146:149], v[200:203], v[22:25]
	v_mfma_f32_16x16x32_bf16 v[18:21], v[154:157], v[200:203], v[18:21]
	v_mfma_f32_16x16x32_bf16 v[62:65], v[150:153], v[166:169], v[62:65]
	v_mfma_f32_16x16x32_bf16 v[58:61], v[158:161], v[166:169], v[58:61]
	v_mfma_f32_16x16x32_bf16 v[54:57], v[150:153], v[174:177], v[54:57]
	v_mfma_f32_16x16x32_bf16 v[50:53], v[158:161], v[174:177], v[50:53]
	v_mfma_f32_16x16x32_bf16 v[38:41], v[150:153], v[196:199], v[38:41]
	v_mfma_f32_16x16x32_bf16 v[34:37], v[158:161], v[196:199], v[34:37]
	v_mfma_f32_16x16x32_bf16 v[22:25], v[150:153], v[204:207], v[22:25]
	v_mfma_f32_16x16x32_bf16 v[18:21], v[158:161], v[204:207], v[18:21]
	s_setprio 0
	s_barrier
	s_add_u32 s22, s82, 0x20080
	s_addc_u32 s23, s83, 0
	s_add_i32 s52, s53, s26
	v_lshl_add_u64 v[146:147], s[22:23], 0, v[134:135]
	s_mov_b32 m0, s52
	s_nop 0
	global_load_lds_dwordx4 v[146:147], off
	v_lshl_add_u64 v[146:147], s[22:23], 0, v[130:131]
	s_add_i32 m0, s52, 0x2000
	s_nop 0
	global_load_lds_dwordx4 v[146:147], off
	v_add_u32_e32 v145, 0x10000, v142
	ds_read_b128 v[146:149], v145
	ds_read_b128 v[150:153], v145 offset:1024
	ds_read_b128 v[154:157], v145 offset:2048
	ds_read_b128 v[158:161], v145 offset:3072
	s_waitcnt vmcnt(6)
	s_barrier
	s_setprio 1
	v_mfma_f32_16x16x32_bf16 v[46:49], v[208:211], v[162:165], v[46:49]
	v_mfma_f32_16x16x32_bf16 v[42:45], v[228:231], v[162:165], v[42:45]
	v_mfma_f32_16x16x32_bf16 v[30:33], v[208:211], v[170:173], v[30:33]
	v_mfma_f32_16x16x32_bf16 v[26:29], v[228:231], v[170:173], v[26:29]
	v_mfma_f32_16x16x32_bf16 v[14:17], v[208:211], v[192:195], v[14:17]
	v_mfma_f32_16x16x32_bf16 v[10:13], v[228:231], v[192:195], v[10:13]
	v_mfma_f32_16x16x32_bf16 v[6:9], v[208:211], v[200:203], v[6:9]
	v_mfma_f32_16x16x32_bf16 v[2:5], v[228:231], v[200:203], v[2:5]
	v_mfma_f32_16x16x32_bf16 v[46:49], v[224:227], v[166:169], v[46:49]
	v_mfma_f32_16x16x32_bf16 v[42:45], v[232:235], v[166:169], v[42:45]
	v_mfma_f32_16x16x32_bf16 v[30:33], v[224:227], v[174:177], v[30:33]
	v_mfma_f32_16x16x32_bf16 v[26:29], v[232:235], v[174:177], v[26:29]
	v_mfma_f32_16x16x32_bf16 v[14:17], v[224:227], v[196:199], v[14:17]
	v_mfma_f32_16x16x32_bf16 v[10:13], v[232:235], v[196:199], v[10:13]
	v_mfma_f32_16x16x32_bf16 v[6:9], v[224:227], v[204:207], v[6:9]
	v_mfma_f32_16x16x32_bf16 v[2:5], v[232:235], v[204:207], v[2:5]
	s_setprio 0
	s_add_i32 s51, s51, 2
	s_add_u32 s20, s20, 0x100
	s_addc_u32 s21, s21, 0
	s_add_u32 s49, s49, 0x100
	s_addc_u32 s50, s50, 0
	s_cmp_gt_u32 s51, 5
	s_barrier
	s_cbranch_scc0 .LBB0_373
	s_waitcnt lgkmcnt(0)
	v_lshl_add_u32 v146, s46, 8, v1
	v_lshl_or_b32 v148, s45, 8, v143
	v_ashrrev_i32_e32 v147, 31, v146
	v_readlane_b32 s48, v254, 40
	v_ashrrev_i32_e32 v149, 31, v148
	v_lshlrev_b64 v[150:151], 14, v[146:147]
	v_readlane_b32 s62, v254, 54
	v_readlane_b32 s63, v254, 55
	v_lshlrev_b64 v[148:149], 1, v[148:149]
	s_mov_b32 s19, 0x200000
	v_lshl_add_u64 v[150:151], s[62:63], 0, v[150:151]
	v_lshl_add_u64 v[150:151], v[150:151], 0, v[148:149]
	s_mov_b64 s[20:21], 0x200000
	v_cvt_pk_bf16_f32 v62, v62, v63
	v_cvt_pk_bf16_f32 v63, v64, v65
	v_cvt_pk_bf16_f32 v64, v58, v59
	v_add_co_u32_e32 v58, vcc, s19, v150
	v_cvt_pk_bf16_f32 v70, v70, v71
	v_cvt_pk_bf16_f32 v71, v72, v73
	v_cvt_pk_bf16_f32 v72, v66, v67
	v_lshl_add_u64 v[66:67], v[150:151], 0, s[20:21]
	v_addc_co_u32_e32 v59, vcc, 0, v151, vcc
	v_cvt_pk_bf16_f32 v46, v46, v47
	v_cvt_pk_bf16_f32 v47, v48, v49
	v_cvt_pk_bf16_f32 v48, v42, v43
	v_cvt_pk_bf16_f32 v49, v44, v45
	s_mov_b32 s19, 0x240000
	v_cvt_pk_bf16_f32 v110, v110, v111
	v_cvt_pk_bf16_f32 v111, v112, v113
	v_cvt_pk_bf16_f32 v112, v106, v107
	v_or_b32_e32 v106, 16, v146
	global_store_dwordx4 v[66:67], v[46:49], off offset:256
	s_mov_b64 s[20:21], 0x240000
	v_ashrrev_i32_e32 v107, 31, v106
	v_add_co_u32_e32 v48, vcc, s19, v150
	v_cvt_pk_bf16_f32 v94, v94, v95
	v_cvt_pk_bf16_f32 v95, v96, v97
	v_cvt_pk_bf16_f32 v96, v90, v91
	v_or_b32_e32 v90, 32, v146
	v_lshl_add_u64 v[46:47], v[150:151], 0, s[20:21]
	v_addc_co_u32_e32 v49, vcc, 0, v151, vcc
	v_cvt_pk_bf16_f32 v30, v30, v31
	v_cvt_pk_bf16_f32 v31, v32, v33
	v_cvt_pk_bf16_f32 v32, v26, v27
	v_cvt_pk_bf16_f32 v33, v28, v29
	s_mov_b32 s19, 0x280000
	v_lshlrev_b64 v[106:107], 14, v[106:107]
	v_ashrrev_i32_e32 v91, 31, v90
	v_cvt_pk_bf16_f32 v78, v78, v79
	v_cvt_pk_bf16_f32 v79, v80, v81
	v_cvt_pk_bf16_f32 v80, v74, v75
	v_or_b32_e32 v74, 48, v146
	global_store_dwordx4 v[46:47], v[30:33], off offset:256
	s_mov_b64 s[20:21], 0x280000
	v_cvt_pk_bf16_f32 v113, v108, v109
	v_add_co_u32_e32 v32, vcc, s19, v150
	v_lshl_add_u64 v[106:107], s[62:63], 0, v[106:107]
	v_lshlrev_b64 v[90:91], 14, v[90:91]
	v_ashrrev_i32_e32 v75, 31, v74
	v_lshl_add_u64 v[30:31], v[150:151], 0, s[20:21]
	v_addc_co_u32_e32 v33, vcc, 0, v151, vcc
	v_cvt_pk_bf16_f32 v14, v14, v15
	v_cvt_pk_bf16_f32 v15, v16, v17
	v_cvt_pk_bf16_f32 v16, v10, v11
	v_cvt_pk_bf16_f32 v17, v12, v13
	s_mov_b32 s19, 0x2c0000
	global_store_dwordx4 v[150:151], v[110:113], off offset:256
	v_cvt_pk_bf16_f32 v97, v92, v93
	v_lshl_add_u64 v[90:91], s[62:63], 0, v[90:91]
	v_lshl_add_u64 v[110:111], v[106:107], 0, v[148:149]
	v_lshlrev_b64 v[74:75], 14, v[74:75]
	global_store_dwordx4 v[30:31], v[14:17], off offset:256
	global_store_dwordx4 v[110:111], v[94:97], off offset:256
	v_cvt_pk_bf16_f32 v81, v76, v77
	v_add_co_u32_e32 v16, vcc, s19, v150
	v_lshl_add_u64 v[94:95], v[90:91], 0, v[148:149]
	v_lshl_add_u64 v[74:75], s[62:63], 0, v[74:75]
	s_mov_b64 s[20:21], 0x2c0000
	v_addc_co_u32_e32 v17, vcc, 0, v151, vcc
	v_cvt_pk_bf16_f32 v126, v126, v127
	v_cvt_pk_bf16_f32 v127, v128, v129
	v_cvt_pk_bf16_f32 v128, v122, v123
	v_cvt_pk_bf16_f32 v129, v124, v125
	v_cvt_pk_bf16_f32 v106, v118, v119
	v_cvt_pk_bf16_f32 v107, v120, v121
	v_cvt_pk_bf16_f32 v108, v114, v115
	v_cvt_pk_bf16_f32 v109, v116, v117
	v_cvt_pk_bf16_f32 v90, v102, v103
	v_cvt_pk_bf16_f32 v91, v104, v105
	v_cvt_pk_bf16_f32 v92, v98, v99
	v_cvt_pk_bf16_f32 v93, v100, v101
	global_store_dwordx4 v[94:95], v[78:81], off offset:256
	v_cvt_pk_bf16_f32 v76, v82, v83
	v_cvt_pk_bf16_f32 v77, v84, v85
	v_lshl_add_u64 v[78:79], v[74:75], 0, v[148:149]
	v_cvt_pk_bf16_f32 v74, v86, v87
	v_cvt_pk_bf16_f32 v75, v88, v89
	v_cvt_pk_bf16_f32 v73, v68, v69
	v_cvt_pk_bf16_f32 v65, v60, v61
	v_cvt_pk_bf16_f32 v42, v54, v55
	v_cvt_pk_bf16_f32 v43, v56, v57
	v_cvt_pk_bf16_f32 v44, v50, v51
	v_cvt_pk_bf16_f32 v45, v52, v53
	v_cvt_pk_bf16_f32 v26, v38, v39
	v_cvt_pk_bf16_f32 v27, v40, v41
	v_cvt_pk_bf16_f32 v28, v34, v35
	v_cvt_pk_bf16_f32 v29, v36, v37
	v_lshl_add_u64 v[14:15], v[150:151], 0, s[20:21]
	v_cvt_pk_bf16_f32 v10, v22, v23
	v_cvt_pk_bf16_f32 v11, v24, v25
	v_cvt_pk_bf16_f32 v12, v18, v19
	v_cvt_pk_bf16_f32 v13, v20, v21
	v_cvt_pk_bf16_f32 v6, v6, v7
	v_cvt_pk_bf16_f32 v7, v8, v9
	v_cvt_pk_bf16_f32 v8, v2, v3
	v_cvt_pk_bf16_f32 v9, v4, v5
	s_and_b64 vcc, exec, s[0:1]
	s_mov_b32 s45, s18
	s_mov_b32 s46, s30
	s_mov_b64 s[22:23], s[80:81]
	s_mov_b64 s[20:21], s[38:39]
	s_mov_b32 s64, 0x800000
	s_movk_i32 s65, 0x1fff
	v_readlane_b32 s49, v254, 41
	v_readlane_b32 s50, v254, 42
	v_readlane_b32 s51, v254, 43
	v_readlane_b32 s52, v254, 44
	v_readlane_b32 s53, v254, 45
	v_readlane_b32 s54, v254, 46
	v_readlane_b32 s55, v254, 47
	v_readlane_b32 s56, v254, 48
	v_readlane_b32 s57, v254, 49
	v_readlane_b32 s58, v254, 50
	v_readlane_b32 s59, v254, 51
	v_readlane_b32 s60, v254, 52
	v_readlane_b32 s61, v254, 53
	global_store_dwordx4 v[150:151], v[126:129], off
	global_store_dwordx4 v[110:111], v[106:109], off
	global_store_dwordx4 v[94:95], v[90:93], off
	global_store_dwordx4 v[78:79], v[74:77], off
	global_store_dwordx4 v[78:79], v[70:73], off offset:256
	global_store_dwordx4 v[58:59], v[62:65], off
	global_store_dwordx4 v[48:49], v[42:45], off
	global_store_dwordx4 v[32:33], v[26:29], off
	global_store_dwordx4 v[16:17], v[10:13], off
	global_store_dwordx4 v[14:15], v[6:9], off offset:256
	s_cbranch_vccz .LBB0_366
	s_waitcnt vmcnt(0)
	v_readlane_b32 s44, v255, 30
	s_mov_b32 s66, s90
	s_cmpk_gt_u32 s25, 0xff
	v_readlane_b32 s45, v255, 31
	v_readlane_b32 s42, v255, 32
	s_cbranch_scc1 .LBB0_377
	s_barrier

.LBB0_385:
	v_mov_b64_e32 v[2:3], 0x180
	s_ashr_i32 s81, s80, 31
	v_readlane_b32 s44, v254, 40
	v_cmp_lt_i64_e32 vcc, s[22:23], v[2:3]
	s_lshl_b64 s[22:23], s[80:81], 18
	v_readlane_b32 s50, v254, 46
	v_readlane_b32 s51, v254, 47
	s_add_u32 s82, s50, s22
	s_addc_u32 s83, s51, s23
	v_readlane_b32 s45, v254, 41
	s_and_b64 s[22:23], vcc, exec
	s_cselect_b32 s44, s83, s19
	s_cselect_b32 s45, s82, s18
	s_ashr_i32 s39, s38, 31
	s_lshl_b64 s[22:23], s[38:39], 18
	s_add_u32 s84, s30, s22
	s_addc_u32 s85, s31, s23
	v_readlane_b32 s46, v254, 42
	s_and_b64 s[22:23], vcc, exec
	s_cselect_b32 s39, s85, s21
	s_cselect_b32 s46, s84, s20
	s_add_u32 s18, s18, 0x20080
	v_readlane_b32 s47, v254, 43
	s_addc_u32 s19, s19, 0
	v_readlane_b32 s48, v254, 44
	v_readlane_b32 s49, v254, 45
	s_add_u32 s47, s20, 0x100
	v_mov_b32_e32 v2, 0
	s_addc_u32 s48, s21, 0
	s_mov_b32 s49, -2
	v_mov_b32_e32 v3, v2
	v_mov_b32_e32 v4, v2
	v_mov_b32_e32 v5, v2
	v_mov_b32_e32 v6, v2
	v_mov_b32_e32 v7, v2
	v_mov_b32_e32 v8, v2
	v_mov_b32_e32 v9, v2
	v_mov_b32_e32 v10, v2
	v_mov_b32_e32 v11, v2
	v_mov_b32_e32 v12, v2
	v_mov_b32_e32 v13, v2
	v_mov_b32_e32 v18, v2
	v_mov_b32_e32 v19, v2
	v_mov_b32_e32 v20, v2
	v_mov_b32_e32 v21, v2
	v_mov_b32_e32 v26, v2
	v_mov_b32_e32 v27, v2
	v_mov_b32_e32 v28, v2
	v_mov_b32_e32 v29, v2
	v_mov_b32_e32 v34, v2
	v_mov_b32_e32 v35, v2
	v_mov_b32_e32 v36, v2
	v_mov_b32_e32 v37, v2
	v_mov_b32_e32 v42, v2
	v_mov_b32_e32 v43, v2
	v_mov_b32_e32 v44, v2
	v_mov_b32_e32 v45, v2
	v_mov_b32_e32 v50, v2
	v_mov_b32_e32 v51, v2
	v_mov_b32_e32 v52, v2
	v_mov_b32_e32 v53, v2
	v_mov_b32_e32 v14, v2
	v_mov_b32_e32 v15, v2
	v_mov_b32_e32 v16, v2
	v_mov_b32_e32 v17, v2
	v_mov_b32_e32 v22, v2
	v_mov_b32_e32 v23, v2
	v_mov_b32_e32 v24, v2
	v_mov_b32_e32 v25, v2
	v_mov_b32_e32 v30, v2
	v_mov_b32_e32 v31, v2
	v_mov_b32_e32 v32, v2
	v_mov_b32_e32 v33, v2
	v_mov_b32_e32 v38, v2
	v_mov_b32_e32 v39, v2
	v_mov_b32_e32 v40, v2
	v_mov_b32_e32 v41, v2
	v_mov_b32_e32 v46, v2
	v_mov_b32_e32 v47, v2
	v_mov_b32_e32 v48, v2
	v_mov_b32_e32 v49, v2
	v_mov_b32_e32 v54, v2
	v_mov_b32_e32 v55, v2
	v_mov_b32_e32 v56, v2
	v_mov_b32_e32 v57, v2
	v_mov_b32_e32 v58, v2
	v_mov_b32_e32 v59, v2
	v_mov_b32_e32 v60, v2
	v_mov_b32_e32 v61, v2
	v_mov_b32_e32 v62, v2
	v_mov_b32_e32 v63, v2
	v_mov_b32_e32 v64, v2
	v_mov_b32_e32 v65, v2
	v_mov_b32_e32 v66, v2
	v_mov_b32_e32 v67, v2
	v_mov_b32_e32 v68, v2
	v_mov_b32_e32 v69, v2
	v_mov_b32_e32 v70, v2
	v_mov_b32_e32 v71, v2
	v_mov_b32_e32 v72, v2
	v_mov_b32_e32 v73, v2
	v_mov_b32_e32 v74, v2
	v_mov_b32_e32 v75, v2
	v_mov_b32_e32 v76, v2
	v_mov_b32_e32 v77, v2
	v_mov_b32_e32 v82, v2
	v_mov_b32_e32 v83, v2
	v_mov_b32_e32 v84, v2
	v_mov_b32_e32 v85, v2
	v_mov_b32_e32 v90, v2
	v_mov_b32_e32 v91, v2
	v_mov_b32_e32 v92, v2
	v_mov_b32_e32 v93, v2
	v_mov_b32_e32 v98, v2
	v_mov_b32_e32 v99, v2
	v_mov_b32_e32 v100, v2
	v_mov_b32_e32 v101, v2
	v_mov_b32_e32 v106, v2
	v_mov_b32_e32 v107, v2
	v_mov_b32_e32 v108, v2
	v_mov_b32_e32 v109, v2
	v_mov_b32_e32 v114, v2
	v_mov_b32_e32 v115, v2
	v_mov_b32_e32 v116, v2
	v_mov_b32_e32 v117, v2
	v_mov_b32_e32 v78, v2
	v_mov_b32_e32 v79, v2
	v_mov_b32_e32 v80, v2
	v_mov_b32_e32 v81, v2
	v_mov_b32_e32 v86, v2
	v_mov_b32_e32 v87, v2
	v_mov_b32_e32 v88, v2
	v_mov_b32_e32 v89, v2
	v_mov_b32_e32 v94, v2
	v_mov_b32_e32 v95, v2
	v_mov_b32_e32 v96, v2
	v_mov_b32_e32 v97, v2
	v_mov_b32_e32 v102, v2
	v_mov_b32_e32 v103, v2
	v_mov_b32_e32 v104, v2
	v_mov_b32_e32 v105, v2
	v_mov_b32_e32 v110, v2
	v_mov_b32_e32 v111, v2
	v_mov_b32_e32 v112, v2
	v_mov_b32_e32 v113, v2
	v_mov_b32_e32 v118, v2
	v_mov_b32_e32 v119, v2
	v_mov_b32_e32 v120, v2
	v_mov_b32_e32 v121, v2
	v_mov_b32_e32 v122, v2
	v_mov_b32_e32 v123, v2
	v_mov_b32_e32 v124, v2
	v_mov_b32_e32 v125, v2
	v_mov_b32_e32 v126, v2
	v_mov_b32_e32 v127, v2
	v_mov_b32_e32 v128, v2
	v_mov_b32_e32 v129, v2
	v_readlane_b32 s52, v254, 48
	v_readlane_b32 s53, v254, 49
	v_readlane_b32 s54, v254, 50
	v_readlane_b32 s55, v254, 51
	v_readlane_b32 s56, v254, 52
	v_readlane_b32 s57, v254, 53
	v_readlane_b32 s58, v254, 54
	v_readlane_b32 s59, v254, 55
	v_add_u32_e32 v157, 0x10000, v154
	ds_read_b128 v[130:133], v157
	ds_read_b128 v[134:137], v157 offset:1024
	ds_read_b128 v[150:153], v157 offset:2048
	ds_read_b128 v[158:161], v157 offset:3072
.LBB0_386:
	s_add_u32 s20, s18, 0xfffe0080
	s_addc_u32 s21, s19, -1
	s_add_i32 s50, 0, 0x10000
	s_cmp_eq_u32 s49, 4
	s_cselect_b32 s23, s44, s21
	s_cselect_b32 s22, s45, s20
	s_cselect_b32 s21, s39, s48
	s_cselect_b32 s20, s46, s47
	v_lshl_add_u64 v[178:179], s[18:19], 0, v[146:147]
	s_add_i32 m0, s90, 0xc000
	ds_read_b128 v[162:165], v156
	ds_read_b128 v[166:169], v156 offset:1024
	ds_read_b128 v[170:173], v156 offset:2048
	ds_read_b128 v[174:177], v156 offset:3072
	ds_read_b128 v[192:195], v156 offset:4096
	ds_read_b128 v[196:199], v156 offset:5120
	ds_read_b128 v[200:203], v156 offset:6144
	ds_read_b128 v[204:207], v156 offset:7168
	global_load_lds_dwordx4 v[178:179], off
	v_lshl_add_u64 v[178:179], s[18:19], 0, v[148:149]
	s_add_i32 m0, s90, 0xe000
	s_nop 0
	global_load_lds_dwordx4 v[178:179], off
	s_waitcnt lgkmcnt(8)
	s_barrier
	s_waitcnt lgkmcnt(0)
	s_setprio 1
	s_waitcnt lgkmcnt(0)
	v_mfma_f32_16x16x32_bf16 v[126:129], v[130:133], v[162:165], v[126:129]
	v_mfma_f32_16x16x32_bf16 v[122:125], v[150:153], v[162:165], v[122:125]
	v_mfma_f32_16x16x32_bf16 v[118:121], v[130:133], v[170:173], v[118:121]
	v_mfma_f32_16x16x32_bf16 v[110:113], v[150:153], v[170:173], v[110:113]
	v_mfma_f32_16x16x32_bf16 v[102:105], v[130:133], v[192:195], v[102:105]
	v_mfma_f32_16x16x32_bf16 v[94:97], v[150:153], v[192:195], v[94:97]
	v_mfma_f32_16x16x32_bf16 v[86:89], v[130:133], v[200:203], v[86:89]
	v_mfma_f32_16x16x32_bf16 v[78:81], v[150:153], v[200:203], v[78:81]
	v_mfma_f32_16x16x32_bf16 v[126:129], v[134:137], v[166:169], v[126:129]
	v_mfma_f32_16x16x32_bf16 v[122:125], v[158:161], v[166:169], v[122:125]
	v_mfma_f32_16x16x32_bf16 v[118:121], v[134:137], v[174:177], v[118:121]
	v_mfma_f32_16x16x32_bf16 v[110:113], v[158:161], v[174:177], v[110:113]
	v_mfma_f32_16x16x32_bf16 v[102:105], v[134:137], v[196:199], v[102:105]
	v_mfma_f32_16x16x32_bf16 v[94:97], v[158:161], v[196:199], v[94:97]
	v_mfma_f32_16x16x32_bf16 v[86:89], v[134:137], v[204:207], v[86:89]
	v_mfma_f32_16x16x32_bf16 v[78:81], v[158:161], v[204:207], v[78:81]
	s_setprio 0
	s_barrier
	s_add_i32 s52, 0, 0x14000
	s_add_i32 s50, s50, s36
	v_add_u32_e32 v157, s52, v154
	v_lshl_add_u64 v[178:179], s[20:21], 0, v[142:143]
	s_mov_b32 m0, s50
	ds_read_b128 v[208:211], v157
	ds_read_b128 v[224:227], v157 offset:1024
	ds_read_b128 v[228:231], v157 offset:2048
	ds_read_b128 v[232:235], v157 offset:3072
	global_load_lds_dwordx4 v[178:179], off
	v_lshl_add_u64 v[212:213], s[20:21], 0, v[138:139]
	s_add_i32 m0, s50, 0x2000
	s_nop 0
	global_load_lds_dwordx4 v[212:213], off
	s_barrier
	s_waitcnt lgkmcnt(0)
	s_setprio 1
	s_waitcnt lgkmcnt(0)
	v_mfma_f32_16x16x32_bf16 v[114:117], v[208:211], v[162:165], v[114:117]
	v_mfma_f32_16x16x32_bf16 v[106:109], v[228:231], v[162:165], v[106:109]
	v_mfma_f32_16x16x32_bf16 v[98:101], v[208:211], v[170:173], v[98:101]
	v_mfma_f32_16x16x32_bf16 v[90:93], v[228:231], v[170:173], v[90:93]
	v_mfma_f32_16x16x32_bf16 v[82:85], v[208:211], v[192:195], v[82:85]
	v_mfma_f32_16x16x32_bf16 v[74:77], v[228:231], v[192:195], v[74:77]
	v_mfma_f32_16x16x32_bf16 v[70:73], v[208:211], v[200:203], v[70:73]
	v_mfma_f32_16x16x32_bf16 v[66:69], v[228:231], v[200:203], v[66:69]
	v_mfma_f32_16x16x32_bf16 v[114:117], v[224:227], v[166:169], v[114:117]
	v_mfma_f32_16x16x32_bf16 v[106:109], v[232:235], v[166:169], v[106:109]
	v_mfma_f32_16x16x32_bf16 v[98:101], v[224:227], v[174:177], v[98:101]
	v_mfma_f32_16x16x32_bf16 v[90:93], v[232:235], v[174:177], v[90:93]
	v_mfma_f32_16x16x32_bf16 v[82:85], v[224:227], v[196:199], v[82:85]
	v_mfma_f32_16x16x32_bf16 v[74:77], v[232:235], v[196:199], v[74:77]
	v_mfma_f32_16x16x32_bf16 v[70:73], v[224:227], v[204:207], v[70:73]
	v_mfma_f32_16x16x32_bf16 v[66:69], v[232:235], v[204:207], v[66:69]
	s_setprio 0
	s_mov_b32 m0, s90
	v_lshl_add_u64 v[236:237], s[22:23], 0, v[144:145]
	s_barrier
	ds_read_b128 v[162:165], v156 offset:16384
	ds_read_b128 v[166:169], v156 offset:17408
	ds_read_b128 v[170:173], v156 offset:18432
	ds_read_b128 v[174:177], v156 offset:19456
	ds_read_b128 v[192:195], v156 offset:20480
	ds_read_b128 v[196:199], v156 offset:21504
	ds_read_b128 v[200:203], v156 offset:22528
	ds_read_b128 v[204:207], v156 offset:23552
	global_load_lds_dwordx4 v[236:237], off
	v_lshl_add_u64 v[238:239], s[22:23], 0, v[140:141]
	s_mov_b32 m0, s91
	s_nop 0
	global_load_lds_dwordx4 v[238:239], off
	s_waitcnt vmcnt(10)
	s_barrier
	s_waitcnt lgkmcnt(0)
	s_setprio 1
	s_waitcnt lgkmcnt(0)
	v_mfma_f32_16x16x32_bf16 v[62:65], v[130:133], v[162:165], v[62:65]
	v_mfma_f32_16x16x32_bf16 v[58:61], v[150:153], v[162:165], v[58:61]
	v_mfma_f32_16x16x32_bf16 v[54:57], v[130:133], v[170:173], v[54:57]
	v_mfma_f32_16x16x32_bf16 v[46:49], v[150:153], v[170:173], v[46:49]
	v_mfma_f32_16x16x32_bf16 v[38:41], v[130:133], v[192:195], v[38:41]
	v_mfma_f32_16x16x32_bf16 v[30:33], v[150:153], v[192:195], v[30:33]
	v_mfma_f32_16x16x32_bf16 v[22:25], v[130:133], v[200:203], v[22:25]
	v_mfma_f32_16x16x32_bf16 v[14:17], v[150:153], v[200:203], v[14:17]
	v_mfma_f32_16x16x32_bf16 v[62:65], v[134:137], v[166:169], v[62:65]
	v_mfma_f32_16x16x32_bf16 v[58:61], v[158:161], v[166:169], v[58:61]
	v_mfma_f32_16x16x32_bf16 v[54:57], v[134:137], v[174:177], v[54:57]
	v_mfma_f32_16x16x32_bf16 v[46:49], v[158:161], v[174:177], v[46:49]
	v_mfma_f32_16x16x32_bf16 v[38:41], v[134:137], v[196:199], v[38:41]
	v_mfma_f32_16x16x32_bf16 v[30:33], v[158:161], v[196:199], v[30:33]
	v_mfma_f32_16x16x32_bf16 v[22:25], v[134:137], v[204:207], v[22:25]
	v_mfma_f32_16x16x32_bf16 v[14:17], v[158:161], v[204:207], v[14:17]
	s_setprio 0
	s_barrier
	s_add_u32 s50, s20, 0x20000
	s_addc_u32 s51, s21, 0
	s_add_i32 s52, s52, s36
	v_lshl_add_u64 v[130:131], s[50:51], 0, v[142:143]
	s_mov_b32 m0, s52
	s_nop 0
	global_load_lds_dwordx4 v[130:131], off
	v_lshl_add_u64 v[130:131], s[50:51], 0, v[138:139]
	s_add_i32 m0, s52, 0x2000
	s_nop 0
	global_load_lds_dwordx4 v[130:131], off
	v_add_u32_e32 v157, 0x18000, v154
	ds_read_b128 v[130:133], v157
	ds_read_b128 v[134:137], v157 offset:1024
	ds_read_b128 v[150:153], v157 offset:2048
	ds_read_b128 v[158:161], v157 offset:3072
	s_waitcnt vmcnt(6)
	s_barrier
	s_setprio 1
	v_mfma_f32_16x16x32_bf16 v[50:53], v[208:211], v[162:165], v[50:53]
	v_mfma_f32_16x16x32_bf16 v[42:45], v[228:231], v[162:165], v[42:45]
	v_mfma_f32_16x16x32_bf16 v[34:37], v[208:211], v[170:173], v[34:37]
	v_mfma_f32_16x16x32_bf16 v[26:29], v[228:231], v[170:173], v[26:29]
	v_mfma_f32_16x16x32_bf16 v[18:21], v[208:211], v[192:195], v[18:21]
	v_mfma_f32_16x16x32_bf16 v[10:13], v[228:231], v[192:195], v[10:13]
	v_mfma_f32_16x16x32_bf16 v[6:9], v[208:211], v[200:203], v[6:9]
	v_mfma_f32_16x16x32_bf16 v[2:5], v[228:231], v[200:203], v[2:5]
	v_mfma_f32_16x16x32_bf16 v[50:53], v[224:227], v[166:169], v[50:53]
	v_mfma_f32_16x16x32_bf16 v[42:45], v[232:235], v[166:169], v[42:45]
	v_mfma_f32_16x16x32_bf16 v[34:37], v[224:227], v[174:177], v[34:37]
	v_mfma_f32_16x16x32_bf16 v[26:29], v[232:235], v[174:177], v[26:29]
	v_mfma_f32_16x16x32_bf16 v[18:21], v[224:227], v[196:199], v[18:21]
	v_mfma_f32_16x16x32_bf16 v[10:13], v[232:235], v[196:199], v[10:13]
	v_mfma_f32_16x16x32_bf16 v[6:9], v[224:227], v[204:207], v[6:9]
	v_mfma_f32_16x16x32_bf16 v[2:5], v[232:235], v[204:207], v[2:5]
	s_setprio 0
	s_add_i32 s50, 0, 0x18000
	s_barrier
	s_add_u32 s22, s22, 0x20000
	s_addc_u32 s23, s23, 0
	s_mov_b32 m0, s42
	v_lshl_add_u64 v[208:209], s[22:23], 0, v[144:145]
	ds_read_b128 v[162:165], v156 offset:32768
	ds_read_b128 v[166:169], v156 offset:33792
	ds_read_b128 v[170:173], v156 offset:34816
	ds_read_b128 v[174:177], v156 offset:35840
	ds_read_b128 v[192:195], v156 offset:36864
	ds_read_b128 v[196:199], v156 offset:37888
	ds_read_b128 v[200:203], v156 offset:38912
	ds_read_b128 v[204:207], v156 offset:39936
	global_load_lds_dwordx4 v[208:209], off
	v_lshl_add_u64 v[208:209], s[22:23], 0, v[140:141]
	s_mov_b32 m0, s43
	s_nop 0
	global_load_lds_dwordx4 v[208:209], off
	s_waitcnt lgkmcnt(8)
	s_barrier
	s_waitcnt lgkmcnt(0)
	s_setprio 1
	s_waitcnt lgkmcnt(0)
	v_mfma_f32_16x16x32_bf16 v[126:129], v[130:133], v[162:165], v[126:129]
	v_mfma_f32_16x16x32_bf16 v[122:125], v[150:153], v[162:165], v[122:125]
	v_mfma_f32_16x16x32_bf16 v[118:121], v[130:133], v[170:173], v[118:121]
	v_mfma_f32_16x16x32_bf16 v[110:113], v[150:153], v[170:173], v[110:113]
	v_mfma_f32_16x16x32_bf16 v[102:105], v[130:133], v[192:195], v[102:105]
	v_mfma_f32_16x16x32_bf16 v[94:97], v[150:153], v[192:195], v[94:97]
	v_mfma_f32_16x16x32_bf16 v[86:89], v[130:133], v[200:203], v[86:89]
	v_mfma_f32_16x16x32_bf16 v[78:81], v[150:153], v[200:203], v[78:81]
	v_mfma_f32_16x16x32_bf16 v[126:129], v[134:137], v[166:169], v[126:129]
	v_mfma_f32_16x16x32_bf16 v[122:125], v[158:161], v[166:169], v[122:125]
	v_mfma_f32_16x16x32_bf16 v[118:121], v[134:137], v[174:177], v[118:121]
	v_mfma_f32_16x16x32_bf16 v[110:113], v[158:161], v[174:177], v[110:113]
	v_mfma_f32_16x16x32_bf16 v[102:105], v[134:137], v[196:199], v[102:105]
	v_mfma_f32_16x16x32_bf16 v[94:97], v[158:161], v[196:199], v[94:97]
	v_mfma_f32_16x16x32_bf16 v[86:89], v[134:137], v[204:207], v[86:89]
	v_mfma_f32_16x16x32_bf16 v[78:81], v[158:161], v[204:207], v[78:81]
	s_setprio 0
	s_barrier
	s_add_i32 s22, 0, 0x1c000
	s_add_i32 s23, s50, s36
	v_add_u32_e32 v157, s22, v154
	v_lshl_add_u64 v[178:179], v[178:179], 0, s[78:79]
	s_mov_b32 m0, s23
	ds_read_b128 v[208:211], v157
	ds_read_b128 v[224:227], v157 offset:1024
	ds_read_b128 v[228:231], v157 offset:2048
	ds_read_b128 v[232:235], v157 offset:3072
	global_load_lds_dwordx4 v[178:179], off
	v_lshl_add_u64 v[178:179], v[212:213], 0, s[78:79]
	s_add_i32 m0, s23, 0x2000
	s_nop 0
	global_load_lds_dwordx4 v[178:179], off
	s_barrier
	s_waitcnt lgkmcnt(0)
	s_setprio 1
	s_waitcnt lgkmcnt(0)
	v_mfma_f32_16x16x32_bf16 v[114:117], v[208:211], v[162:165], v[114:117]
	v_mfma_f32_16x16x32_bf16 v[106:109], v[228:231], v[162:165], v[106:109]
	v_mfma_f32_16x16x32_bf16 v[98:101], v[208:211], v[170:173], v[98:101]
	v_mfma_f32_16x16x32_bf16 v[90:93], v[228:231], v[170:173], v[90:93]
	v_mfma_f32_16x16x32_bf16 v[82:85], v[208:211], v[192:195], v[82:85]
	v_mfma_f32_16x16x32_bf16 v[74:77], v[228:231], v[192:195], v[74:77]
	v_mfma_f32_16x16x32_bf16 v[70:73], v[208:211], v[200:203], v[70:73]
	v_mfma_f32_16x16x32_bf16 v[66:69], v[228:231], v[200:203], v[66:69]
	v_mfma_f32_16x16x32_bf16 v[114:117], v[224:227], v[166:169], v[114:117]
	v_mfma_f32_16x16x32_bf16 v[106:109], v[232:235], v[166:169], v[106:109]
	v_mfma_f32_16x16x32_bf16 v[98:101], v[224:227], v[174:177], v[98:101]
	v_mfma_f32_16x16x32_bf16 v[90:93], v[232:235], v[174:177], v[90:93]
	v_mfma_f32_16x16x32_bf16 v[82:85], v[224:227], v[196:199], v[82:85]
	v_mfma_f32_16x16x32_bf16 v[74:77], v[232:235], v[196:199], v[74:77]
	v_mfma_f32_16x16x32_bf16 v[70:73], v[224:227], v[204:207], v[70:73]
	v_mfma_f32_16x16x32_bf16 v[66:69], v[232:235], v[204:207], v[66:69]
	s_setprio 0
	s_mov_b32 m0, s25
	v_lshl_add_u64 v[178:179], v[236:237], 0, s[78:79]
	s_barrier
	ds_read_b128 v[162:165], v156 offset:49152
	ds_read_b128 v[166:169], v156 offset:50176
	ds_read_b128 v[170:173], v156 offset:51200
	ds_read_b128 v[174:177], v156 offset:52224
	ds_read_b128 v[192:195], v156 offset:53248
	ds_read_b128 v[196:199], v156 offset:54272
	ds_read_b128 v[200:203], v156 offset:55296
	ds_read_b128 v[204:207], v156 offset:56320
	global_load_lds_dwordx4 v[178:179], off
	v_lshl_add_u64 v[178:179], v[238:239], 0, s[78:79]
	s_mov_b32 m0, s26
	s_nop 0
	global_load_lds_dwordx4 v[178:179], off
	s_waitcnt vmcnt(10)
	s_barrier
	s_waitcnt lgkmcnt(0)
	s_setprio 1
	s_waitcnt lgkmcnt(0)
	v_mfma_f32_16x16x32_bf16 v[62:65], v[130:133], v[162:165], v[62:65]
	v_mfma_f32_16x16x32_bf16 v[58:61], v[150:153], v[162:165], v[58:61]
	v_mfma_f32_16x16x32_bf16 v[54:57], v[130:133], v[170:173], v[54:57]
	v_mfma_f32_16x16x32_bf16 v[46:49], v[150:153], v[170:173], v[46:49]
	v_mfma_f32_16x16x32_bf16 v[38:41], v[130:133], v[192:195], v[38:41]
	v_mfma_f32_16x16x32_bf16 v[30:33], v[150:153], v[192:195], v[30:33]
	v_mfma_f32_16x16x32_bf16 v[22:25], v[130:133], v[200:203], v[22:25]
	v_mfma_f32_16x16x32_bf16 v[14:17], v[150:153], v[200:203], v[14:17]
	v_mfma_f32_16x16x32_bf16 v[62:65], v[134:137], v[166:169], v[62:65]
	v_mfma_f32_16x16x32_bf16 v[58:61], v[158:161], v[166:169], v[58:61]
	v_mfma_f32_16x16x32_bf16 v[54:57], v[134:137], v[174:177], v[54:57]
	v_mfma_f32_16x16x32_bf16 v[46:49], v[158:161], v[174:177], v[46:49]
	v_mfma_f32_16x16x32_bf16 v[38:41], v[134:137], v[196:199], v[38:41]
	v_mfma_f32_16x16x32_bf16 v[30:33], v[158:161], v[196:199], v[30:33]
	v_mfma_f32_16x16x32_bf16 v[22:25], v[134:137], v[204:207], v[22:25]
	v_mfma_f32_16x16x32_bf16 v[14:17], v[158:161], v[204:207], v[14:17]
	s_setprio 0
	s_barrier
	s_add_u32 s20, s20, 0x20080
	s_addc_u32 s21, s21, 0
	s_add_i32 s22, s22, s36
	v_lshl_add_u64 v[130:131], s[20:21], 0, v[142:143]
	s_mov_b32 m0, s22
	s_nop 0
	global_load_lds_dwordx4 v[130:131], off
	v_lshl_add_u64 v[130:131], s[20:21], 0, v[138:139]
	s_add_i32 m0, s22, 0x2000
	s_nop 0
	global_load_lds_dwordx4 v[130:131], off
	v_add_u32_e32 v157, 0x10000, v154
	ds_read_b128 v[130:133], v157
	ds_read_b128 v[134:137], v157 offset:1024
	ds_read_b128 v[150:153], v157 offset:2048
	ds_read_b128 v[158:161], v157 offset:3072
	s_waitcnt vmcnt(6)
	s_barrier
	s_setprio 1
	v_mfma_f32_16x16x32_bf16 v[50:53], v[208:211], v[162:165], v[50:53]
	v_mfma_f32_16x16x32_bf16 v[42:45], v[228:231], v[162:165], v[42:45]
	v_mfma_f32_16x16x32_bf16 v[34:37], v[208:211], v[170:173], v[34:37]
	v_mfma_f32_16x16x32_bf16 v[26:29], v[228:231], v[170:173], v[26:29]
	v_mfma_f32_16x16x32_bf16 v[18:21], v[208:211], v[192:195], v[18:21]
	v_mfma_f32_16x16x32_bf16 v[10:13], v[228:231], v[192:195], v[10:13]
	v_mfma_f32_16x16x32_bf16 v[6:9], v[208:211], v[200:203], v[6:9]
	v_mfma_f32_16x16x32_bf16 v[2:5], v[228:231], v[200:203], v[2:5]
	v_mfma_f32_16x16x32_bf16 v[50:53], v[224:227], v[166:169], v[50:53]
	v_mfma_f32_16x16x32_bf16 v[42:45], v[232:235], v[166:169], v[42:45]
	v_mfma_f32_16x16x32_bf16 v[34:37], v[224:227], v[174:177], v[34:37]
	v_mfma_f32_16x16x32_bf16 v[26:29], v[232:235], v[174:177], v[26:29]
	v_mfma_f32_16x16x32_bf16 v[18:21], v[224:227], v[196:199], v[18:21]
	v_mfma_f32_16x16x32_bf16 v[10:13], v[232:235], v[196:199], v[10:13]
	v_mfma_f32_16x16x32_bf16 v[6:9], v[224:227], v[204:207], v[6:9]
	v_mfma_f32_16x16x32_bf16 v[2:5], v[232:235], v[204:207], v[2:5]
	s_setprio 0
	s_add_i32 s49, s49, 2
	s_add_u32 s18, s18, 0x100
	s_addc_u32 s19, s19, 0
	s_add_u32 s47, s47, 0x100
	s_addc_u32 s48, s48, 0
	s_cmp_gt_u32 s49, 5
	s_barrier
	s_cbranch_scc0 .LBB0_386
	s_waitcnt lgkmcnt(0)
	v_lshl_add_u32 v164, s29, 8, v1
	v_lshl_or_b32 v150, s28, 8, v155
	s_mov_b64 s[18:19], -1
	s_cmp_lt_i32 s28, 8
	v_or_b32_e32 v163, 16, v164
	v_or_b32_e32 v162, 32, v164
	v_or_b32_e32 v161, 48, v164
	v_add_u32_e32 v160, 0x80, v164
	v_add_u32_e32 v159, 0x90, v164
	v_add_u32_e32 v158, 0xa0, v164
	v_add_u32_e32 v157, 0xb0, v164
	s_cbranch_scc1 .LBB0_389
	v_lshlrev_b32_e32 v130, 7, v164
	v_readlane_b32 s4, v255, 4
	v_and_b32_e32 v132, 0x3e780, v130
	v_mov_b32_e32 v133, v0
	v_readlane_b32 s5, v255, 5
	v_readlane_b32 s6, v255, 6
	v_readlane_b32 s7, v255, 7
	v_lshlrev_b32_e32 v130, 1, v150
	v_lshl_add_u64 v[134:135], s[4:5], 0, v[132:133]
	v_and_b32_e32 v130, 0x70, v130
	v_mov_b32_e32 v131, v0
	v_lshl_add_u64 v[132:133], s[6:7], 0, v[132:133]
	v_lshl_add_u64 v[152:153], v[132:133], 0, v[130:131]
	v_lshl_add_u64 v[136:137], v[134:135], 0, v[130:131]
	global_load_dwordx4 v[170:173], v[152:153], off
	global_load_dwordx4 v[166:169], v[136:137], off
	v_readlane_b32 s8, v255, 8
	v_readlane_b32 s9, v255, 9
	v_mov_b32_e32 v151, v0
	v_lshlrev_b64 v[134:135], 1, v[150:151]
	v_mov_b64_e32 v[132:133], s[8:9]
	v_mad_i64_i32 v[174:175], s[18:19], v164, s24, v[132:133]
	v_lshl_add_u64 v[174:175], v[174:175], 0, v[134:135]
	v_readlane_b32 s10, v255, 10
	v_readlane_b32 s11, v255, 11
	s_waitcnt vmcnt(0)
	v_pk_mul_f32 v[172:173], v[172:173], s[86:87] op_sel_hi:[1,0]
	v_pk_mul_f32 v[170:171], v[170:171], s[86:87] op_sel_hi:[1,0]
	v_pk_mul_f32 v[168:169], v[168:169], s[86:87] op_sel_hi:[1,0]
	v_pk_mul_f32 v[166:167], v[166:167], s[86:87] op_sel_hi:[1,0]
	v_pk_mul_f32 v[176:177], v[124:125], v[172:173]
	v_pk_mul_f32 v[178:179], v[122:123], v[170:171]
	v_pk_mul_f32 v[172:173], v[128:129], v[172:173]
	v_pk_mul_f32 v[170:171], v[126:127], v[170:171]
	v_pk_fma_f32 v[176:177], v[128:129], v[168:169], v[176:177] neg_lo:[0,0,1] neg_hi:[0,0,1]
	v_pk_fma_f32 v[178:179], v[126:127], v[166:167], v[178:179] neg_lo:[0,0,1] neg_hi:[0,0,1]
	v_pk_fma_f32 v[172:173], v[124:125], v[168:169], v[172:173]
	v_pk_fma_f32 v[168:169], v[122:123], v[166:167], v[170:171]
	v_cvt_pk_bf16_f32 v166, v178, v179
	v_cvt_pk_bf16_f32 v167, v176, v177
	v_cvt_pk_bf16_f32 v168, v168, v169
	v_cvt_pk_bf16_f32 v169, v172, v173
	global_store_dwordx4 v[174:175], v[166:169], off
	global_load_dwordx4 v[166:169], v[136:137], off
	s_nop 0
	global_load_dwordx4 v[170:173], v[152:153], off
	v_lshlrev_b32_e32 v136, 7, v163
	v_mov_b32_e32 v137, v0
	v_and_b32_e32 v136, 0x3ef80, v136
	v_lshl_add_u64 v[152:153], s[4:5], 0, v[136:137]
	v_lshl_add_u64 v[136:137], s[6:7], 0, v[136:137]
	v_lshl_add_u64 v[136:137], v[136:137], 0, v[130:131]
	v_lshl_add_u64 v[152:153], v[152:153], 0, v[130:131]
	s_waitcnt vmcnt(0)
	v_pk_mul_f32 v[168:169], v[168:169], s[86:87] op_sel_hi:[1,0]
	v_pk_mul_f32 v[172:173], v[172:173], s[86:87] op_sel_hi:[1,0]
	v_pk_mul_f32 v[170:171], v[170:171], s[86:87] op_sel_hi:[1,0]
	v_pk_mul_f32 v[166:167], v[166:167], s[86:87] op_sel_hi:[1,0]
	v_pk_mul_f32 v[176:177], v[108:109], v[172:173]
	v_pk_mul_f32 v[178:179], v[106:107], v[170:171]
	v_pk_mul_f32 v[172:173], v[116:117], v[172:173]
	v_pk_mul_f32 v[170:171], v[114:115], v[170:171]
	v_pk_fma_f32 v[176:177], v[116:117], v[168:169], v[176:177] neg_lo:[0,0,1] neg_hi:[0,0,1]
	v_pk_fma_f32 v[178:179], v[114:115], v[166:167], v[178:179] neg_lo:[0,0,1] neg_hi:[0,0,1]
	v_pk_fma_f32 v[172:173], v[108:109], v[168:169], v[172:173]
	v_pk_fma_f32 v[168:169], v[106:107], v[166:167], v[170:171]
	v_cvt_pk_bf16_f32 v166, v178, v179
	v_cvt_pk_bf16_f32 v167, v176, v177
	v_cvt_pk_bf16_f32 v168, v168, v169
	v_cvt_pk_bf16_f32 v169, v172, v173
	global_store_dwordx4 v[174:175], v[166:169], off offset:256
	global_load_dwordx4 v[170:173], v[136:137], off
	v_mad_i64_i32 v[174:175], s[18:19], v163, s24, v[132:133]
	global_load_dwordx4 v[166:169], v[152:153], off
	v_lshl_add_u64 v[174:175], v[174:175], 0, v[134:135]
	s_waitcnt vmcnt(0)
	v_pk_mul_f32 v[172:173], v[172:173], s[86:87] op_sel_hi:[1,0]
	v_pk_mul_f32 v[170:171], v[170:171], s[86:87] op_sel_hi:[1,0]
	v_pk_mul_f32 v[176:177], v[112:113], v[172:173]
	v_pk_mul_f32 v[168:169], v[168:169], s[86:87] op_sel_hi:[1,0]
	v_pk_mul_f32 v[166:167], v[166:167], s[86:87] op_sel_hi:[1,0]
	v_pk_mul_f32 v[178:179], v[110:111], v[170:171]
	v_pk_mul_f32 v[172:173], v[120:121], v[172:173]
	v_pk_mul_f32 v[170:171], v[118:119], v[170:171]
	v_pk_fma_f32 v[176:177], v[120:121], v[168:169], v[176:177] neg_lo:[0,0,1] neg_hi:[0,0,1]
	v_pk_fma_f32 v[178:179], v[118:119], v[166:167], v[178:179] neg_lo:[0,0,1] neg_hi:[0,0,1]
	v_pk_fma_f32 v[172:173], v[112:113], v[168:169], v[172:173]
	v_pk_fma_f32 v[168:169], v[110:111], v[166:167], v[170:171]
	v_cvt_pk_bf16_f32 v166, v178, v179
	v_cvt_pk_bf16_f32 v167, v176, v177
	v_cvt_pk_bf16_f32 v168, v168, v169
	v_cvt_pk_bf16_f32 v169, v172, v173
	global_store_dwordx4 v[174:175], v[166:169], off
	global_load_dwordx4 v[166:169], v[152:153], off
	s_nop 0
	global_load_dwordx4 v[170:173], v[136:137], off
	v_lshlrev_b32_e32 v136, 7, v162
	v_mov_b32_e32 v137, v0
	v_and_b32_e32 v136, 0x3f780, v136
	v_lshl_add_u64 v[152:153], s[4:5], 0, v[136:137]
	v_lshl_add_u64 v[136:137], s[6:7], 0, v[136:137]
	v_lshl_add_u64 v[136:137], v[136:137], 0, v[130:131]
	v_lshl_add_u64 v[152:153], v[152:153], 0, v[130:131]
	s_waitcnt vmcnt(0)
	v_pk_mul_f32 v[168:169], v[168:169], s[86:87] op_sel_hi:[1,0]
	v_pk_mul_f32 v[172:173], v[172:173], s[86:87] op_sel_hi:[1,0]
	v_pk_mul_f32 v[170:171], v[170:171], s[86:87] op_sel_hi:[1,0]
	v_pk_mul_f32 v[166:167], v[166:167], s[86:87] op_sel_hi:[1,0]
	v_pk_mul_f32 v[176:177], v[92:93], v[172:173]
	v_pk_mul_f32 v[178:179], v[90:91], v[170:171]
	v_pk_mul_f32 v[172:173], v[100:101], v[172:173]
	v_pk_mul_f32 v[170:171], v[98:99], v[170:171]
	v_pk_fma_f32 v[176:177], v[100:101], v[168:169], v[176:177] neg_lo:[0,0,1] neg_hi:[0,0,1]
	v_pk_fma_f32 v[178:179], v[98:99], v[166:167], v[178:179] neg_lo:[0,0,1] neg_hi:[0,0,1]
	v_pk_fma_f32 v[172:173], v[92:93], v[168:169], v[172:173]
	v_pk_fma_f32 v[168:169], v[90:91], v[166:167], v[170:171]
	v_cvt_pk_bf16_f32 v166, v178, v179
	v_cvt_pk_bf16_f32 v167, v176, v177
	v_cvt_pk_bf16_f32 v168, v168, v169
	v_cvt_pk_bf16_f32 v169, v172, v173
	global_store_dwordx4 v[174:175], v[166:169], off offset:256
	global_load_dwordx4 v[170:173], v[136:137], off
	v_mad_i64_i32 v[174:175], s[18:19], v162, s24, v[132:133]
	global_load_dwordx4 v[166:169], v[152:153], off
	v_lshl_add_u64 v[174:175], v[174:175], 0, v[134:135]
	s_waitcnt vmcnt(0)
	v_pk_mul_f32 v[172:173], v[172:173], s[86:87] op_sel_hi:[1,0]
	v_pk_mul_f32 v[170:171], v[170:171], s[86:87] op_sel_hi:[1,0]
	v_pk_mul_f32 v[176:177], v[96:97], v[172:173]
	v_pk_mul_f32 v[168:169], v[168:169], s[86:87] op_sel_hi:[1,0]
	v_pk_mul_f32 v[166:167], v[166:167], s[86:87] op_sel_hi:[1,0]
	v_pk_mul_f32 v[178:179], v[94:95], v[170:171]
	v_pk_mul_f32 v[172:173], v[104:105], v[172:173]
	v_pk_mul_f32 v[170:171], v[102:103], v[170:171]
	v_pk_fma_f32 v[176:177], v[104:105], v[168:169], v[176:177] neg_lo:[0,0,1] neg_hi:[0,0,1]
	v_pk_fma_f32 v[178:179], v[102:103], v[166:167], v[178:179] neg_lo:[0,0,1] neg_hi:[0,0,1]
	v_pk_fma_f32 v[172:173], v[96:97], v[168:169], v[172:173]
	v_pk_fma_f32 v[168:169], v[94:95], v[166:167], v[170:171]
	v_cvt_pk_bf16_f32 v166, v178, v179
	v_cvt_pk_bf16_f32 v167, v176, v177
	v_cvt_pk_bf16_f32 v168, v168, v169
	v_cvt_pk_bf16_f32 v169, v172, v173
	global_store_dwordx4 v[174:175], v[166:169], off
	global_load_dwordx4 v[166:169], v[152:153], off
	s_nop 0
	global_load_dwordx4 v[170:173], v[136:137], off
	v_lshlrev_b32_e32 v136, 7, v161
	v_mov_b32_e32 v137, v0
	v_and_b32_e32 v136, 0x3ff80, v136
	v_lshl_add_u64 v[152:153], s[4:5], 0, v[136:137]
	v_lshl_add_u64 v[136:137], s[6:7], 0, v[136:137]
	v_lshl_add_u64 v[136:137], v[136:137], 0, v[130:131]
	v_lshl_add_u64 v[152:153], v[152:153], 0, v[130:131]
	s_waitcnt vmcnt(0)
	v_pk_mul_f32 v[168:169], v[168:169], s[86:87] op_sel_hi:[1,0]
	v_pk_mul_f32 v[172:173], v[172:173], s[86:87] op_sel_hi:[1,0]
	v_pk_mul_f32 v[170:171], v[170:171], s[86:87] op_sel_hi:[1,0]
	v_pk_mul_f32 v[166:167], v[166:167], s[86:87] op_sel_hi:[1,0]
	v_pk_mul_f32 v[176:177], v[76:77], v[172:173]
	v_pk_mul_f32 v[178:179], v[74:75], v[170:171]
	v_pk_mul_f32 v[172:173], v[84:85], v[172:173]
	v_pk_mul_f32 v[170:171], v[82:83], v[170:171]
	v_pk_fma_f32 v[176:177], v[84:85], v[168:169], v[176:177] neg_lo:[0,0,1] neg_hi:[0,0,1]
	v_pk_fma_f32 v[178:179], v[82:83], v[166:167], v[178:179] neg_lo:[0,0,1] neg_hi:[0,0,1]
	v_pk_fma_f32 v[172:173], v[76:77], v[168:169], v[172:173]
	v_pk_fma_f32 v[168:169], v[74:75], v[166:167], v[170:171]
	v_cvt_pk_bf16_f32 v166, v178, v179
	v_cvt_pk_bf16_f32 v167, v176, v177
	v_cvt_pk_bf16_f32 v168, v168, v169
	v_cvt_pk_bf16_f32 v169, v172, v173
	global_store_dwordx4 v[174:175], v[166:169], off offset:256
	global_load_dwordx4 v[170:173], v[136:137], off
	v_mad_i64_i32 v[174:175], s[18:19], v161, s24, v[132:133]
	global_load_dwordx4 v[166:169], v[152:153], off
	v_lshl_add_u64 v[174:175], v[174:175], 0, v[134:135]
	s_waitcnt vmcnt(0)
	v_pk_mul_f32 v[172:173], v[172:173], s[86:87] op_sel_hi:[1,0]
	v_pk_mul_f32 v[170:171], v[170:171], s[86:87] op_sel_hi:[1,0]
	v_pk_mul_f32 v[176:177], v[80:81], v[172:173]
	v_pk_mul_f32 v[168:169], v[168:169], s[86:87] op_sel_hi:[1,0]
	v_pk_mul_f32 v[166:167], v[166:167], s[86:87] op_sel_hi:[1,0]
	v_pk_mul_f32 v[178:179], v[78:79], v[170:171]
	v_pk_mul_f32 v[172:173], v[88:89], v[172:173]
	v_pk_mul_f32 v[170:171], v[86:87], v[170:171]
	v_pk_fma_f32 v[176:177], v[88:89], v[168:169], v[176:177] neg_lo:[0,0,1] neg_hi:[0,0,1]
	v_pk_fma_f32 v[178:179], v[86:87], v[166:167], v[178:179] neg_lo:[0,0,1] neg_hi:[0,0,1]
	v_pk_fma_f32 v[172:173], v[80:81], v[168:169], v[172:173]
	v_pk_fma_f32 v[168:169], v[78:79], v[166:167], v[170:171]
	v_cvt_pk_bf16_f32 v166, v178, v179
	v_cvt_pk_bf16_f32 v167, v176, v177
	v_cvt_pk_bf16_f32 v168, v168, v169
	v_cvt_pk_bf16_f32 v169, v172, v173
	global_store_dwordx4 v[174:175], v[166:169], off
	global_load_dwordx4 v[166:169], v[152:153], off
	s_nop 0
	global_load_dwordx4 v[170:173], v[136:137], off
	v_lshlrev_b32_e32 v136, 7, v160
	v_mov_b32_e32 v137, v0
	v_and_b32_e32 v136, 0x3e780, v136
	v_lshl_add_u64 v[152:153], s[4:5], 0, v[136:137]
	v_lshl_add_u64 v[136:137], s[6:7], 0, v[136:137]
	v_lshl_add_u64 v[136:137], v[136:137], 0, v[130:131]
	v_lshl_add_u64 v[152:153], v[152:153], 0, v[130:131]
	s_waitcnt vmcnt(0)
	v_pk_mul_f32 v[168:169], v[168:169], s[86:87] op_sel_hi:[1,0]
	v_pk_mul_f32 v[172:173], v[172:173], s[86:87] op_sel_hi:[1,0]
	v_pk_mul_f32 v[170:171], v[170:171], s[86:87] op_sel_hi:[1,0]
	v_pk_mul_f32 v[166:167], v[166:167], s[86:87] op_sel_hi:[1,0]
	v_pk_mul_f32 v[176:177], v[68:69], v[172:173]
	v_pk_mul_f32 v[178:179], v[66:67], v[170:171]
	v_pk_mul_f32 v[172:173], v[72:73], v[172:173]
	v_pk_mul_f32 v[170:171], v[70:71], v[170:171]
	v_pk_fma_f32 v[176:177], v[72:73], v[168:169], v[176:177] neg_lo:[0,0,1] neg_hi:[0,0,1]
	v_pk_fma_f32 v[178:179], v[70:71], v[166:167], v[178:179] neg_lo:[0,0,1] neg_hi:[0,0,1]
	v_pk_fma_f32 v[172:173], v[68:69], v[168:169], v[172:173]
	v_pk_fma_f32 v[168:169], v[66:67], v[166:167], v[170:171]
	v_cvt_pk_bf16_f32 v166, v178, v179
	v_cvt_pk_bf16_f32 v167, v176, v177
	v_cvt_pk_bf16_f32 v168, v168, v169
	v_cvt_pk_bf16_f32 v169, v172, v173
	global_store_dwordx4 v[174:175], v[166:169], off offset:256
	global_load_dwordx4 v[170:173], v[136:137], off
	v_mad_i64_i32 v[174:175], s[18:19], v160, s24, v[132:133]
	global_load_dwordx4 v[166:169], v[152:153], off
	v_lshl_add_u64 v[174:175], v[174:175], 0, v[134:135]
	s_waitcnt vmcnt(0)
	v_pk_mul_f32 v[172:173], v[172:173], s[86:87] op_sel_hi:[1,0]
	v_pk_mul_f32 v[170:171], v[170:171], s[86:87] op_sel_hi:[1,0]
	v_pk_mul_f32 v[176:177], v[60:61], v[172:173]
	v_pk_mul_f32 v[168:169], v[168:169], s[86:87] op_sel_hi:[1,0]
	v_pk_mul_f32 v[166:167], v[166:167], s[86:87] op_sel_hi:[1,0]
	v_pk_mul_f32 v[178:179], v[58:59], v[170:171]
	v_pk_mul_f32 v[172:173], v[64:65], v[172:173]
	v_pk_mul_f32 v[170:171], v[62:63], v[170:171]
	v_pk_fma_f32 v[176:177], v[64:65], v[168:169], v[176:177] neg_lo:[0,0,1] neg_hi:[0,0,1]
	v_pk_fma_f32 v[178:179], v[62:63], v[166:167], v[178:179] neg_lo:[0,0,1] neg_hi:[0,0,1]
	v_pk_fma_f32 v[172:173], v[60:61], v[168:169], v[172:173]
	v_pk_fma_f32 v[168:169], v[58:59], v[166:167], v[170:171]
	v_cvt_pk_bf16_f32 v166, v178, v179
	v_cvt_pk_bf16_f32 v167, v176, v177
	v_cvt_pk_bf16_f32 v168, v168, v169
	v_cvt_pk_bf16_f32 v169, v172, v173
	global_store_dwordx4 v[174:175], v[166:169], off
	global_load_dwordx4 v[166:169], v[152:153], off
	s_nop 0
	global_load_dwordx4 v[170:173], v[136:137], off
	v_lshlrev_b32_e32 v136, 7, v159
	v_mov_b32_e32 v137, v0
	v_and_b32_e32 v136, 0x3ef80, v136
	v_lshl_add_u64 v[152:153], s[4:5], 0, v[136:137]
	v_lshl_add_u64 v[136:137], s[6:7], 0, v[136:137]
	v_lshl_add_u64 v[136:137], v[136:137], 0, v[130:131]
	v_lshl_add_u64 v[152:153], v[152:153], 0, v[130:131]
	s_waitcnt vmcnt(0)
	v_pk_mul_f32 v[168:169], v[168:169], s[86:87] op_sel_hi:[1,0]
	v_pk_mul_f32 v[172:173], v[172:173], s[86:87] op_sel_hi:[1,0]
	v_pk_mul_f32 v[170:171], v[170:171], s[86:87] op_sel_hi:[1,0]
	v_pk_mul_f32 v[166:167], v[166:167], s[86:87] op_sel_hi:[1,0]
	v_pk_mul_f32 v[176:177], v[44:45], v[172:173]
	v_pk_mul_f32 v[178:179], v[42:43], v[170:171]
	v_pk_mul_f32 v[172:173], v[52:53], v[172:173]
	v_pk_mul_f32 v[170:171], v[50:51], v[170:171]
	v_pk_fma_f32 v[176:177], v[52:53], v[168:169], v[176:177] neg_lo:[0,0,1] neg_hi:[0,0,1]
	v_pk_fma_f32 v[178:179], v[50:51], v[166:167], v[178:179] neg_lo:[0,0,1] neg_hi:[0,0,1]
	v_pk_fma_f32 v[172:173], v[44:45], v[168:169], v[172:173]
	v_pk_fma_f32 v[168:169], v[42:43], v[166:167], v[170:171]
	v_cvt_pk_bf16_f32 v166, v178, v179
	v_cvt_pk_bf16_f32 v167, v176, v177
	v_cvt_pk_bf16_f32 v168, v168, v169
	v_cvt_pk_bf16_f32 v169, v172, v173
	global_store_dwordx4 v[174:175], v[166:169], off offset:256
	global_load_dwordx4 v[170:173], v[136:137], off
	v_mad_i64_i32 v[174:175], s[18:19], v159, s24, v[132:133]
	global_load_dwordx4 v[166:169], v[152:153], off
	v_lshl_add_u64 v[174:175], v[174:175], 0, v[134:135]
	s_waitcnt vmcnt(0)
	v_pk_mul_f32 v[172:173], v[172:173], s[86:87] op_sel_hi:[1,0]
	v_pk_mul_f32 v[170:171], v[170:171], s[86:87] op_sel_hi:[1,0]
	v_pk_mul_f32 v[176:177], v[48:49], v[172:173]
	v_pk_mul_f32 v[168:169], v[168:169], s[86:87] op_sel_hi:[1,0]
	v_pk_mul_f32 v[166:167], v[166:167], s[86:87] op_sel_hi:[1,0]
	v_pk_mul_f32 v[178:179], v[46:47], v[170:171]
	v_pk_mul_f32 v[172:173], v[56:57], v[172:173]
	v_pk_mul_f32 v[170:171], v[54:55], v[170:171]
	v_pk_fma_f32 v[176:177], v[56:57], v[168:169], v[176:177] neg_lo:[0,0,1] neg_hi:[0,0,1]
	v_pk_fma_f32 v[178:179], v[54:55], v[166:167], v[178:179] neg_lo:[0,0,1] neg_hi:[0,0,1]
	v_pk_fma_f32 v[172:173], v[48:49], v[168:169], v[172:173]
	v_pk_fma_f32 v[168:169], v[46:47], v[166:167], v[170:171]
	v_cvt_pk_bf16_f32 v166, v178, v179
	v_cvt_pk_bf16_f32 v167, v176, v177
	v_cvt_pk_bf16_f32 v168, v168, v169
	v_cvt_pk_bf16_f32 v169, v172, v173
	global_store_dwordx4 v[174:175], v[166:169], off
	global_load_dwordx4 v[166:169], v[152:153], off
	s_nop 0
	global_load_dwordx4 v[170:173], v[136:137], off
	v_lshlrev_b32_e32 v136, 7, v158
	v_mov_b32_e32 v137, v0
	v_and_b32_e32 v136, 0x3f780, v136
	v_lshl_add_u64 v[152:153], s[4:5], 0, v[136:137]
	v_lshl_add_u64 v[136:137], s[6:7], 0, v[136:137]
	v_lshl_add_u64 v[136:137], v[136:137], 0, v[130:131]
	v_lshl_add_u64 v[152:153], v[152:153], 0, v[130:131]
	s_waitcnt vmcnt(0)
	v_pk_mul_f32 v[168:169], v[168:169], s[86:87] op_sel_hi:[1,0]
	v_pk_mul_f32 v[172:173], v[172:173], s[86:87] op_sel_hi:[1,0]
	v_pk_mul_f32 v[170:171], v[170:171], s[86:87] op_sel_hi:[1,0]
	v_pk_mul_f32 v[166:167], v[166:167], s[86:87] op_sel_hi:[1,0]
	v_pk_mul_f32 v[176:177], v[28:29], v[172:173]
	v_pk_mul_f32 v[178:179], v[26:27], v[170:171]
	v_pk_mul_f32 v[172:173], v[36:37], v[172:173]
	v_pk_mul_f32 v[170:171], v[34:35], v[170:171]
	v_pk_fma_f32 v[176:177], v[36:37], v[168:169], v[176:177] neg_lo:[0,0,1] neg_hi:[0,0,1]
	v_pk_fma_f32 v[178:179], v[34:35], v[166:167], v[178:179] neg_lo:[0,0,1] neg_hi:[0,0,1]
	v_pk_fma_f32 v[172:173], v[28:29], v[168:169], v[172:173]
	v_pk_fma_f32 v[168:169], v[26:27], v[166:167], v[170:171]
	v_cvt_pk_bf16_f32 v166, v178, v179
	v_cvt_pk_bf16_f32 v167, v176, v177
	v_cvt_pk_bf16_f32 v168, v168, v169
	v_cvt_pk_bf16_f32 v169, v172, v173
	global_store_dwordx4 v[174:175], v[166:169], off offset:256
	global_load_dwordx4 v[170:173], v[136:137], off
	v_mad_i64_i32 v[174:175], s[18:19], v158, s24, v[132:133]
	global_load_dwordx4 v[166:169], v[152:153], off
	v_lshl_add_u64 v[174:175], v[174:175], 0, v[134:135]
	s_waitcnt vmcnt(0)
	v_pk_mul_f32 v[172:173], v[172:173], s[86:87] op_sel_hi:[1,0]
	v_pk_mul_f32 v[170:171], v[170:171], s[86:87] op_sel_hi:[1,0]
	v_pk_mul_f32 v[176:177], v[32:33], v[172:173]
	v_pk_mul_f32 v[168:169], v[168:169], s[86:87] op_sel_hi:[1,0]
	v_pk_mul_f32 v[166:167], v[166:167], s[86:87] op_sel_hi:[1,0]
	v_pk_mul_f32 v[178:179], v[30:31], v[170:171]
	v_pk_mul_f32 v[172:173], v[40:41], v[172:173]
	v_pk_mul_f32 v[170:171], v[38:39], v[170:171]
	v_pk_fma_f32 v[176:177], v[40:41], v[168:169], v[176:177] neg_lo:[0,0,1] neg_hi:[0,0,1]
	v_pk_fma_f32 v[178:179], v[38:39], v[166:167], v[178:179] neg_lo:[0,0,1] neg_hi:[0,0,1]
	v_pk_fma_f32 v[172:173], v[32:33], v[168:169], v[172:173]
	v_pk_fma_f32 v[168:169], v[30:31], v[166:167], v[170:171]
	v_cvt_pk_bf16_f32 v166, v178, v179
	v_cvt_pk_bf16_f32 v167, v176, v177
	v_cvt_pk_bf16_f32 v168, v168, v169
	v_cvt_pk_bf16_f32 v169, v172, v173
	global_store_dwordx4 v[174:175], v[166:169], off
	global_load_dwordx4 v[166:169], v[152:153], off
	s_nop 0
	global_load_dwordx4 v[170:173], v[136:137], off
	v_lshlrev_b32_e32 v136, 7, v157
	v_mov_b32_e32 v137, v0
	v_and_b32_e32 v136, 0x3ff80, v136
	v_lshl_add_u64 v[152:153], s[4:5], 0, v[136:137]
	v_lshl_add_u64 v[176:177], v[152:153], 0, v[130:131]
	v_lshl_add_u64 v[136:137], s[6:7], 0, v[136:137]
	v_lshl_add_u64 v[136:137], v[136:137], 0, v[130:131]
	v_mad_i64_i32 v[130:131], s[18:19], v157, s24, v[132:133]
	s_mov_b64 s[18:19], 0
	s_waitcnt vmcnt(0)
	v_pk_mul_f32 v[152:153], v[168:169], s[86:87] op_sel_hi:[1,0]
	v_pk_mul_f32 v[168:169], v[172:173], s[86:87] op_sel_hi:[1,0]
	v_pk_mul_f32 v[170:171], v[170:171], s[86:87] op_sel_hi:[1,0]
	v_pk_mul_f32 v[166:167], v[166:167], s[86:87] op_sel_hi:[1,0]
	v_pk_mul_f32 v[172:173], v[12:13], v[168:169]
	v_pk_mul_f32 v[178:179], v[10:11], v[170:171]
	v_pk_mul_f32 v[168:169], v[20:21], v[168:169]
	v_pk_mul_f32 v[170:171], v[18:19], v[170:171]
	v_pk_fma_f32 v[172:173], v[20:21], v[152:153], v[172:173] neg_lo:[0,0,1] neg_hi:[0,0,1]
	v_pk_fma_f32 v[178:179], v[18:19], v[166:167], v[178:179] neg_lo:[0,0,1] neg_hi:[0,0,1]
	v_pk_fma_f32 v[152:153], v[12:13], v[152:153], v[168:169]
	v_pk_fma_f32 v[168:169], v[10:11], v[166:167], v[170:171]
	v_cvt_pk_bf16_f32 v166, v178, v179
	v_cvt_pk_bf16_f32 v167, v172, v173
	v_cvt_pk_bf16_f32 v168, v168, v169
	v_cvt_pk_bf16_f32 v169, v152, v153
	global_store_dwordx4 v[174:175], v[166:169], off offset:256
	global_load_dwordx4 v[166:169], v[176:177], off
	v_lshl_add_u64 v[152:153], v[130:131], 0, v[134:135]
	global_load_dwordx4 v[170:173], v[136:137], off
	s_waitcnt vmcnt(0)
	v_pk_mul_f32 v[132:133], v[166:167], s[86:87] op_sel_hi:[1,0]
	v_pk_mul_f32 v[130:131], v[168:169], s[86:87] op_sel_hi:[1,0]
	v_pk_mul_f32 v[134:135], v[172:173], s[86:87] op_sel_hi:[1,0]
	v_pk_mul_f32 v[166:167], v[170:171], s[86:87] op_sel_hi:[1,0]
	v_pk_mul_f32 v[168:169], v[16:17], v[134:135]
	v_pk_mul_f32 v[170:171], v[14:15], v[166:167]
	v_pk_mul_f32 v[134:135], v[24:25], v[134:135]
	v_pk_mul_f32 v[166:167], v[22:23], v[166:167]
	v_pk_fma_f32 v[168:169], v[24:25], v[130:131], v[168:169] neg_lo:[0,0,1] neg_hi:[0,0,1]
	v_pk_fma_f32 v[170:171], v[22:23], v[132:133], v[170:171] neg_lo:[0,0,1] neg_hi:[0,0,1]
	v_pk_fma_f32 v[134:135], v[16:17], v[130:131], v[134:135]
	v_pk_fma_f32 v[132:133], v[14:15], v[132:133], v[166:167]
	v_cvt_pk_bf16_f32 v130, v170, v171
	v_cvt_pk_bf16_f32 v131, v168, v169
	v_cvt_pk_bf16_f32 v132, v132, v133
	v_cvt_pk_bf16_f32 v133, v134, v135
	global_store_dwordx4 v[152:153], v[130:133], off
	global_load_dwordx4 v[130:133], v[176:177], off
	s_nop 0
	global_load_dwordx4 v[134:137], v[136:137], off
	s_waitcnt vmcnt(0)
	v_pk_mul_f32 v[166:167], v[132:133], s[86:87] op_sel_hi:[1,0]
	v_pk_mul_f32 v[168:169], v[130:131], s[86:87] op_sel_hi:[1,0]
	v_pk_mul_f32 v[130:131], v[136:137], s[86:87] op_sel_hi:[1,0]
	v_pk_mul_f32 v[132:133], v[134:135], s[86:87] op_sel_hi:[1,0]
	v_pk_mul_f32 v[134:135], v[4:5], v[130:131]
	v_pk_mul_f32 v[136:137], v[2:3], v[132:133]
	v_pk_mul_f32 v[170:171], v[8:9], v[130:131]
	v_pk_mul_f32 v[172:173], v[6:7], v[132:133]
	v_pk_fma_f32 v[132:133], v[8:9], v[166:167], v[134:135] neg_lo:[0,0,1] neg_hi:[0,0,1]
	v_pk_fma_f32 v[130:131], v[6:7], v[168:169], v[136:137] neg_lo:[0,0,1] neg_hi:[0,0,1]
	v_pk_fma_f32 v[136:137], v[4:5], v[166:167], v[170:171]
	v_pk_fma_f32 v[134:135], v[2:3], v[168:169], v[172:173]

.LBB0_525:
	v_mov_b64_e32 v[2:3], 0x300
	s_ashr_i32 s39, s38, 31
	v_cmp_lt_i64_e32 vcc, s[22:23], v[2:3]
	s_lshl_b64 s[22:23], s[38:39], 20
	s_add_u32 s42, s34, s22
	s_addc_u32 s43, s35, s23
	s_and_b64 s[22:23], vcc, exec
	s_cselect_b32 s39, s43, s19
	s_cselect_b32 s51, s42, s18
	s_ashr_i32 s31, s30, 31
	s_lshl_b64 s[22:23], s[30:31], 20
	s_add_u32 s80, s26, s22
	s_addc_u32 s81, s27, s23
	s_and_b64 s[22:23], vcc, exec
	s_cselect_b32 s31, s81, s21
	s_cselect_b32 s52, s80, s20
	s_add_u32 s18, s18, 0x80080
	s_addc_u32 s19, s19, 0
	s_add_u32 s53, s20, 0x100
	v_mov_b32_e32 v2, 0
	s_addc_u32 s54, s21, 0
	s_mov_b32 s55, -2
	v_mov_b32_e32 v3, v2
	v_mov_b32_e32 v4, v2
	v_mov_b32_e32 v5, v2
	v_mov_b32_e32 v6, v2
	v_mov_b32_e32 v7, v2
	v_mov_b32_e32 v8, v2
	v_mov_b32_e32 v9, v2
	v_mov_b32_e32 v10, v2
	v_mov_b32_e32 v11, v2
	v_mov_b32_e32 v12, v2
	v_mov_b32_e32 v13, v2
	v_mov_b32_e32 v14, v2
	v_mov_b32_e32 v15, v2
	v_mov_b32_e32 v16, v2
	v_mov_b32_e32 v17, v2
	v_mov_b32_e32 v26, v2
	v_mov_b32_e32 v27, v2
	v_mov_b32_e32 v28, v2
	v_mov_b32_e32 v29, v2
	v_mov_b32_e32 v30, v2
	v_mov_b32_e32 v31, v2
	v_mov_b32_e32 v32, v2
	v_mov_b32_e32 v33, v2
	v_mov_b32_e32 v42, v2
	v_mov_b32_e32 v43, v2
	v_mov_b32_e32 v44, v2
	v_mov_b32_e32 v45, v2
	v_mov_b32_e32 v46, v2
	v_mov_b32_e32 v47, v2
	v_mov_b32_e32 v48, v2
	v_mov_b32_e32 v49, v2
	v_mov_b32_e32 v18, v2
	v_mov_b32_e32 v19, v2
	v_mov_b32_e32 v20, v2
	v_mov_b32_e32 v21, v2
	v_mov_b32_e32 v22, v2
	v_mov_b32_e32 v23, v2
	v_mov_b32_e32 v24, v2
	v_mov_b32_e32 v25, v2
	v_mov_b32_e32 v34, v2
	v_mov_b32_e32 v35, v2
	v_mov_b32_e32 v36, v2
	v_mov_b32_e32 v37, v2
	v_mov_b32_e32 v38, v2
	v_mov_b32_e32 v39, v2
	v_mov_b32_e32 v40, v2
	v_mov_b32_e32 v41, v2
	v_mov_b32_e32 v50, v2
	v_mov_b32_e32 v51, v2
	v_mov_b32_e32 v52, v2
	v_mov_b32_e32 v53, v2
	v_mov_b32_e32 v54, v2
	v_mov_b32_e32 v55, v2
	v_mov_b32_e32 v56, v2
	v_mov_b32_e32 v57, v2
	v_mov_b32_e32 v58, v2
	v_mov_b32_e32 v59, v2
	v_mov_b32_e32 v60, v2
	v_mov_b32_e32 v61, v2
	v_mov_b32_e32 v62, v2
	v_mov_b32_e32 v63, v2
	v_mov_b32_e32 v64, v2
	v_mov_b32_e32 v65, v2
	v_mov_b32_e32 v66, v2
	v_mov_b32_e32 v67, v2
	v_mov_b32_e32 v68, v2
	v_mov_b32_e32 v69, v2
	v_mov_b32_e32 v70, v2
	v_mov_b32_e32 v71, v2
	v_mov_b32_e32 v72, v2
	v_mov_b32_e32 v73, v2
	v_mov_b32_e32 v74, v2
	v_mov_b32_e32 v75, v2
	v_mov_b32_e32 v76, v2
	v_mov_b32_e32 v77, v2
	v_mov_b32_e32 v78, v2
	v_mov_b32_e32 v79, v2
	v_mov_b32_e32 v80, v2
	v_mov_b32_e32 v81, v2
	v_mov_b32_e32 v90, v2
	v_mov_b32_e32 v91, v2
	v_mov_b32_e32 v92, v2
	v_mov_b32_e32 v93, v2
	v_mov_b32_e32 v94, v2
	v_mov_b32_e32 v95, v2
	v_mov_b32_e32 v96, v2
	v_mov_b32_e32 v97, v2
	v_mov_b32_e32 v106, v2
	v_mov_b32_e32 v107, v2
	v_mov_b32_e32 v108, v2
	v_mov_b32_e32 v109, v2
	v_mov_b32_e32 v110, v2
	v_mov_b32_e32 v111, v2
	v_mov_b32_e32 v112, v2
	v_mov_b32_e32 v113, v2
	v_mov_b32_e32 v82, v2
	v_mov_b32_e32 v83, v2
	v_mov_b32_e32 v84, v2
	v_mov_b32_e32 v85, v2
	v_mov_b32_e32 v86, v2
	v_mov_b32_e32 v87, v2
	v_mov_b32_e32 v88, v2
	v_mov_b32_e32 v89, v2
	v_mov_b32_e32 v98, v2
	v_mov_b32_e32 v99, v2
	v_mov_b32_e32 v100, v2
	v_mov_b32_e32 v101, v2
	v_mov_b32_e32 v102, v2
	v_mov_b32_e32 v103, v2
	v_mov_b32_e32 v104, v2
	v_mov_b32_e32 v105, v2
	v_mov_b32_e32 v114, v2
	v_mov_b32_e32 v115, v2
	v_mov_b32_e32 v116, v2
	v_mov_b32_e32 v117, v2
	v_mov_b32_e32 v118, v2
	v_mov_b32_e32 v119, v2
	v_mov_b32_e32 v120, v2
	v_mov_b32_e32 v121, v2
	v_mov_b32_e32 v122, v2
	v_mov_b32_e32 v123, v2
	v_mov_b32_e32 v124, v2
	v_mov_b32_e32 v125, v2
	v_mov_b32_e32 v126, v2
	v_mov_b32_e32 v127, v2
	v_mov_b32_e32 v128, v2
	v_mov_b32_e32 v129, v2
	v_add_u32_e32 v152, 0x10000, v139
	ds_read_b128 v[144:147], v152
	ds_read_b128 v[148:151], v152 offset:1024
	ds_read_b128 v[156:159], v152 offset:2048
	ds_read_b128 v[160:163], v152 offset:3072
.LBB0_526:
	s_add_u32 s20, s18, 0xfff80080
	s_addc_u32 s21, s19, -1
	s_add_i32 s56, 0, 0x10000
	s_cmp_eq_u32 s55, 28
	s_cselect_b32 s23, s39, s21
	s_cselect_b32 s22, s51, s20
	s_cselect_b32 s21, s31, s54
	s_cselect_b32 s20, s52, s53
	v_lshl_add_u64 v[152:153], s[18:19], 0, v[140:141]
	s_add_i32 m0, s29, 0xc000
	ds_read_b128 v[164:167], v154
	ds_read_b128 v[168:171], v154 offset:1024
	ds_read_b128 v[172:175], v154 offset:2048
	ds_read_b128 v[176:179], v154 offset:3072
	ds_read_b128 v[192:195], v154 offset:4096
	ds_read_b128 v[196:199], v154 offset:5120
	ds_read_b128 v[200:203], v154 offset:6144
	ds_read_b128 v[204:207], v154 offset:7168
	global_load_lds_dwordx4 v[152:153], off
	v_lshl_add_u64 v[152:153], s[18:19], 0, v[142:143]
	s_add_i32 m0, s29, 0xe000
	s_nop 0
	global_load_lds_dwordx4 v[152:153], off
	s_waitcnt lgkmcnt(8)
	s_barrier
	s_waitcnt lgkmcnt(0)
	s_setprio 1
	s_waitcnt lgkmcnt(0)
	v_mfma_f32_16x16x32_bf16 v[126:129], v[144:147], v[164:167], v[126:129]
	v_mfma_f32_16x16x32_bf16 v[122:125], v[156:159], v[164:167], v[122:125]
	v_mfma_f32_16x16x32_bf16 v[118:121], v[144:147], v[172:175], v[118:121]
	v_mfma_f32_16x16x32_bf16 v[114:117], v[156:159], v[172:175], v[114:117]
	v_mfma_f32_16x16x32_bf16 v[102:105], v[144:147], v[192:195], v[102:105]
	v_mfma_f32_16x16x32_bf16 v[98:101], v[156:159], v[192:195], v[98:101]
	v_mfma_f32_16x16x32_bf16 v[86:89], v[144:147], v[200:203], v[86:89]
	v_mfma_f32_16x16x32_bf16 v[82:85], v[156:159], v[200:203], v[82:85]
	v_mfma_f32_16x16x32_bf16 v[126:129], v[148:151], v[168:171], v[126:129]
	v_mfma_f32_16x16x32_bf16 v[122:125], v[160:163], v[168:171], v[122:125]
	v_mfma_f32_16x16x32_bf16 v[118:121], v[148:151], v[176:179], v[118:121]
	v_mfma_f32_16x16x32_bf16 v[114:117], v[160:163], v[176:179], v[114:117]
	v_mfma_f32_16x16x32_bf16 v[102:105], v[148:151], v[196:199], v[102:105]
	v_mfma_f32_16x16x32_bf16 v[98:101], v[160:163], v[196:199], v[98:101]
	v_mfma_f32_16x16x32_bf16 v[86:89], v[148:151], v[204:207], v[86:89]
	v_mfma_f32_16x16x32_bf16 v[82:85], v[160:163], v[204:207], v[82:85]
	s_setprio 0
	s_barrier
	s_add_i32 s58, 0, 0x14000
	v_add_u32_e32 v152, s58, v139
	s_add_i32 s56, s56, s28
	ds_read_b128 v[208:211], v152
	ds_read_b128 v[224:227], v152 offset:1024
	ds_read_b128 v[228:231], v152 offset:2048
	ds_read_b128 v[232:235], v152 offset:3072
	v_lshl_add_u64 v[152:153], s[20:21], 0, v[134:135]
	s_mov_b32 m0, s56
	v_lshl_add_u64 v[212:213], s[20:21], 0, v[130:131]
	global_load_lds_dwordx4 v[152:153], off
	s_add_i32 m0, s56, 0x2000
	s_nop 0
	global_load_lds_dwordx4 v[212:213], off
	s_barrier
	s_waitcnt lgkmcnt(0)
	s_setprio 1
	s_waitcnt lgkmcnt(0)
	v_mfma_f32_16x16x32_bf16 v[110:113], v[208:211], v[164:167], v[110:113]
	v_mfma_f32_16x16x32_bf16 v[106:109], v[228:231], v[164:167], v[106:109]
	v_mfma_f32_16x16x32_bf16 v[94:97], v[208:211], v[172:175], v[94:97]
	v_mfma_f32_16x16x32_bf16 v[90:93], v[228:231], v[172:175], v[90:93]
	v_mfma_f32_16x16x32_bf16 v[78:81], v[208:211], v[192:195], v[78:81]
	v_mfma_f32_16x16x32_bf16 v[74:77], v[228:231], v[192:195], v[74:77]
	v_mfma_f32_16x16x32_bf16 v[70:73], v[208:211], v[200:203], v[70:73]
	v_mfma_f32_16x16x32_bf16 v[66:69], v[228:231], v[200:203], v[66:69]
	v_mfma_f32_16x16x32_bf16 v[110:113], v[224:227], v[168:171], v[110:113]
	v_mfma_f32_16x16x32_bf16 v[106:109], v[232:235], v[168:171], v[106:109]
	v_mfma_f32_16x16x32_bf16 v[94:97], v[224:227], v[176:179], v[94:97]
	v_mfma_f32_16x16x32_bf16 v[90:93], v[232:235], v[176:179], v[90:93]
	v_mfma_f32_16x16x32_bf16 v[78:81], v[224:227], v[196:199], v[78:81]
	v_mfma_f32_16x16x32_bf16 v[74:77], v[232:235], v[196:199], v[74:77]
	v_mfma_f32_16x16x32_bf16 v[70:73], v[224:227], v[204:207], v[70:73]
	v_mfma_f32_16x16x32_bf16 v[66:69], v[232:235], v[204:207], v[66:69]
	s_setprio 0
	s_mov_b32 m0, s29
	v_lshl_add_u64 v[236:237], s[22:23], 0, v[136:137]
	s_barrier
	ds_read_b128 v[164:167], v154 offset:16384
	ds_read_b128 v[168:171], v154 offset:17408
	ds_read_b128 v[172:175], v154 offset:18432
	ds_read_b128 v[176:179], v154 offset:19456
	ds_read_b128 v[192:195], v154 offset:20480
	ds_read_b128 v[196:199], v154 offset:21504
	ds_read_b128 v[200:203], v154 offset:22528
	ds_read_b128 v[204:207], v154 offset:23552
	global_load_lds_dwordx4 v[236:237], off
	v_lshl_add_u64 v[238:239], s[22:23], 0, v[132:133]
	s_mov_b32 m0, s44
	s_nop 0
	global_load_lds_dwordx4 v[238:239], off
	s_waitcnt vmcnt(10)
	s_barrier
	s_waitcnt lgkmcnt(0)
	s_setprio 1
	s_waitcnt lgkmcnt(0)
	v_mfma_f32_16x16x32_bf16 v[62:65], v[144:147], v[164:167], v[62:65]
	v_mfma_f32_16x16x32_bf16 v[58:61], v[156:159], v[164:167], v[58:61]
	v_mfma_f32_16x16x32_bf16 v[54:57], v[144:147], v[172:175], v[54:57]
	v_mfma_f32_16x16x32_bf16 v[50:53], v[156:159], v[172:175], v[50:53]
	v_mfma_f32_16x16x32_bf16 v[38:41], v[144:147], v[192:195], v[38:41]
	v_mfma_f32_16x16x32_bf16 v[34:37], v[156:159], v[192:195], v[34:37]
	v_mfma_f32_16x16x32_bf16 v[22:25], v[144:147], v[200:203], v[22:25]
	v_mfma_f32_16x16x32_bf16 v[18:21], v[156:159], v[200:203], v[18:21]
	v_mfma_f32_16x16x32_bf16 v[62:65], v[148:151], v[168:171], v[62:65]
	v_mfma_f32_16x16x32_bf16 v[58:61], v[160:163], v[168:171], v[58:61]
	v_mfma_f32_16x16x32_bf16 v[54:57], v[148:151], v[176:179], v[54:57]
	v_mfma_f32_16x16x32_bf16 v[50:53], v[160:163], v[176:179], v[50:53]
	v_mfma_f32_16x16x32_bf16 v[38:41], v[148:151], v[196:199], v[38:41]
	v_mfma_f32_16x16x32_bf16 v[34:37], v[160:163], v[196:199], v[34:37]
	v_mfma_f32_16x16x32_bf16 v[22:25], v[148:151], v[204:207], v[22:25]
	v_mfma_f32_16x16x32_bf16 v[18:21], v[160:163], v[204:207], v[18:21]
	s_setprio 0
	s_barrier
	s_add_u32 s56, s20, 0x80000
	s_addc_u32 s57, s21, 0
	s_add_i32 s58, s58, s28
	v_lshl_add_u64 v[144:145], s[56:57], 0, v[134:135]
	s_mov_b32 m0, s58
	s_nop 0
	global_load_lds_dwordx4 v[144:145], off
	v_lshl_add_u64 v[144:145], s[56:57], 0, v[130:131]
	s_add_i32 m0, s58, 0x2000
	s_nop 0
	global_load_lds_dwordx4 v[144:145], off
	v_add_u32_e32 v155, 0x18000, v139
	ds_read_b128 v[144:147], v155
	ds_read_b128 v[148:151], v155 offset:1024
	ds_read_b128 v[156:159], v155 offset:2048
	ds_read_b128 v[160:163], v155 offset:3072
	s_waitcnt vmcnt(6)
	s_barrier
	s_setprio 1
	v_mfma_f32_16x16x32_bf16 v[46:49], v[208:211], v[164:167], v[46:49]
	v_mfma_f32_16x16x32_bf16 v[42:45], v[228:231], v[164:167], v[42:45]
	v_mfma_f32_16x16x32_bf16 v[30:33], v[208:211], v[172:175], v[30:33]
	v_mfma_f32_16x16x32_bf16 v[26:29], v[228:231], v[172:175], v[26:29]
	v_mfma_f32_16x16x32_bf16 v[14:17], v[208:211], v[192:195], v[14:17]
	v_mfma_f32_16x16x32_bf16 v[10:13], v[228:231], v[192:195], v[10:13]
	v_mfma_f32_16x16x32_bf16 v[6:9], v[208:211], v[200:203], v[6:9]
	v_mfma_f32_16x16x32_bf16 v[2:5], v[228:231], v[200:203], v[2:5]
	v_mfma_f32_16x16x32_bf16 v[46:49], v[224:227], v[168:171], v[46:49]
	v_mfma_f32_16x16x32_bf16 v[42:45], v[232:235], v[168:171], v[42:45]
	v_mfma_f32_16x16x32_bf16 v[30:33], v[224:227], v[176:179], v[30:33]
	v_mfma_f32_16x16x32_bf16 v[26:29], v[232:235], v[176:179], v[26:29]
	v_mfma_f32_16x16x32_bf16 v[14:17], v[224:227], v[196:199], v[14:17]
	v_mfma_f32_16x16x32_bf16 v[10:13], v[232:235], v[196:199], v[10:13]
	v_mfma_f32_16x16x32_bf16 v[6:9], v[224:227], v[204:207], v[6:9]
	v_mfma_f32_16x16x32_bf16 v[2:5], v[232:235], v[204:207], v[2:5]
	s_setprio 0
	s_add_i32 s56, 0, 0x18000
	s_barrier
	s_add_u32 s22, s22, 0x80000
	s_addc_u32 s23, s23, 0
	s_mov_b32 m0, s45
	v_lshl_add_u64 v[208:209], s[22:23], 0, v[136:137]
	ds_read_b128 v[164:167], v154 offset:32768
	ds_read_b128 v[168:171], v154 offset:33792
	ds_read_b128 v[172:175], v154 offset:34816
	ds_read_b128 v[176:179], v154 offset:35840
	ds_read_b128 v[192:195], v154 offset:36864
	ds_read_b128 v[196:199], v154 offset:37888
	ds_read_b128 v[200:203], v154 offset:38912
	ds_read_b128 v[204:207], v154 offset:39936
	global_load_lds_dwordx4 v[208:209], off
	v_lshl_add_u64 v[208:209], s[22:23], 0, v[132:133]
	s_mov_b32 m0, s46
	s_nop 0
	global_load_lds_dwordx4 v[208:209], off
	s_waitcnt lgkmcnt(8)
	s_barrier
	s_waitcnt lgkmcnt(0)
	s_setprio 1
	s_waitcnt lgkmcnt(0)
	v_mfma_f32_16x16x32_bf16 v[126:129], v[144:147], v[164:167], v[126:129]
	v_mfma_f32_16x16x32_bf16 v[122:125], v[156:159], v[164:167], v[122:125]
	v_mfma_f32_16x16x32_bf16 v[118:121], v[144:147], v[172:175], v[118:121]
	v_mfma_f32_16x16x32_bf16 v[114:117], v[156:159], v[172:175], v[114:117]
	v_mfma_f32_16x16x32_bf16 v[102:105], v[144:147], v[192:195], v[102:105]
	v_mfma_f32_16x16x32_bf16 v[98:101], v[156:159], v[192:195], v[98:101]
	v_mfma_f32_16x16x32_bf16 v[86:89], v[144:147], v[200:203], v[86:89]
	v_mfma_f32_16x16x32_bf16 v[82:85], v[156:159], v[200:203], v[82:85]
	v_mfma_f32_16x16x32_bf16 v[126:129], v[148:151], v[168:171], v[126:129]
	v_mfma_f32_16x16x32_bf16 v[122:125], v[160:163], v[168:171], v[122:125]
	v_mfma_f32_16x16x32_bf16 v[118:121], v[148:151], v[176:179], v[118:121]
	v_mfma_f32_16x16x32_bf16 v[114:117], v[160:163], v[176:179], v[114:117]
	v_mfma_f32_16x16x32_bf16 v[102:105], v[148:151], v[196:199], v[102:105]
	v_mfma_f32_16x16x32_bf16 v[98:101], v[160:163], v[196:199], v[98:101]
	v_mfma_f32_16x16x32_bf16 v[86:89], v[148:151], v[204:207], v[86:89]
	v_mfma_f32_16x16x32_bf16 v[82:85], v[160:163], v[204:207], v[82:85]
	s_setprio 0
	s_barrier
	s_add_i32 s22, 0, 0x1c000
	s_add_i32 s23, s56, s28
	v_add_u32_e32 v155, s22, v139
	v_lshl_add_u64 v[152:153], v[152:153], 0, s[78:79]
	s_mov_b32 m0, s23
	ds_read_b128 v[208:211], v155
	ds_read_b128 v[224:227], v155 offset:1024
	ds_read_b128 v[228:231], v155 offset:2048
	ds_read_b128 v[232:235], v155 offset:3072
	global_load_lds_dwordx4 v[152:153], off
	v_lshl_add_u64 v[152:153], v[212:213], 0, s[78:79]
	s_add_i32 m0, s23, 0x2000
	s_nop 0
	global_load_lds_dwordx4 v[152:153], off
	s_barrier
	s_waitcnt lgkmcnt(0)
	s_setprio 1
	s_waitcnt lgkmcnt(0)
	v_mfma_f32_16x16x32_bf16 v[110:113], v[208:211], v[164:167], v[110:113]
	v_mfma_f32_16x16x32_bf16 v[106:109], v[228:231], v[164:167], v[106:109]
	v_mfma_f32_16x16x32_bf16 v[94:97], v[208:211], v[172:175], v[94:97]
	v_mfma_f32_16x16x32_bf16 v[90:93], v[228:231], v[172:175], v[90:93]
	v_mfma_f32_16x16x32_bf16 v[78:81], v[208:211], v[192:195], v[78:81]
	v_mfma_f32_16x16x32_bf16 v[74:77], v[228:231], v[192:195], v[74:77]
	v_mfma_f32_16x16x32_bf16 v[70:73], v[208:211], v[200:203], v[70:73]
	v_mfma_f32_16x16x32_bf16 v[66:69], v[228:231], v[200:203], v[66:69]
	v_mfma_f32_16x16x32_bf16 v[110:113], v[224:227], v[168:171], v[110:113]
	v_mfma_f32_16x16x32_bf16 v[106:109], v[232:235], v[168:171], v[106:109]
	v_mfma_f32_16x16x32_bf16 v[94:97], v[224:227], v[176:179], v[94:97]
	v_mfma_f32_16x16x32_bf16 v[90:93], v[232:235], v[176:179], v[90:93]
	v_mfma_f32_16x16x32_bf16 v[78:81], v[224:227], v[196:199], v[78:81]
	v_mfma_f32_16x16x32_bf16 v[74:77], v[232:235], v[196:199], v[74:77]
	v_mfma_f32_16x16x32_bf16 v[70:73], v[224:227], v[204:207], v[70:73]
	v_mfma_f32_16x16x32_bf16 v[66:69], v[232:235], v[204:207], v[66:69]
	s_setprio 0
	s_mov_b32 m0, s47
	v_lshl_add_u64 v[152:153], v[236:237], 0, s[78:79]
	s_barrier
	ds_read_b128 v[164:167], v154 offset:49152
	ds_read_b128 v[168:171], v154 offset:50176
	ds_read_b128 v[172:175], v154 offset:51200
	ds_read_b128 v[176:179], v154 offset:52224
	ds_read_b128 v[192:195], v154 offset:53248
	ds_read_b128 v[196:199], v154 offset:54272
	ds_read_b128 v[200:203], v154 offset:55296
	ds_read_b128 v[204:207], v154 offset:56320
	global_load_lds_dwordx4 v[152:153], off
	v_lshl_add_u64 v[152:153], v[238:239], 0, s[78:79]
	s_mov_b32 m0, s48
	s_nop 0
	global_load_lds_dwordx4 v[152:153], off
	s_waitcnt vmcnt(10)
	s_barrier
	s_waitcnt lgkmcnt(0)
	s_setprio 1
	s_waitcnt lgkmcnt(0)
	v_mfma_f32_16x16x32_bf16 v[62:65], v[144:147], v[164:167], v[62:65]
	v_mfma_f32_16x16x32_bf16 v[58:61], v[156:159], v[164:167], v[58:61]
	v_mfma_f32_16x16x32_bf16 v[54:57], v[144:147], v[172:175], v[54:57]
	v_mfma_f32_16x16x32_bf16 v[50:53], v[156:159], v[172:175], v[50:53]
	v_mfma_f32_16x16x32_bf16 v[38:41], v[144:147], v[192:195], v[38:41]
	v_mfma_f32_16x16x32_bf16 v[34:37], v[156:159], v[192:195], v[34:37]
	v_mfma_f32_16x16x32_bf16 v[22:25], v[144:147], v[200:203], v[22:25]
	v_mfma_f32_16x16x32_bf16 v[18:21], v[156:159], v[200:203], v[18:21]
	v_mfma_f32_16x16x32_bf16 v[62:65], v[148:151], v[168:171], v[62:65]
	v_mfma_f32_16x16x32_bf16 v[58:61], v[160:163], v[168:171], v[58:61]
	v_mfma_f32_16x16x32_bf16 v[54:57], v[148:151], v[176:179], v[54:57]
	v_mfma_f32_16x16x32_bf16 v[50:53], v[160:163], v[176:179], v[50:53]
	v_mfma_f32_16x16x32_bf16 v[38:41], v[148:151], v[196:199], v[38:41]
	v_mfma_f32_16x16x32_bf16 v[34:37], v[160:163], v[196:199], v[34:37]
	v_mfma_f32_16x16x32_bf16 v[22:25], v[148:151], v[204:207], v[22:25]
	v_mfma_f32_16x16x32_bf16 v[18:21], v[160:163], v[204:207], v[18:21]
	s_setprio 0
	s_barrier
	s_add_u32 s20, s20, 0x80080
	s_addc_u32 s21, s21, 0
	s_add_i32 s22, s22, s28
	v_lshl_add_u64 v[144:145], s[20:21], 0, v[134:135]
	s_mov_b32 m0, s22
	s_nop 0
	global_load_lds_dwordx4 v[144:145], off
	v_lshl_add_u64 v[144:145], s[20:21], 0, v[130:131]
	s_add_i32 m0, s22, 0x2000
	s_nop 0
	global_load_lds_dwordx4 v[144:145], off
	v_add_u32_e32 v152, 0x10000, v139
	ds_read_b128 v[144:147], v152
	ds_read_b128 v[148:151], v152 offset:1024
	ds_read_b128 v[156:159], v152 offset:2048
	ds_read_b128 v[160:163], v152 offset:3072
	s_waitcnt vmcnt(6)
	s_barrier
	s_setprio 1
	v_mfma_f32_16x16x32_bf16 v[46:49], v[208:211], v[164:167], v[46:49]
	v_mfma_f32_16x16x32_bf16 v[42:45], v[228:231], v[164:167], v[42:45]
	v_mfma_f32_16x16x32_bf16 v[30:33], v[208:211], v[172:175], v[30:33]
	v_mfma_f32_16x16x32_bf16 v[26:29], v[228:231], v[172:175], v[26:29]
	v_mfma_f32_16x16x32_bf16 v[14:17], v[208:211], v[192:195], v[14:17]
	v_mfma_f32_16x16x32_bf16 v[10:13], v[228:231], v[192:195], v[10:13]
	v_mfma_f32_16x16x32_bf16 v[6:9], v[208:211], v[200:203], v[6:9]
	v_mfma_f32_16x16x32_bf16 v[2:5], v[228:231], v[200:203], v[2:5]
	v_mfma_f32_16x16x32_bf16 v[46:49], v[224:227], v[168:171], v[46:49]
	v_mfma_f32_16x16x32_bf16 v[42:45], v[232:235], v[168:171], v[42:45]
	v_mfma_f32_16x16x32_bf16 v[30:33], v[224:227], v[176:179], v[30:33]
	v_mfma_f32_16x16x32_bf16 v[26:29], v[232:235], v[176:179], v[26:29]
	v_mfma_f32_16x16x32_bf16 v[14:17], v[224:227], v[196:199], v[14:17]
	v_mfma_f32_16x16x32_bf16 v[10:13], v[232:235], v[196:199], v[10:13]
	v_mfma_f32_16x16x32_bf16 v[6:9], v[224:227], v[204:207], v[6:9]
	v_mfma_f32_16x16x32_bf16 v[2:5], v[232:235], v[204:207], v[2:5]
	s_setprio 0
	s_add_i32 s55, s55, 2
	s_add_u32 s18, s18, 0x100
	s_addc_u32 s19, s19, 0
	s_add_u32 s53, s53, 0x100
	s_addc_u32 s54, s54, 0
	s_cmp_gt_u32 s55, 29
	s_barrier
	s_cbranch_scc0 .LBB0_526
	s_waitcnt lgkmcnt(0)
	v_lshl_add_u32 v152, s36, 8, v1
	v_or_b32_e32 v150, 16, v152
	v_or_b32_e32 v148, 32, v152
	v_or_b32_e32 v146, 48, v152
	s_mov_b64 s[18:19], -1
	s_cmp_lt_i32 s50, 8
	v_ashrrev_i32_e32 v153, 31, v152
	v_lshlrev_b32_e32 v144, 1, v138
	v_ashrrev_i32_e32 v151, 31, v150
	v_ashrrev_i32_e32 v149, 31, v148
	v_ashrrev_i32_e32 v147, 31, v146
	s_cbranch_scc1 .LBB0_529
	s_lshl_b32 s18, s50, 7
	s_add_i32 s36, s18, 0xfffffc00
	v_lshlrev_b64 v[156:157], 12, v[152:153]
	v_lshl_add_u64 v[156:157], s[72:73], 0, v[156:157]
	s_lshl_b64 s[18:19], s[36:37], 1
	v_lshl_add_u64 v[156:157], v[156:157], 0, s[18:19]
	v_mov_b32_e32 v145, v0
	v_lshl_add_u64 v[160:161], v[156:157], 0, v[144:145]
	v_pk_mul_f32 v[158:159], v[128:129], v[112:113]
	v_pk_mul_f32 v[156:157], v[126:127], v[110:111]
	v_pk_mul_f32 v[162:163], v[124:125], v[108:109]
	v_pk_mul_f32 v[164:165], v[122:123], v[106:107]
	v_cvt_pk_bf16_f32 v156, v156, v157
	v_cvt_pk_bf16_f32 v157, v158, v159
	v_cvt_pk_bf16_f32 v158, v164, v165
	v_cvt_pk_bf16_f32 v159, v162, v163
	global_store_dwordx4 v[160:161], v[156:159], off
	v_pk_mul_f32 v[164:165], v[116:117], v[92:93]
	v_pk_mul_f32 v[166:167], v[114:115], v[90:91]
	v_lshlrev_b64 v[156:157], 12, v[150:151]
	v_lshl_add_u64 v[156:157], s[72:73], 0, v[156:157]
	v_lshl_add_u64 v[156:157], v[156:157], 0, s[18:19]
	v_lshl_add_u64 v[162:163], v[156:157], 0, v[144:145]
	v_pk_mul_f32 v[158:159], v[120:121], v[96:97]
	v_pk_mul_f32 v[156:157], v[118:119], v[94:95]
	s_nop 0
	v_cvt_pk_bf16_f32 v156, v156, v157
	v_cvt_pk_bf16_f32 v157, v158, v159
	v_cvt_pk_bf16_f32 v158, v166, v167
	v_cvt_pk_bf16_f32 v159, v164, v165
	global_store_dwordx4 v[162:163], v[156:159], off
	v_pk_mul_f32 v[164:165], v[100:101], v[76:77]
	v_pk_mul_f32 v[166:167], v[98:99], v[74:75]
	v_lshlrev_b64 v[156:157], 12, v[148:149]
	v_lshl_add_u64 v[156:157], s[72:73], 0, v[156:157]
	v_lshl_add_u64 v[156:157], v[156:157], 0, s[18:19]
	v_lshl_add_u64 v[162:163], v[156:157], 0, v[144:145]
	v_pk_mul_f32 v[158:159], v[104:105], v[80:81]
	v_pk_mul_f32 v[156:157], v[102:103], v[78:79]
	s_nop 0
	v_cvt_pk_bf16_f32 v156, v156, v157
	v_cvt_pk_bf16_f32 v157, v158, v159
	v_cvt_pk_bf16_f32 v158, v166, v167
	v_cvt_pk_bf16_f32 v159, v164, v165
	global_store_dwordx4 v[162:163], v[156:159], off
	v_pk_mul_f32 v[164:165], v[84:85], v[68:69]
	v_pk_mul_f32 v[166:167], v[82:83], v[66:67]
	v_lshlrev_b64 v[156:157], 12, v[146:147]
	v_lshl_add_u64 v[156:157], s[72:73], 0, v[156:157]
	v_lshl_add_u64 v[156:157], v[156:157], 0, s[18:19]
	v_lshl_add_u64 v[162:163], v[156:157], 0, v[144:145]
	v_pk_mul_f32 v[158:159], v[88:89], v[72:73]
	v_pk_mul_f32 v[156:157], v[86:87], v[70:71]
	s_mov_b32 s18, 0x80000
	v_cvt_pk_bf16_f32 v156, v156, v157
	v_cvt_pk_bf16_f32 v157, v158, v159
	v_cvt_pk_bf16_f32 v158, v166, v167
	v_cvt_pk_bf16_f32 v159, v164, v165
	global_store_dwordx4 v[162:163], v[156:159], off
	v_pk_mul_f32 v[162:163], v[60:61], v[44:45]
	v_pk_mul_f32 v[164:165], v[58:59], v[42:43]
	v_pk_mul_f32 v[158:159], v[64:65], v[48:49]
	v_pk_mul_f32 v[156:157], v[62:63], v[46:47]
	s_nop 0
	v_cvt_pk_bf16_f32 v156, v156, v157
	v_cvt_pk_bf16_f32 v157, v158, v159
	v_cvt_pk_bf16_f32 v159, v162, v163
	v_add_co_u32_e32 v162, vcc, s18, v160
	v_cvt_pk_bf16_f32 v158, v164, v165
	s_nop 0
	v_addc_co_u32_e32 v163, vcc, 0, v161, vcc
	global_store_dwordx4 v[162:163], v[156:159], off
	v_pk_mul_f32 v[162:163], v[52:53], v[28:29]
	s_mov_b32 s18, 0x90000
	v_pk_mul_f32 v[158:159], v[56:57], v[32:33]
	v_pk_mul_f32 v[156:157], v[54:55], v[30:31]
	v_pk_mul_f32 v[164:165], v[50:51], v[26:27]
	v_cvt_pk_bf16_f32 v156, v156, v157
	v_cvt_pk_bf16_f32 v157, v158, v159
	v_cvt_pk_bf16_f32 v159, v162, v163
	v_add_co_u32_e32 v162, vcc, s18, v160
	v_cvt_pk_bf16_f32 v158, v164, v165
	s_nop 0
	v_addc_co_u32_e32 v163, vcc, 0, v161, vcc
	global_store_dwordx4 v[162:163], v[156:159], off
	v_pk_mul_f32 v[162:163], v[36:37], v[12:13]
	s_mov_b32 s18, 0xa0000
	v_pk_mul_f32 v[158:159], v[40:41], v[16:17]
	v_pk_mul_f32 v[156:157], v[38:39], v[14:15]
	v_pk_mul_f32 v[164:165], v[34:35], v[10:11]
	v_cvt_pk_bf16_f32 v156, v156, v157
	v_cvt_pk_bf16_f32 v157, v158, v159
	v_cvt_pk_bf16_f32 v159, v162, v163
	v_add_co_u32_e32 v162, vcc, s18, v160
	v_cvt_pk_bf16_f32 v158, v164, v165
	s_nop 0
	v_addc_co_u32_e32 v163, vcc, 0, v161, vcc
	global_store_dwordx4 v[162:163], v[156:159], off
	v_pk_mul_f32 v[162:163], v[20:21], v[4:5]
	v_pk_mul_f32 v[164:165], v[18:19], v[2:3]
	v_pk_mul_f32 v[158:159], v[24:25], v[8:9]
	v_pk_mul_f32 v[156:157], v[22:23], v[6:7]
	v_add_co_u32_e32 v160, vcc, 0xb0000, v160
	v_cvt_pk_bf16_f32 v156, v156, v157
	v_cvt_pk_bf16_f32 v157, v158, v159
	v_cvt_pk_bf16_f32 v158, v164, v165
	v_cvt_pk_bf16_f32 v159, v162, v163
	v_addc_co_u32_e32 v161, vcc, 0, v161, vcc
	s_mov_b64 s[18:19], 0
	global_store_dwordx4 v[160:161], v[156:159], off

.LBB0_648:
	s_add_u32 s50, s18, 0x100
	s_addc_u32 s51, s19, 0
	s_ashr_i32 s83, s82, 31
	s_lshl_b64 s[20:21], s[82:83], 20
	s_add_u32 s20, s30, s20
	s_addc_u32 s21, s31, s21
	s_and_b64 s[22:23], s[42:43], exec
	s_cselect_b32 s52, s21, s39
	s_cselect_b32 s53, s20, s38
	s_ashr_i32 s81, s80, 31
	s_lshl_b64 s[22:23], s[80:81], 20
	s_add_u32 s90, s26, s22
	s_addc_u32 s91, s27, s23
	s_and_b64 s[22:23], s[42:43], exec
	s_cselect_b32 s54, s91, s19
	s_cselect_b32 s55, s90, s18
	s_add_u32 s18, s38, 0x80080
	s_addc_u32 s19, s39, 0
	v_lshl_add_u64 v[142:143], s[18:19], 0, v[138:139]
	v_lshl_add_u64 v[144:145], s[18:19], 0, v[140:141]
	s_mov_b32 s56, -2
	s_mov_b64 vcc, 0
	v_add_u32_e32 v149, 0x10000, v147
	ds_read_b128 v[150:153], v149
	ds_read_b128 v[154:157], v149 offset:1024
	ds_read_b128 v[158:161], v149 offset:2048
	ds_read_b128 v[166:169], v149 offset:3072
.LBB0_649:
	s_add_u32 s18, s38, vcc_lo
	s_addc_u32 s19, s39, vcc_hi
	s_add_u32 s18, s18, 0x100
	s_addc_u32 s19, s19, 0
	s_add_u32 s57, s50, vcc_lo
	s_addc_u32 s58, s51, vcc_hi
	s_add_i32 s59, 0, 0x10000
	s_cmpk_eq_i32 vcc_lo, 0xf00
	s_cselect_b32 s23, s52, s19
	s_cselect_b32 s22, s53, s18
	s_cselect_b32 s19, s54, s58
	s_cselect_b32 s18, s55, s57
	v_lshl_add_u64 v[162:163], v[142:143], 0, vcc
	s_add_i32 m0, s28, 0xc000
	ds_read_b128 v[170:173], v148
	ds_read_b128 v[174:177], v148 offset:1024
	ds_read_b128 v[192:195], v148 offset:2048
	ds_read_b128 v[196:199], v148 offset:3072
	ds_read_b128 v[200:203], v148 offset:4096
	ds_read_b128 v[204:207], v148 offset:5120
	ds_read_b128 v[208:211], v148 offset:6144
	ds_read_b128 v[224:227], v148 offset:7168
	global_load_lds_dwordx4 v[162:163], off
	v_lshl_add_u64 v[162:163], v[144:145], 0, vcc
	s_add_i32 m0, s28, 0xe000
	s_nop 0
	global_load_lds_dwordx4 v[162:163], off
	s_waitcnt lgkmcnt(8)
	s_barrier
	s_waitcnt lgkmcnt(0)
	s_setprio 1
	s_waitcnt lgkmcnt(0)
	v_mfma_f32_16x16x32_bf16 v[90:93], v[150:153], v[170:173], v[90:93]
	v_mfma_f32_16x16x32_bf16 v[94:97], v[158:161], v[170:173], v[94:97]
	v_mfma_f32_16x16x32_bf16 v[102:105], v[150:153], v[192:195], v[102:105]
	v_mfma_f32_16x16x32_bf16 v[106:109], v[158:161], v[192:195], v[106:109]
	v_mfma_f32_16x16x32_bf16 v[114:117], v[150:153], v[200:203], v[114:117]
	v_mfma_f32_16x16x32_bf16 v[118:121], v[158:161], v[200:203], v[118:121]
	v_mfma_f32_16x16x32_bf16 v[122:125], v[150:153], v[208:211], v[122:125]
	v_mfma_f32_16x16x32_bf16 v[126:129], v[158:161], v[208:211], v[126:129]
	v_mfma_f32_16x16x32_bf16 v[90:93], v[154:157], v[174:177], v[90:93]
	v_mfma_f32_16x16x32_bf16 v[94:97], v[166:169], v[174:177], v[94:97]
	v_mfma_f32_16x16x32_bf16 v[102:105], v[154:157], v[196:199], v[102:105]
	v_mfma_f32_16x16x32_bf16 v[106:109], v[166:169], v[196:199], v[106:109]
	v_mfma_f32_16x16x32_bf16 v[114:117], v[154:157], v[204:207], v[114:117]
	v_mfma_f32_16x16x32_bf16 v[118:121], v[166:169], v[204:207], v[118:121]
	v_mfma_f32_16x16x32_bf16 v[122:125], v[154:157], v[224:227], v[122:125]
	v_mfma_f32_16x16x32_bf16 v[126:129], v[166:169], v[224:227], v[126:129]
	s_setprio 0
	s_barrier
	s_add_i32 s57, 0, 0x14000
	s_add_i32 s58, s59, s85
	v_add_u32_e32 v149, s57, v147
	v_lshl_add_u64 v[162:163], s[18:19], 0, v[134:135]
	s_mov_b32 m0, s58
	ds_read_b128 v[228:231], v149
	ds_read_b128 v[232:235], v149 offset:1024
	ds_read_b128 v[236:239], v149 offset:2048
	ds_read_b128 v[240:243], v149 offset:3072
	global_load_lds_dwordx4 v[162:163], off
	v_lshl_add_u64 v[178:179], s[18:19], 0, v[130:131]
	s_add_i32 m0, s58, 0x2000
	s_nop 0
	global_load_lds_dwordx4 v[178:179], off
	s_barrier
	s_waitcnt lgkmcnt(0)
	s_setprio 1
	s_waitcnt lgkmcnt(0)
	v_mfma_f32_16x16x32_bf16 v[10:13], v[228:231], v[170:173], v[10:13]
	v_mfma_f32_16x16x32_bf16 v[14:17], v[236:239], v[170:173], v[14:17]
	v_mfma_f32_16x16x32_bf16 v[26:29], v[228:231], v[192:195], v[26:29]
	v_mfma_f32_16x16x32_bf16 v[38:41], v[236:239], v[192:195], v[38:41]
	v_mfma_f32_16x16x32_bf16 v[58:61], v[228:231], v[200:203], v[58:61]
	v_mfma_f32_16x16x32_bf16 v[62:65], v[236:239], v[200:203], v[62:65]
	v_mfma_f32_16x16x32_bf16 v[74:77], v[228:231], v[208:211], v[74:77]
	v_mfma_f32_16x16x32_bf16 v[78:81], v[236:239], v[208:211], v[78:81]
	v_mfma_f32_16x16x32_bf16 v[10:13], v[232:235], v[174:177], v[10:13]
	v_mfma_f32_16x16x32_bf16 v[14:17], v[240:243], v[174:177], v[14:17]
	v_mfma_f32_16x16x32_bf16 v[26:29], v[232:235], v[196:199], v[26:29]
	v_mfma_f32_16x16x32_bf16 v[38:41], v[240:243], v[196:199], v[38:41]
	v_mfma_f32_16x16x32_bf16 v[58:61], v[232:235], v[204:207], v[58:61]
	v_mfma_f32_16x16x32_bf16 v[62:65], v[240:243], v[204:207], v[62:65]
	v_mfma_f32_16x16x32_bf16 v[74:77], v[232:235], v[224:227], v[74:77]
	v_mfma_f32_16x16x32_bf16 v[78:81], v[240:243], v[224:227], v[78:81]
	s_setprio 0
	s_mov_b32 m0, s28
	v_lshl_add_u64 v[212:213], s[22:23], 0, v[136:137]
	s_barrier
	ds_read_b128 v[170:173], v148 offset:16384
	ds_read_b128 v[174:177], v148 offset:17408
	ds_read_b128 v[192:195], v148 offset:18432
	ds_read_b128 v[196:199], v148 offset:19456
	ds_read_b128 v[200:203], v148 offset:20480
	ds_read_b128 v[204:207], v148 offset:21504
	ds_read_b128 v[208:211], v148 offset:22528
	ds_read_b128 v[224:227], v148 offset:23552
	global_load_lds_dwordx4 v[212:213], off
	v_lshl_add_u64 v[244:245], s[22:23], 0, v[132:133]
	s_mov_b32 m0, s29
	s_nop 0
	global_load_lds_dwordx4 v[244:245], off
	s_waitcnt vmcnt(10)
	s_barrier
	s_waitcnt lgkmcnt(0)
	s_setprio 1
	s_waitcnt lgkmcnt(0)
	v_mfma_f32_16x16x32_bf16 v[110:113], v[150:153], v[170:173], v[110:113]
	v_mfma_f32_16x16x32_bf16 v[98:101], v[158:161], v[170:173], v[98:101]
	v_mfma_f32_16x16x32_bf16 v[82:85], v[150:153], v[192:195], v[82:85]
	v_mfma_f32_16x16x32_bf16 v[66:69], v[158:161], v[192:195], v[66:69]
	v_mfma_f32_16x16x32_bf16 v[50:53], v[150:153], v[200:203], v[50:53]
	v_mfma_f32_16x16x32_bf16 v[42:45], v[158:161], v[200:203], v[42:45]
	v_mfma_f32_16x16x32_bf16 v[30:33], v[150:153], v[208:211], v[30:33]
	v_mfma_f32_16x16x32_bf16 v[18:21], v[158:161], v[208:211], v[18:21]
	v_mfma_f32_16x16x32_bf16 v[110:113], v[154:157], v[174:177], v[110:113]
	v_mfma_f32_16x16x32_bf16 v[98:101], v[166:169], v[174:177], v[98:101]
	v_mfma_f32_16x16x32_bf16 v[82:85], v[154:157], v[196:199], v[82:85]
	v_mfma_f32_16x16x32_bf16 v[66:69], v[166:169], v[196:199], v[66:69]
	v_mfma_f32_16x16x32_bf16 v[50:53], v[154:157], v[204:207], v[50:53]
	v_mfma_f32_16x16x32_bf16 v[42:45], v[166:169], v[204:207], v[42:45]
	v_mfma_f32_16x16x32_bf16 v[30:33], v[154:157], v[224:227], v[30:33]
	v_mfma_f32_16x16x32_bf16 v[18:21], v[166:169], v[224:227], v[18:21]
	s_setprio 0
	s_barrier
	s_add_u32 s58, s18, 0x80000
	s_addc_u32 s59, s19, 0
	s_add_i32 s57, s57, s85
	v_lshl_add_u64 v[150:151], s[58:59], 0, v[134:135]
	s_mov_b32 m0, s57
	s_nop 0
	global_load_lds_dwordx4 v[150:151], off
	v_lshl_add_u64 v[150:151], s[58:59], 0, v[130:131]
	s_add_i32 m0, s57, 0x2000
	s_nop 0
	global_load_lds_dwordx4 v[150:151], off
	v_add_u32_e32 v149, 0x18000, v147
	ds_read_b128 v[150:153], v149
	ds_read_b128 v[154:157], v149 offset:1024
	ds_read_b128 v[158:161], v149 offset:2048
	ds_read_b128 v[166:169], v149 offset:3072
	s_waitcnt vmcnt(6)
	s_barrier
	s_setprio 1
	v_mfma_f32_16x16x32_bf16 v[86:89], v[228:231], v[170:173], v[86:89]
	v_mfma_f32_16x16x32_bf16 v[70:73], v[236:239], v[170:173], v[70:73]
	v_mfma_f32_16x16x32_bf16 v[54:57], v[228:231], v[192:195], v[54:57]
	v_mfma_f32_16x16x32_bf16 v[46:49], v[236:239], v[192:195], v[46:49]
	v_mfma_f32_16x16x32_bf16 v[34:37], v[228:231], v[200:203], v[34:37]
	v_mfma_f32_16x16x32_bf16 v[22:25], v[236:239], v[200:203], v[22:25]
	v_mfma_f32_16x16x32_bf16 v[6:9], v[228:231], v[208:211], v[6:9]
	v_mfma_f32_16x16x32_bf16 v[2:5], v[236:239], v[208:211], v[2:5]
	v_mfma_f32_16x16x32_bf16 v[86:89], v[232:235], v[174:177], v[86:89]
	v_mfma_f32_16x16x32_bf16 v[70:73], v[240:243], v[174:177], v[70:73]
	v_mfma_f32_16x16x32_bf16 v[54:57], v[232:235], v[196:199], v[54:57]
	v_mfma_f32_16x16x32_bf16 v[46:49], v[240:243], v[196:199], v[46:49]
	v_mfma_f32_16x16x32_bf16 v[34:37], v[232:235], v[204:207], v[34:37]
	v_mfma_f32_16x16x32_bf16 v[22:25], v[240:243], v[204:207], v[22:25]
	v_mfma_f32_16x16x32_bf16 v[6:9], v[232:235], v[224:227], v[6:9]
	v_mfma_f32_16x16x32_bf16 v[2:5], v[240:243], v[224:227], v[2:5]
	s_setprio 0
	s_add_i32 s57, 0, 0x18000
	s_barrier
	s_add_u32 s22, s22, 0x80000
	s_addc_u32 s23, s23, 0
	s_mov_b32 m0, s97
	v_lshl_add_u64 v[228:229], s[22:23], 0, v[136:137]
	ds_read_b128 v[170:173], v148 offset:32768
	ds_read_b128 v[174:177], v148 offset:33792
	ds_read_b128 v[192:195], v148 offset:34816
	ds_read_b128 v[196:199], v148 offset:35840
	ds_read_b128 v[200:203], v148 offset:36864
	ds_read_b128 v[204:207], v148 offset:37888
	ds_read_b128 v[208:211], v148 offset:38912
	ds_read_b128 v[224:227], v148 offset:39936
	global_load_lds_dwordx4 v[228:229], off
	v_lshl_add_u64 v[228:229], s[22:23], 0, v[132:133]
	s_mov_b32 m0, s44
	s_nop 0
	global_load_lds_dwordx4 v[228:229], off
	s_waitcnt lgkmcnt(8)
	s_barrier
	s_waitcnt lgkmcnt(0)
	s_setprio 1
	s_waitcnt lgkmcnt(0)
	v_mfma_f32_16x16x32_bf16 v[90:93], v[150:153], v[170:173], v[90:93]
	v_mfma_f32_16x16x32_bf16 v[94:97], v[158:161], v[170:173], v[94:97]
	v_mfma_f32_16x16x32_bf16 v[102:105], v[150:153], v[192:195], v[102:105]
	v_mfma_f32_16x16x32_bf16 v[106:109], v[158:161], v[192:195], v[106:109]
	v_mfma_f32_16x16x32_bf16 v[114:117], v[150:153], v[200:203], v[114:117]
	v_mfma_f32_16x16x32_bf16 v[118:121], v[158:161], v[200:203], v[118:121]
	v_mfma_f32_16x16x32_bf16 v[122:125], v[150:153], v[208:211], v[122:125]
	v_mfma_f32_16x16x32_bf16 v[126:129], v[158:161], v[208:211], v[126:129]
	v_mfma_f32_16x16x32_bf16 v[90:93], v[154:157], v[174:177], v[90:93]
	v_mfma_f32_16x16x32_bf16 v[94:97], v[166:169], v[174:177], v[94:97]
	v_mfma_f32_16x16x32_bf16 v[102:105], v[154:157], v[196:199], v[102:105]
	v_mfma_f32_16x16x32_bf16 v[106:109], v[166:169], v[196:199], v[106:109]
	v_mfma_f32_16x16x32_bf16 v[114:117], v[154:157], v[204:207], v[114:117]
	v_mfma_f32_16x16x32_bf16 v[118:121], v[166:169], v[204:207], v[118:121]
	v_mfma_f32_16x16x32_bf16 v[122:125], v[154:157], v[224:227], v[122:125]
	v_mfma_f32_16x16x32_bf16 v[126:129], v[166:169], v[224:227], v[126:129]
	s_setprio 0
	s_barrier
	s_add_i32 s22, 0, 0x1c000
	s_add_i32 s23, s57, s85
	v_add_u32_e32 v149, s22, v147
	v_lshl_add_u64 v[162:163], v[162:163], 0, s[78:79]
	s_mov_b32 m0, s23
	ds_read_b128 v[228:231], v149
	ds_read_b128 v[232:235], v149 offset:1024
	ds_read_b128 v[236:239], v149 offset:2048
	ds_read_b128 v[240:243], v149 offset:3072
	global_load_lds_dwordx4 v[162:163], off
	v_lshl_add_u64 v[162:163], v[178:179], 0, s[78:79]
	s_add_i32 m0, s23, 0x2000
	s_nop 0
	global_load_lds_dwordx4 v[162:163], off
	s_barrier
	s_waitcnt lgkmcnt(0)
	s_setprio 1
	s_waitcnt lgkmcnt(0)
	v_mfma_f32_16x16x32_bf16 v[10:13], v[228:231], v[170:173], v[10:13]
	v_mfma_f32_16x16x32_bf16 v[14:17], v[236:239], v[170:173], v[14:17]
	v_mfma_f32_16x16x32_bf16 v[26:29], v[228:231], v[192:195], v[26:29]
	v_mfma_f32_16x16x32_bf16 v[38:41], v[236:239], v[192:195], v[38:41]
	v_mfma_f32_16x16x32_bf16 v[58:61], v[228:231], v[200:203], v[58:61]
	v_mfma_f32_16x16x32_bf16 v[62:65], v[236:239], v[200:203], v[62:65]
	v_mfma_f32_16x16x32_bf16 v[74:77], v[228:231], v[208:211], v[74:77]
	v_mfma_f32_16x16x32_bf16 v[78:81], v[236:239], v[208:211], v[78:81]
	v_mfma_f32_16x16x32_bf16 v[10:13], v[232:235], v[174:177], v[10:13]
	v_mfma_f32_16x16x32_bf16 v[14:17], v[240:243], v[174:177], v[14:17]
	v_mfma_f32_16x16x32_bf16 v[26:29], v[232:235], v[196:199], v[26:29]
	v_mfma_f32_16x16x32_bf16 v[38:41], v[240:243], v[196:199], v[38:41]
	v_mfma_f32_16x16x32_bf16 v[58:61], v[232:235], v[204:207], v[58:61]
	v_mfma_f32_16x16x32_bf16 v[62:65], v[240:243], v[204:207], v[62:65]
	v_mfma_f32_16x16x32_bf16 v[74:77], v[232:235], v[224:227], v[74:77]
	v_mfma_f32_16x16x32_bf16 v[78:81], v[240:243], v[224:227], v[78:81]
	s_setprio 0
	s_mov_b32 m0, s46
	v_lshl_add_u64 v[162:163], v[212:213], 0, s[78:79]
	s_barrier
	ds_read_b128 v[170:173], v148 offset:49152
	ds_read_b128 v[174:177], v148 offset:50176
	ds_read_b128 v[192:195], v148 offset:51200
	ds_read_b128 v[196:199], v148 offset:52224
	ds_read_b128 v[200:203], v148 offset:53248
	ds_read_b128 v[204:207], v148 offset:54272
	ds_read_b128 v[208:211], v148 offset:55296
	ds_read_b128 v[224:227], v148 offset:56320
	global_load_lds_dwordx4 v[162:163], off
	v_lshl_add_u64 v[162:163], v[244:245], 0, s[78:79]
	s_mov_b32 m0, s47
	s_nop 0
	global_load_lds_dwordx4 v[162:163], off
	s_waitcnt vmcnt(10)
	s_barrier
	s_waitcnt lgkmcnt(0)
	s_setprio 1
	s_waitcnt lgkmcnt(0)
	v_mfma_f32_16x16x32_bf16 v[110:113], v[150:153], v[170:173], v[110:113]
	v_mfma_f32_16x16x32_bf16 v[98:101], v[158:161], v[170:173], v[98:101]
	v_mfma_f32_16x16x32_bf16 v[82:85], v[150:153], v[192:195], v[82:85]
	v_mfma_f32_16x16x32_bf16 v[66:69], v[158:161], v[192:195], v[66:69]
	v_mfma_f32_16x16x32_bf16 v[50:53], v[150:153], v[200:203], v[50:53]
	v_mfma_f32_16x16x32_bf16 v[42:45], v[158:161], v[200:203], v[42:45]
	v_mfma_f32_16x16x32_bf16 v[30:33], v[150:153], v[208:211], v[30:33]
	v_mfma_f32_16x16x32_bf16 v[18:21], v[158:161], v[208:211], v[18:21]
	v_mfma_f32_16x16x32_bf16 v[110:113], v[154:157], v[174:177], v[110:113]
	v_mfma_f32_16x16x32_bf16 v[98:101], v[166:169], v[174:177], v[98:101]
	v_mfma_f32_16x16x32_bf16 v[82:85], v[154:157], v[196:199], v[82:85]
	v_mfma_f32_16x16x32_bf16 v[66:69], v[166:169], v[196:199], v[66:69]
	v_mfma_f32_16x16x32_bf16 v[50:53], v[154:157], v[204:207], v[50:53]
	v_mfma_f32_16x16x32_bf16 v[42:45], v[166:169], v[204:207], v[42:45]
	v_mfma_f32_16x16x32_bf16 v[30:33], v[154:157], v[224:227], v[30:33]
	v_mfma_f32_16x16x32_bf16 v[18:21], v[166:169], v[224:227], v[18:21]
	s_setprio 0
	s_barrier
	s_add_u32 s18, s18, 0x80080
	s_addc_u32 s19, s19, 0
	s_add_i32 s22, s22, s85
	v_lshl_add_u64 v[150:151], s[18:19], 0, v[134:135]
	s_mov_b32 m0, s22
	s_nop 0
	global_load_lds_dwordx4 v[150:151], off
	v_lshl_add_u64 v[150:151], s[18:19], 0, v[130:131]
	s_add_i32 m0, s22, 0x2000
	s_nop 0
	global_load_lds_dwordx4 v[150:151], off
	v_add_u32_e32 v149, 0x10000, v147
	ds_read_b128 v[150:153], v149
	ds_read_b128 v[154:157], v149 offset:1024
	ds_read_b128 v[158:161], v149 offset:2048
	ds_read_b128 v[166:169], v149 offset:3072
	s_waitcnt vmcnt(6)
	s_barrier
	s_setprio 1
	v_mfma_f32_16x16x32_bf16 v[86:89], v[228:231], v[170:173], v[86:89]
	v_mfma_f32_16x16x32_bf16 v[70:73], v[236:239], v[170:173], v[70:73]
	v_mfma_f32_16x16x32_bf16 v[54:57], v[228:231], v[192:195], v[54:57]
	v_mfma_f32_16x16x32_bf16 v[46:49], v[236:239], v[192:195], v[46:49]
	v_mfma_f32_16x16x32_bf16 v[34:37], v[228:231], v[200:203], v[34:37]
	v_mfma_f32_16x16x32_bf16 v[22:25], v[236:239], v[200:203], v[22:25]
	v_mfma_f32_16x16x32_bf16 v[6:9], v[228:231], v[208:211], v[6:9]
	v_mfma_f32_16x16x32_bf16 v[2:5], v[236:239], v[208:211], v[2:5]
	v_mfma_f32_16x16x32_bf16 v[86:89], v[232:235], v[174:177], v[86:89]
	v_mfma_f32_16x16x32_bf16 v[70:73], v[240:243], v[174:177], v[70:73]
	v_mfma_f32_16x16x32_bf16 v[54:57], v[232:235], v[196:199], v[54:57]
	v_mfma_f32_16x16x32_bf16 v[46:49], v[240:243], v[196:199], v[46:49]
	v_mfma_f32_16x16x32_bf16 v[34:37], v[232:235], v[204:207], v[34:37]
	v_mfma_f32_16x16x32_bf16 v[22:25], v[240:243], v[204:207], v[22:25]
	v_mfma_f32_16x16x32_bf16 v[6:9], v[232:235], v[224:227], v[6:9]
	v_mfma_f32_16x16x32_bf16 v[2:5], v[240:243], v[224:227], v[2:5]
	s_setprio 0
	s_add_i32 s56, s56, 2
	s_add_u32 vcc_lo, vcc_lo, 0x100
	s_addc_u32 vcc_hi, vcc_hi, 0
	s_cmp_gt_u32 s56, 29
	s_barrier
	s_cbranch_scc0 .LBB0_649
	s_waitcnt lgkmcnt(0)
	s_add_u32 s18, s50, 0xffffff00
	s_addc_u32 s19, s51, -1
	s_andn2_b64 vcc, exec, s[42:43]
	s_cbranch_vccnz .LBB0_652
	v_mov_b32_e32 v2, 0
	s_mov_b32 s84, s80
	s_mov_b32 s25, s82
	s_mov_b64 s[38:39], s[20:21]
	s_mov_b32 s48, s49
	v_mov_b32_e32 v3, v2
	v_mov_b32_e32 v4, v2
	v_mov_b32_e32 v5, v2
	v_mov_b32_e32 v6, v2
	v_mov_b32_e32 v7, v2
	v_mov_b32_e32 v8, v2
	v_mov_b32_e32 v9, v2
	v_mov_b32_e32 v22, v2
	v_mov_b32_e32 v23, v2
	v_mov_b32_e32 v24, v2
	v_mov_b32_e32 v25, v2
	v_mov_b32_e32 v34, v2
	v_mov_b32_e32 v35, v2
	v_mov_b32_e32 v36, v2
	v_mov_b32_e32 v37, v2
	v_mov_b32_e32 v46, v2
	v_mov_b32_e32 v47, v2
	v_mov_b32_e32 v48, v2
	v_mov_b32_e32 v49, v2
	v_mov_b32_e32 v54, v2
	v_mov_b32_e32 v55, v2
	v_mov_b32_e32 v56, v2
	v_mov_b32_e32 v57, v2
	v_mov_b32_e32 v70, v2
	v_mov_b32_e32 v71, v2
	v_mov_b32_e32 v72, v2
	v_mov_b32_e32 v73, v2
	v_mov_b32_e32 v86, v2
	v_mov_b32_e32 v87, v2
	v_mov_b32_e32 v88, v2
	v_mov_b32_e32 v89, v2
	v_mov_b32_e32 v18, v2
	v_mov_b32_e32 v19, v2
	v_mov_b32_e32 v20, v2
	v_mov_b32_e32 v21, v2
	v_mov_b32_e32 v30, v2
	v_mov_b32_e32 v31, v2
	v_mov_b32_e32 v32, v2
	v_mov_b32_e32 v33, v2
	v_mov_b32_e32 v42, v2
	v_mov_b32_e32 v43, v2
	v_mov_b32_e32 v44, v2
	v_mov_b32_e32 v45, v2
	v_mov_b32_e32 v50, v2
	v_mov_b32_e32 v51, v2
	v_mov_b32_e32 v52, v2
	v_mov_b32_e32 v53, v2
	v_mov_b32_e32 v66, v2
	v_mov_b32_e32 v67, v2
	v_mov_b32_e32 v68, v2
	v_mov_b32_e32 v69, v2
	v_mov_b32_e32 v82, v2
	v_mov_b32_e32 v83, v2
	v_mov_b32_e32 v84, v2
	v_mov_b32_e32 v85, v2
	v_mov_b32_e32 v98, v2
	v_mov_b32_e32 v99, v2
	v_mov_b32_e32 v100, v2
	v_mov_b32_e32 v101, v2
	v_mov_b32_e32 v110, v2
	v_mov_b32_e32 v111, v2
	v_mov_b32_e32 v112, v2
	v_mov_b32_e32 v113, v2
	v_mov_b32_e32 v78, v2
	v_mov_b32_e32 v79, v2
	v_mov_b32_e32 v80, v2
	v_mov_b32_e32 v81, v2
	v_mov_b32_e32 v74, v2
	v_mov_b32_e32 v75, v2
	v_mov_b32_e32 v76, v2
	v_mov_b32_e32 v77, v2
	v_mov_b32_e32 v62, v2
	v_mov_b32_e32 v63, v2
	v_mov_b32_e32 v64, v2
	v_mov_b32_e32 v65, v2
	v_mov_b32_e32 v58, v2
	v_mov_b32_e32 v59, v2
	v_mov_b32_e32 v60, v2
	v_mov_b32_e32 v61, v2
	v_mov_b32_e32 v38, v2
	v_mov_b32_e32 v39, v2
	v_mov_b32_e32 v40, v2
	v_mov_b32_e32 v41, v2
	v_mov_b32_e32 v26, v2
	v_mov_b32_e32 v27, v2
	v_mov_b32_e32 v28, v2
	v_mov_b32_e32 v29, v2
	v_mov_b32_e32 v14, v2
	v_mov_b32_e32 v15, v2
	v_mov_b32_e32 v16, v2
	v_mov_b32_e32 v17, v2
	v_mov_b32_e32 v10, v2
	v_mov_b32_e32 v11, v2
	v_mov_b32_e32 v12, v2
	v_mov_b32_e32 v13, v2
	v_mov_b32_e32 v126, v2
	v_mov_b32_e32 v127, v2
	v_mov_b32_e32 v128, v2
	v_mov_b32_e32 v129, v2
	v_mov_b32_e32 v122, v2
	v_mov_b32_e32 v123, v2
	v_mov_b32_e32 v124, v2
	v_mov_b32_e32 v125, v2
	v_mov_b32_e32 v118, v2
	v_mov_b32_e32 v119, v2
	v_mov_b32_e32 v120, v2
	v_mov_b32_e32 v121, v2
	v_mov_b32_e32 v114, v2
	v_mov_b32_e32 v115, v2
	v_mov_b32_e32 v116, v2
	v_mov_b32_e32 v117, v2
	v_mov_b32_e32 v106, v2
	v_mov_b32_e32 v107, v2
	v_mov_b32_e32 v108, v2
	v_mov_b32_e32 v109, v2
	v_mov_b32_e32 v102, v2
	v_mov_b32_e32 v103, v2
	v_mov_b32_e32 v104, v2
	v_mov_b32_e32 v105, v2
	v_mov_b32_e32 v94, v2
	v_mov_b32_e32 v95, v2
	v_mov_b32_e32 v96, v2
	v_mov_b32_e32 v97, v2
	v_mov_b32_e32 v90, v2
	v_mov_b32_e32 v91, v2
	v_mov_b32_e32 v92, v2
	v_mov_b32_e32 v93, v2
	s_andn2_b64 vcc, exec, s[0:1]
	s_cbranch_vccnz .LBB0_653
	s_branch .LBB0_654

.LBB0_748:
	s_ashr_i32 s39, s38, 31
	v_cmp_lt_i64_e32 vcc, s[22:23], v[190:191]
	s_lshl_b64 s[22:23], s[38:39], 20
	s_add_u32 s42, s34, s22
	s_addc_u32 s43, s35, s23
	s_and_b64 s[22:23], vcc, exec
	s_cselect_b32 s39, s43, s19
	s_cselect_b32 s53, s42, s18
	s_ashr_i32 s31, s30, 31
	s_lshl_b64 s[22:23], s[30:31], 20
	s_add_u32 s80, s27, s22
	s_addc_u32 s81, s28, s23
	s_and_b64 s[22:23], vcc, exec
	s_cselect_b32 s31, s81, s21
	s_cselect_b32 s54, s80, s20
	s_add_u32 s18, s18, 0x80080
	s_addc_u32 s19, s19, 0
	s_add_u32 s55, s20, 0x100
	v_mov_b32_e32 v2, 0
	s_addc_u32 s56, s21, 0
	s_mov_b32 s57, -2
	v_mov_b32_e32 v3, v2
	v_mov_b32_e32 v4, v2
	v_mov_b32_e32 v5, v2
	v_mov_b32_e32 v6, v2
	v_mov_b32_e32 v7, v2
	v_mov_b32_e32 v8, v2
	v_mov_b32_e32 v9, v2
	v_mov_b32_e32 v18, v2
	v_mov_b32_e32 v19, v2
	v_mov_b32_e32 v20, v2
	v_mov_b32_e32 v21, v2
	v_mov_b32_e32 v22, v2
	v_mov_b32_e32 v23, v2
	v_mov_b32_e32 v24, v2
	v_mov_b32_e32 v25, v2
	v_mov_b32_e32 v34, v2
	v_mov_b32_e32 v35, v2
	v_mov_b32_e32 v36, v2
	v_mov_b32_e32 v37, v2
	v_mov_b32_e32 v38, v2
	v_mov_b32_e32 v39, v2
	v_mov_b32_e32 v40, v2
	v_mov_b32_e32 v41, v2
	v_mov_b32_e32 v50, v2
	v_mov_b32_e32 v51, v2
	v_mov_b32_e32 v52, v2
	v_mov_b32_e32 v53, v2
	v_mov_b32_e32 v54, v2
	v_mov_b32_e32 v55, v2
	v_mov_b32_e32 v56, v2
	v_mov_b32_e32 v57, v2
	v_mov_b32_e32 v10, v2
	v_mov_b32_e32 v11, v2
	v_mov_b32_e32 v12, v2
	v_mov_b32_e32 v13, v2
	v_mov_b32_e32 v14, v2
	v_mov_b32_e32 v15, v2
	v_mov_b32_e32 v16, v2
	v_mov_b32_e32 v17, v2
	v_mov_b32_e32 v26, v2
	v_mov_b32_e32 v27, v2
	v_mov_b32_e32 v28, v2
	v_mov_b32_e32 v29, v2
	v_mov_b32_e32 v30, v2
	v_mov_b32_e32 v31, v2
	v_mov_b32_e32 v32, v2
	v_mov_b32_e32 v33, v2
	v_mov_b32_e32 v42, v2
	v_mov_b32_e32 v43, v2
	v_mov_b32_e32 v44, v2
	v_mov_b32_e32 v45, v2
	v_mov_b32_e32 v46, v2
	v_mov_b32_e32 v47, v2
	v_mov_b32_e32 v48, v2
	v_mov_b32_e32 v49, v2
	v_mov_b32_e32 v58, v2
	v_mov_b32_e32 v59, v2
	v_mov_b32_e32 v60, v2
	v_mov_b32_e32 v61, v2
	v_mov_b32_e32 v62, v2
	v_mov_b32_e32 v63, v2
	v_mov_b32_e32 v64, v2
	v_mov_b32_e32 v65, v2
	v_mov_b32_e32 v66, v2
	v_mov_b32_e32 v67, v2
	v_mov_b32_e32 v68, v2
	v_mov_b32_e32 v69, v2
	v_mov_b32_e32 v70, v2
	v_mov_b32_e32 v71, v2
	v_mov_b32_e32 v72, v2
	v_mov_b32_e32 v73, v2
	v_mov_b32_e32 v82, v2
	v_mov_b32_e32 v83, v2
	v_mov_b32_e32 v84, v2
	v_mov_b32_e32 v85, v2
	v_mov_b32_e32 v86, v2
	v_mov_b32_e32 v87, v2
	v_mov_b32_e32 v88, v2
	v_mov_b32_e32 v89, v2
	v_mov_b32_e32 v98, v2
	v_mov_b32_e32 v99, v2
	v_mov_b32_e32 v100, v2
	v_mov_b32_e32 v101, v2
	v_mov_b32_e32 v102, v2
	v_mov_b32_e32 v103, v2
	v_mov_b32_e32 v104, v2
	v_mov_b32_e32 v105, v2
	v_mov_b32_e32 v114, v2
	v_mov_b32_e32 v115, v2
	v_mov_b32_e32 v116, v2
	v_mov_b32_e32 v117, v2
	v_mov_b32_e32 v118, v2
	v_mov_b32_e32 v119, v2
	v_mov_b32_e32 v120, v2
	v_mov_b32_e32 v121, v2
	v_mov_b32_e32 v74, v2
	v_mov_b32_e32 v75, v2
	v_mov_b32_e32 v76, v2
	v_mov_b32_e32 v77, v2
	v_mov_b32_e32 v78, v2
	v_mov_b32_e32 v79, v2
	v_mov_b32_e32 v80, v2
	v_mov_b32_e32 v81, v2
	v_mov_b32_e32 v90, v2
	v_mov_b32_e32 v91, v2
	v_mov_b32_e32 v92, v2
	v_mov_b32_e32 v93, v2
	v_mov_b32_e32 v94, v2
	v_mov_b32_e32 v95, v2
	v_mov_b32_e32 v96, v2
	v_mov_b32_e32 v97, v2
	v_mov_b32_e32 v106, v2
	v_mov_b32_e32 v107, v2
	v_mov_b32_e32 v108, v2
	v_mov_b32_e32 v109, v2
	v_mov_b32_e32 v110, v2
	v_mov_b32_e32 v111, v2
	v_mov_b32_e32 v112, v2
	v_mov_b32_e32 v113, v2
	v_mov_b32_e32 v122, v2
	v_mov_b32_e32 v123, v2
	v_mov_b32_e32 v124, v2
	v_mov_b32_e32 v125, v2
	v_mov_b32_e32 v126, v2
	v_mov_b32_e32 v127, v2
	v_mov_b32_e32 v128, v2
	v_mov_b32_e32 v129, v2
	v_add_u32_e32 v159, 0x10000, v1
	ds_read_b128 v[160:163], v159
	ds_read_b128 v[164:167], v159 offset:1024
	ds_read_b128 v[168:171], v159 offset:2048
	ds_read_b128 v[172:175], v159 offset:3072
.LBB0_749:
	s_add_u32 s20, s18, 0xfff80080
	s_addc_u32 s21, s19, -1
	s_add_i32 s58, 0, 0x10000
	s_cmp_eq_u32 s57, 28
	s_cselect_b32 s23, s39, s21
	s_cselect_b32 s22, s53, s20
	s_cselect_b32 s21, s31, s56
	s_cselect_b32 s20, s54, s55
	v_lshl_add_u64 v[212:213], s[18:19], 0, v[154:155]
	s_add_i32 m0, s44, 0xc000
	ds_read_b128 v[176:179], v158
	ds_read_b128 v[192:195], v158 offset:1024
	ds_read_b128 v[196:199], v158 offset:2048
	ds_read_b128 v[200:203], v158 offset:3072
	ds_read_b128 v[204:207], v158 offset:4096
	ds_read_b128 v[208:211], v158 offset:5120
	ds_read_b128 v[224:227], v158 offset:6144
	ds_read_b128 v[228:231], v158 offset:7168
	global_load_lds_dwordx4 v[212:213], off
	v_lshl_add_u64 v[212:213], s[18:19], 0, v[156:157]
	s_add_i32 m0, s44, 0xe000
	s_nop 0
	global_load_lds_dwordx4 v[212:213], off
	s_waitcnt lgkmcnt(8)
	s_barrier
	s_waitcnt lgkmcnt(0)
	s_setprio 1
	s_waitcnt lgkmcnt(0)
	v_mfma_f32_16x16x32_bf16 v[126:129], v[160:163], v[176:179], v[126:129]
	v_mfma_f32_16x16x32_bf16 v[122:125], v[168:171], v[176:179], v[122:125]
	v_mfma_f32_16x16x32_bf16 v[110:113], v[160:163], v[196:199], v[110:113]
	v_mfma_f32_16x16x32_bf16 v[106:109], v[168:171], v[196:199], v[106:109]
	v_mfma_f32_16x16x32_bf16 v[94:97], v[160:163], v[204:207], v[94:97]
	v_mfma_f32_16x16x32_bf16 v[90:93], v[168:171], v[204:207], v[90:93]
	v_mfma_f32_16x16x32_bf16 v[78:81], v[160:163], v[224:227], v[78:81]
	v_mfma_f32_16x16x32_bf16 v[74:77], v[168:171], v[224:227], v[74:77]
	v_mfma_f32_16x16x32_bf16 v[126:129], v[164:167], v[192:195], v[126:129]
	v_mfma_f32_16x16x32_bf16 v[122:125], v[172:175], v[192:195], v[122:125]
	v_mfma_f32_16x16x32_bf16 v[110:113], v[164:167], v[200:203], v[110:113]
	v_mfma_f32_16x16x32_bf16 v[106:109], v[172:175], v[200:203], v[106:109]
	v_mfma_f32_16x16x32_bf16 v[94:97], v[164:167], v[208:211], v[94:97]
	v_mfma_f32_16x16x32_bf16 v[90:93], v[172:175], v[208:211], v[90:93]
	v_mfma_f32_16x16x32_bf16 v[78:81], v[164:167], v[228:231], v[78:81]
	v_mfma_f32_16x16x32_bf16 v[74:77], v[172:175], v[228:231], v[74:77]
	s_setprio 0
	s_barrier
	s_add_i32 s82, 0, 0x14000
	s_add_i32 s58, s58, s29
	v_add_u32_e32 v159, s82, v1
	v_lshl_add_u64 v[212:213], s[20:21], 0, v[134:135]
	s_mov_b32 m0, s58
	ds_read_b128 v[232:235], v159
	ds_read_b128 v[236:239], v159 offset:1024
	ds_read_b128 v[240:243], v159 offset:2048
	ds_read_b128 v[244:247], v159 offset:3072
	global_load_lds_dwordx4 v[212:213], off
	v_lshl_add_u64 v[248:249], s[20:21], 0, v[130:131]
	s_add_i32 m0, s58, 0x2000
	s_nop 0
	global_load_lds_dwordx4 v[248:249], off
	s_barrier
	s_waitcnt lgkmcnt(0)
	s_setprio 1
	s_waitcnt lgkmcnt(0)
	v_mfma_f32_16x16x32_bf16 v[118:121], v[232:235], v[176:179], v[118:121]
	v_mfma_f32_16x16x32_bf16 v[114:117], v[240:243], v[176:179], v[114:117]
	v_mfma_f32_16x16x32_bf16 v[102:105], v[232:235], v[196:199], v[102:105]
	v_mfma_f32_16x16x32_bf16 v[98:101], v[240:243], v[196:199], v[98:101]
	v_mfma_f32_16x16x32_bf16 v[86:89], v[232:235], v[204:207], v[86:89]
	v_mfma_f32_16x16x32_bf16 v[82:85], v[240:243], v[204:207], v[82:85]
	v_mfma_f32_16x16x32_bf16 v[70:73], v[232:235], v[224:227], v[70:73]
	v_mfma_f32_16x16x32_bf16 v[66:69], v[240:243], v[224:227], v[66:69]
	v_mfma_f32_16x16x32_bf16 v[118:121], v[236:239], v[192:195], v[118:121]
	v_mfma_f32_16x16x32_bf16 v[114:117], v[244:247], v[192:195], v[114:117]
	v_mfma_f32_16x16x32_bf16 v[102:105], v[236:239], v[200:203], v[102:105]
	v_mfma_f32_16x16x32_bf16 v[98:101], v[244:247], v[200:203], v[98:101]
	v_mfma_f32_16x16x32_bf16 v[86:89], v[236:239], v[208:211], v[86:89]
	v_mfma_f32_16x16x32_bf16 v[82:85], v[244:247], v[208:211], v[82:85]
	v_mfma_f32_16x16x32_bf16 v[70:73], v[236:239], v[228:231], v[70:73]
	v_mfma_f32_16x16x32_bf16 v[66:69], v[244:247], v[228:231], v[66:69]
	s_setprio 0
	s_mov_b32 m0, s44
	v_lshl_add_u64 v[250:251], s[22:23], 0, v[136:137]
	s_barrier
	ds_read_b128 v[176:179], v158 offset:16384
	ds_read_b128 v[192:195], v158 offset:17408
	ds_read_b128 v[196:199], v158 offset:18432
	ds_read_b128 v[200:203], v158 offset:19456
	ds_read_b128 v[204:207], v158 offset:20480
	ds_read_b128 v[208:211], v158 offset:21504
	ds_read_b128 v[224:227], v158 offset:22528
	ds_read_b128 v[228:231], v158 offset:23552
	global_load_lds_dwordx4 v[250:251], off
	v_lshl_add_u64 v[222:223], s[22:23], 0, v[132:133]
	s_mov_b32 m0, s45
	s_nop 0
	global_load_lds_dwordx4 v[222:223], off
	s_waitcnt vmcnt(10)
	s_barrier
	s_waitcnt lgkmcnt(0)
	s_setprio 1
	s_waitcnt lgkmcnt(0)
	v_mfma_f32_16x16x32_bf16 v[62:65], v[160:163], v[176:179], v[62:65]
	v_mfma_f32_16x16x32_bf16 v[58:61], v[168:171], v[176:179], v[58:61]
	v_mfma_f32_16x16x32_bf16 v[46:49], v[160:163], v[196:199], v[46:49]
	v_mfma_f32_16x16x32_bf16 v[42:45], v[168:171], v[196:199], v[42:45]
	v_mfma_f32_16x16x32_bf16 v[30:33], v[160:163], v[204:207], v[30:33]
	v_mfma_f32_16x16x32_bf16 v[26:29], v[168:171], v[204:207], v[26:29]
	v_mfma_f32_16x16x32_bf16 v[14:17], v[160:163], v[224:227], v[14:17]
	v_mfma_f32_16x16x32_bf16 v[10:13], v[168:171], v[224:227], v[10:13]
	v_mfma_f32_16x16x32_bf16 v[62:65], v[164:167], v[192:195], v[62:65]
	v_mfma_f32_16x16x32_bf16 v[58:61], v[172:175], v[192:195], v[58:61]
	v_mfma_f32_16x16x32_bf16 v[46:49], v[164:167], v[200:203], v[46:49]
	v_mfma_f32_16x16x32_bf16 v[42:45], v[172:175], v[200:203], v[42:45]
	v_mfma_f32_16x16x32_bf16 v[30:33], v[164:167], v[208:211], v[30:33]
	v_mfma_f32_16x16x32_bf16 v[26:29], v[172:175], v[208:211], v[26:29]
	v_mfma_f32_16x16x32_bf16 v[14:17], v[164:167], v[228:231], v[14:17]
	v_mfma_f32_16x16x32_bf16 v[10:13], v[172:175], v[228:231], v[10:13]
	s_setprio 0
	s_barrier
	s_add_u32 s58, s20, 0x80000
	s_addc_u32 s59, s21, 0
	s_add_i32 s82, s82, s29
	v_lshl_add_u64 v[160:161], s[58:59], 0, v[134:135]
	s_mov_b32 m0, s82
	s_nop 0
	global_load_lds_dwordx4 v[160:161], off
	v_lshl_add_u64 v[160:161], s[58:59], 0, v[130:131]
	s_add_i32 m0, s82, 0x2000
	s_nop 0
	global_load_lds_dwordx4 v[160:161], off
	v_add_u32_e32 v159, 0x18000, v1
	ds_read_b128 v[160:163], v159
	ds_read_b128 v[164:167], v159 offset:1024
	ds_read_b128 v[168:171], v159 offset:2048
	ds_read_b128 v[172:175], v159 offset:3072
	s_waitcnt vmcnt(6)
	s_barrier
	s_setprio 1
	v_mfma_f32_16x16x32_bf16 v[54:57], v[232:235], v[176:179], v[54:57]
	v_mfma_f32_16x16x32_bf16 v[50:53], v[240:243], v[176:179], v[50:53]
	v_mfma_f32_16x16x32_bf16 v[38:41], v[232:235], v[196:199], v[38:41]
	v_mfma_f32_16x16x32_bf16 v[34:37], v[240:243], v[196:199], v[34:37]
	v_mfma_f32_16x16x32_bf16 v[22:25], v[232:235], v[204:207], v[22:25]
	v_mfma_f32_16x16x32_bf16 v[18:21], v[240:243], v[204:207], v[18:21]
	v_mfma_f32_16x16x32_bf16 v[6:9], v[232:235], v[224:227], v[6:9]
	v_mfma_f32_16x16x32_bf16 v[2:5], v[240:243], v[224:227], v[2:5]
	v_mfma_f32_16x16x32_bf16 v[54:57], v[236:239], v[192:195], v[54:57]
	v_mfma_f32_16x16x32_bf16 v[50:53], v[244:247], v[192:195], v[50:53]
	v_mfma_f32_16x16x32_bf16 v[38:41], v[236:239], v[200:203], v[38:41]
	v_mfma_f32_16x16x32_bf16 v[34:37], v[244:247], v[200:203], v[34:37]
	v_mfma_f32_16x16x32_bf16 v[22:25], v[236:239], v[208:211], v[22:25]
	v_mfma_f32_16x16x32_bf16 v[18:21], v[244:247], v[208:211], v[18:21]
	v_mfma_f32_16x16x32_bf16 v[6:9], v[236:239], v[228:231], v[6:9]
	v_mfma_f32_16x16x32_bf16 v[2:5], v[244:247], v[228:231], v[2:5]
	s_setprio 0
	s_add_i32 s58, 0, 0x18000
	s_barrier
	s_add_u32 s22, s22, 0x80000
	s_addc_u32 s23, s23, 0
	s_mov_b32 m0, s46
	v_lshl_add_u64 v[232:233], s[22:23], 0, v[136:137]
	ds_read_b128 v[176:179], v158 offset:32768
	ds_read_b128 v[192:195], v158 offset:33792
	ds_read_b128 v[196:199], v158 offset:34816
	ds_read_b128 v[200:203], v158 offset:35840
	ds_read_b128 v[204:207], v158 offset:36864
	ds_read_b128 v[208:211], v158 offset:37888
	ds_read_b128 v[224:227], v158 offset:38912
	ds_read_b128 v[228:231], v158 offset:39936
	global_load_lds_dwordx4 v[232:233], off
	v_lshl_add_u64 v[232:233], s[22:23], 0, v[132:133]
	s_mov_b32 m0, s47
	s_nop 0
	global_load_lds_dwordx4 v[232:233], off
	s_waitcnt lgkmcnt(8)
	s_barrier
	s_waitcnt lgkmcnt(0)
	s_setprio 1
	s_waitcnt lgkmcnt(0)
	v_mfma_f32_16x16x32_bf16 v[126:129], v[160:163], v[176:179], v[126:129]
	v_mfma_f32_16x16x32_bf16 v[122:125], v[168:171], v[176:179], v[122:125]
	v_mfma_f32_16x16x32_bf16 v[110:113], v[160:163], v[196:199], v[110:113]
	v_mfma_f32_16x16x32_bf16 v[106:109], v[168:171], v[196:199], v[106:109]
	v_mfma_f32_16x16x32_bf16 v[94:97], v[160:163], v[204:207], v[94:97]
	v_mfma_f32_16x16x32_bf16 v[90:93], v[168:171], v[204:207], v[90:93]
	v_mfma_f32_16x16x32_bf16 v[78:81], v[160:163], v[224:227], v[78:81]
	v_mfma_f32_16x16x32_bf16 v[74:77], v[168:171], v[224:227], v[74:77]
	v_mfma_f32_16x16x32_bf16 v[126:129], v[164:167], v[192:195], v[126:129]
	v_mfma_f32_16x16x32_bf16 v[122:125], v[172:175], v[192:195], v[122:125]
	v_mfma_f32_16x16x32_bf16 v[110:113], v[164:167], v[200:203], v[110:113]
	v_mfma_f32_16x16x32_bf16 v[106:109], v[172:175], v[200:203], v[106:109]
	v_mfma_f32_16x16x32_bf16 v[94:97], v[164:167], v[208:211], v[94:97]
	v_mfma_f32_16x16x32_bf16 v[90:93], v[172:175], v[208:211], v[90:93]
	v_mfma_f32_16x16x32_bf16 v[78:81], v[164:167], v[228:231], v[78:81]
	v_mfma_f32_16x16x32_bf16 v[74:77], v[172:175], v[228:231], v[74:77]
	s_setprio 0
	s_barrier
	s_add_i32 s22, 0, 0x1c000
	s_add_i32 s23, s58, s29
	v_add_u32_e32 v159, s22, v1
	v_lshl_add_u64 v[212:213], v[212:213], 0, s[78:79]
	s_mov_b32 m0, s23
	ds_read_b128 v[232:235], v159
	ds_read_b128 v[236:239], v159 offset:1024
	ds_read_b128 v[240:243], v159 offset:2048
	ds_read_b128 v[244:247], v159 offset:3072
	global_load_lds_dwordx4 v[212:213], off
	v_lshl_add_u64 v[212:213], v[248:249], 0, s[78:79]
	s_add_i32 m0, s23, 0x2000
	s_nop 0
	global_load_lds_dwordx4 v[212:213], off
	s_barrier
	s_waitcnt lgkmcnt(0)
	s_setprio 1
	s_waitcnt lgkmcnt(0)
	v_mfma_f32_16x16x32_bf16 v[118:121], v[232:235], v[176:179], v[118:121]
	v_mfma_f32_16x16x32_bf16 v[114:117], v[240:243], v[176:179], v[114:117]
	v_mfma_f32_16x16x32_bf16 v[102:105], v[232:235], v[196:199], v[102:105]
	v_mfma_f32_16x16x32_bf16 v[98:101], v[240:243], v[196:199], v[98:101]
	v_mfma_f32_16x16x32_bf16 v[86:89], v[232:235], v[204:207], v[86:89]
	v_mfma_f32_16x16x32_bf16 v[82:85], v[240:243], v[204:207], v[82:85]
	v_mfma_f32_16x16x32_bf16 v[70:73], v[232:235], v[224:227], v[70:73]
	v_mfma_f32_16x16x32_bf16 v[66:69], v[240:243], v[224:227], v[66:69]
	v_mfma_f32_16x16x32_bf16 v[118:121], v[236:239], v[192:195], v[118:121]
	v_mfma_f32_16x16x32_bf16 v[114:117], v[244:247], v[192:195], v[114:117]
	v_mfma_f32_16x16x32_bf16 v[102:105], v[236:239], v[200:203], v[102:105]
	v_mfma_f32_16x16x32_bf16 v[98:101], v[244:247], v[200:203], v[98:101]
	v_mfma_f32_16x16x32_bf16 v[86:89], v[236:239], v[208:211], v[86:89]
	v_mfma_f32_16x16x32_bf16 v[82:85], v[244:247], v[208:211], v[82:85]
	v_mfma_f32_16x16x32_bf16 v[70:73], v[236:239], v[228:231], v[70:73]
	v_mfma_f32_16x16x32_bf16 v[66:69], v[244:247], v[228:231], v[66:69]
	s_setprio 0
	s_mov_b32 m0, s48
	v_lshl_add_u64 v[212:213], v[250:251], 0, s[78:79]
	s_barrier
	ds_read_b128 v[176:179], v158 offset:49152
	ds_read_b128 v[192:195], v158 offset:50176
	ds_read_b128 v[196:199], v158 offset:51200
	ds_read_b128 v[200:203], v158 offset:52224
	ds_read_b128 v[204:207], v158 offset:53248
	ds_read_b128 v[208:211], v158 offset:54272
	ds_read_b128 v[224:227], v158 offset:55296
	ds_read_b128 v[228:231], v158 offset:56320
	global_load_lds_dwordx4 v[212:213], off
	v_lshl_add_u64 v[212:213], v[222:223], 0, s[78:79]
	s_mov_b32 m0, s49
	s_nop 0
	global_load_lds_dwordx4 v[212:213], off
	s_waitcnt vmcnt(10)
	s_barrier
	s_waitcnt lgkmcnt(0)
	s_setprio 1
	s_waitcnt lgkmcnt(0)
	v_mfma_f32_16x16x32_bf16 v[62:65], v[160:163], v[176:179], v[62:65]
	v_mfma_f32_16x16x32_bf16 v[58:61], v[168:171], v[176:179], v[58:61]
	v_mfma_f32_16x16x32_bf16 v[46:49], v[160:163], v[196:199], v[46:49]
	v_mfma_f32_16x16x32_bf16 v[42:45], v[168:171], v[196:199], v[42:45]
	v_mfma_f32_16x16x32_bf16 v[30:33], v[160:163], v[204:207], v[30:33]
	v_mfma_f32_16x16x32_bf16 v[26:29], v[168:171], v[204:207], v[26:29]
	v_mfma_f32_16x16x32_bf16 v[14:17], v[160:163], v[224:227], v[14:17]
	v_mfma_f32_16x16x32_bf16 v[10:13], v[168:171], v[224:227], v[10:13]
	v_mfma_f32_16x16x32_bf16 v[62:65], v[164:167], v[192:195], v[62:65]
	v_mfma_f32_16x16x32_bf16 v[58:61], v[172:175], v[192:195], v[58:61]
	v_mfma_f32_16x16x32_bf16 v[46:49], v[164:167], v[200:203], v[46:49]
	v_mfma_f32_16x16x32_bf16 v[42:45], v[172:175], v[200:203], v[42:45]
	v_mfma_f32_16x16x32_bf16 v[30:33], v[164:167], v[208:211], v[30:33]
	v_mfma_f32_16x16x32_bf16 v[26:29], v[172:175], v[208:211], v[26:29]
	v_mfma_f32_16x16x32_bf16 v[14:17], v[164:167], v[228:231], v[14:17]
	v_mfma_f32_16x16x32_bf16 v[10:13], v[172:175], v[228:231], v[10:13]
	s_setprio 0
	s_barrier
	s_add_u32 s20, s20, 0x80080
	s_addc_u32 s21, s21, 0
	s_add_i32 s22, s22, s29
	v_lshl_add_u64 v[160:161], s[20:21], 0, v[134:135]
	s_mov_b32 m0, s22
	s_nop 0
	global_load_lds_dwordx4 v[160:161], off
	v_lshl_add_u64 v[160:161], s[20:21], 0, v[130:131]
	s_add_i32 m0, s22, 0x2000
	s_nop 0
	global_load_lds_dwordx4 v[160:161], off
	v_add_u32_e32 v159, 0x10000, v1
	ds_read_b128 v[160:163], v159
	ds_read_b128 v[164:167], v159 offset:1024
	ds_read_b128 v[168:171], v159 offset:2048
	ds_read_b128 v[172:175], v159 offset:3072
	s_waitcnt vmcnt(6)
	s_barrier
	s_setprio 1
	v_mfma_f32_16x16x32_bf16 v[54:57], v[232:235], v[176:179], v[54:57]
	v_mfma_f32_16x16x32_bf16 v[50:53], v[240:243], v[176:179], v[50:53]
	v_mfma_f32_16x16x32_bf16 v[38:41], v[232:235], v[196:199], v[38:41]
	v_mfma_f32_16x16x32_bf16 v[34:37], v[240:243], v[196:199], v[34:37]
	v_mfma_f32_16x16x32_bf16 v[22:25], v[232:235], v[204:207], v[22:25]
	v_mfma_f32_16x16x32_bf16 v[18:21], v[240:243], v[204:207], v[18:21]
	v_mfma_f32_16x16x32_bf16 v[6:9], v[232:235], v[224:227], v[6:9]
	v_mfma_f32_16x16x32_bf16 v[2:5], v[240:243], v[224:227], v[2:5]
	v_mfma_f32_16x16x32_bf16 v[54:57], v[236:239], v[192:195], v[54:57]
	v_mfma_f32_16x16x32_bf16 v[50:53], v[244:247], v[192:195], v[50:53]
	v_mfma_f32_16x16x32_bf16 v[38:41], v[236:239], v[200:203], v[38:41]
	v_mfma_f32_16x16x32_bf16 v[34:37], v[244:247], v[200:203], v[34:37]
	v_mfma_f32_16x16x32_bf16 v[22:25], v[236:239], v[208:211], v[22:25]
	v_mfma_f32_16x16x32_bf16 v[18:21], v[244:247], v[208:211], v[18:21]
	v_mfma_f32_16x16x32_bf16 v[6:9], v[236:239], v[228:231], v[6:9]
	v_mfma_f32_16x16x32_bf16 v[2:5], v[244:247], v[228:231], v[2:5]
	s_setprio 0
	s_add_i32 s57, s57, 2
	s_add_u32 s18, s18, 0x100
	s_addc_u32 s19, s19, 0
	s_add_u32 s55, s55, 0x100
	s_addc_u32 s56, s56, 0
	s_cmp_gt_u32 s57, 29
	s_barrier
	s_cbranch_scc0 .LBB0_749
	s_waitcnt lgkmcnt(0)
	s_lshl_b32 s18, s52, 5
	s_add_i32 s18, s18, s51
	v_max_f32_e32 v122, 0, v122
	v_max_f32_e32 v123, 0, v123
	s_ashr_i32 s19, s18, 31
	v_pk_mul_f32 v[162:163], v[122:123], v[122:123]
	v_max_f32_e32 v123, v124, v124
	s_lshl_b64 s[18:19], s[18:19], 17
	v_max_f32_e32 v122, v128, v128
	v_max_f32_e32 v124, 0, v123
	v_max_f32_e32 v123, v129, v129
	s_add_u32 s18, s68, s18
	v_max_f32_e32 v126, 0, v126
	v_max_f32_e32 v127, 0, v127
	v_max_f32_e32 v122, 0, v122
	v_max_f32_e32 v123, 0, v123
	v_max_f32_e32 v125, 0, v125
	s_addc_u32 s19, s69, s19
	v_pk_mul_f32 v[126:127], v[126:127], v[126:127]
	v_pk_mul_f32 v[128:129], v[122:123], v[122:123]
	v_pk_mul_f32 v[164:165], v[124:125], v[124:125]
	v_lshl_add_u64 v[160:161], v[138:139], 1, s[18:19]
	v_cvt_pk_bf16_f32 v122, v126, v127
	v_cvt_pk_bf16_f32 v123, v128, v129
	v_cvt_pk_bf16_f32 v124, v162, v163
	v_cvt_pk_bf16_f32 v125, v164, v165
	v_max_f32_e32 v114, 0, v114
	v_max_f32_e32 v115, 0, v115
	global_store_dwordx4 v[160:161], v[122:125], off
	v_max_f32_e32 v118, v118, v118
	v_max_f32_e32 v119, v119, v119
	v_pk_mul_f32 v[122:123], v[114:115], v[114:115]
	v_max_f32_e32 v115, v116, v116
	v_max_f32_e32 v114, v120, v120
	v_max_f32_e32 v116, 0, v115
	v_max_f32_e32 v115, v121, v121
	v_max_f32_e32 v118, 0, v118
	v_max_f32_e32 v119, 0, v119
	v_max_f32_e32 v114, 0, v114
	v_max_f32_e32 v115, 0, v115
	v_max_f32_e32 v117, 0, v117
	v_pk_mul_f32 v[118:119], v[118:119], v[118:119]
	v_pk_mul_f32 v[120:121], v[114:115], v[114:115]
	v_pk_mul_f32 v[124:125], v[116:117], v[116:117]
	v_cvt_pk_bf16_f32 v114, v118, v119
	v_cvt_pk_bf16_f32 v115, v120, v121
	v_cvt_pk_bf16_f32 v116, v122, v123
	v_cvt_pk_bf16_f32 v117, v124, v125
	v_max_f32_e32 v106, 0, v106
	v_max_f32_e32 v107, 0, v107
	global_store_dwordx4 v[160:161], v[114:117], off offset:256
	v_max_f32_e32 v110, v110, v110
	v_max_f32_e32 v111, v111, v111
	v_pk_mul_f32 v[116:117], v[106:107], v[106:107]
	v_max_f32_e32 v107, v108, v108
	v_max_f32_e32 v106, v112, v112
	v_max_f32_e32 v108, 0, v107
	v_max_f32_e32 v107, v113, v113
	v_max_f32_e32 v110, 0, v110
	v_max_f32_e32 v111, 0, v111
	v_max_f32_e32 v106, 0, v106
	v_max_f32_e32 v107, 0, v107
	v_max_f32_e32 v109, 0, v109
	v_pk_mul_f32 v[110:111], v[110:111], v[110:111]
	v_pk_mul_f32 v[112:113], v[106:107], v[106:107]
	v_pk_mul_f32 v[118:119], v[108:109], v[108:109]
	v_lshl_add_u64 v[114:115], v[140:141], 1, s[18:19]
	v_cvt_pk_bf16_f32 v106, v110, v111
	v_cvt_pk_bf16_f32 v107, v112, v113
	v_cvt_pk_bf16_f32 v108, v116, v117
	v_cvt_pk_bf16_f32 v109, v118, v119
	v_max_f32_e32 v98, 0, v98
	v_max_f32_e32 v99, 0, v99
	global_store_dwordx4 v[114:115], v[106:109], off
	v_max_f32_e32 v102, v102, v102
	v_max_f32_e32 v103, v103, v103
	v_pk_mul_f32 v[106:107], v[98:99], v[98:99]
	v_max_f32_e32 v99, v100, v100
	v_max_f32_e32 v98, v104, v104
	v_max_f32_e32 v100, 0, v99
	v_max_f32_e32 v99, v105, v105
	v_max_f32_e32 v102, 0, v102
	v_max_f32_e32 v103, 0, v103
	v_max_f32_e32 v98, 0, v98
	v_max_f32_e32 v99, 0, v99
	v_max_f32_e32 v101, 0, v101
	v_pk_mul_f32 v[102:103], v[102:103], v[102:103]
	v_pk_mul_f32 v[104:105], v[98:99], v[98:99]
	v_pk_mul_f32 v[108:109], v[100:101], v[100:101]
	v_cvt_pk_bf16_f32 v98, v102, v103
	v_cvt_pk_bf16_f32 v99, v104, v105
	v_cvt_pk_bf16_f32 v100, v106, v107
	v_cvt_pk_bf16_f32 v101, v108, v109
	v_max_f32_e32 v90, 0, v90
	v_max_f32_e32 v91, 0, v91
	global_store_dwordx4 v[114:115], v[98:101], off offset:256
	v_max_f32_e32 v94, v94, v94
	v_max_f32_e32 v95, v95, v95
	v_pk_mul_f32 v[100:101], v[90:91], v[90:91]
	v_max_f32_e32 v91, v92, v92
	v_max_f32_e32 v90, v96, v96
	v_max_f32_e32 v92, 0, v91
	v_max_f32_e32 v91, v97, v97
	v_max_f32_e32 v94, 0, v94
	v_max_f32_e32 v95, 0, v95
	v_max_f32_e32 v90, 0, v90
	v_max_f32_e32 v91, 0, v91
	v_max_f32_e32 v93, 0, v93
	v_pk_mul_f32 v[94:95], v[94:95], v[94:95]
	v_pk_mul_f32 v[96:97], v[90:91], v[90:91]
	v_pk_mul_f32 v[102:103], v[92:93], v[92:93]
	v_lshl_add_u64 v[98:99], v[142:143], 1, s[18:19]
	v_cvt_pk_bf16_f32 v90, v94, v95
	v_cvt_pk_bf16_f32 v91, v96, v97
	v_cvt_pk_bf16_f32 v92, v100, v101
	v_cvt_pk_bf16_f32 v93, v102, v103
	v_max_f32_e32 v82, 0, v82
	v_max_f32_e32 v83, 0, v83
	global_store_dwordx4 v[98:99], v[90:93], off
	v_max_f32_e32 v86, v86, v86
	v_max_f32_e32 v87, v87, v87
	v_pk_mul_f32 v[90:91], v[82:83], v[82:83]
	v_max_f32_e32 v83, v84, v84
	v_max_f32_e32 v82, v88, v88
	v_max_f32_e32 v84, 0, v83
	v_max_f32_e32 v83, v89, v89
	v_max_f32_e32 v86, 0, v86
	v_max_f32_e32 v87, 0, v87
	v_max_f32_e32 v82, 0, v82
	v_max_f32_e32 v83, 0, v83
	v_max_f32_e32 v85, 0, v85
	v_pk_mul_f32 v[86:87], v[86:87], v[86:87]
	v_pk_mul_f32 v[88:89], v[82:83], v[82:83]
	v_pk_mul_f32 v[92:93], v[84:85], v[84:85]
	v_cvt_pk_bf16_f32 v82, v86, v87
	v_cvt_pk_bf16_f32 v83, v88, v89
	v_cvt_pk_bf16_f32 v84, v90, v91
	v_cvt_pk_bf16_f32 v85, v92, v93
	v_max_f32_e32 v74, 0, v74
	v_max_f32_e32 v75, 0, v75
	global_store_dwordx4 v[98:99], v[82:85], off offset:256
	v_max_f32_e32 v78, v78, v78
	v_max_f32_e32 v79, v79, v79
	v_pk_mul_f32 v[84:85], v[74:75], v[74:75]
	v_max_f32_e32 v75, v76, v76
	v_max_f32_e32 v74, v80, v80
	v_max_f32_e32 v76, 0, v75
	v_max_f32_e32 v75, v81, v81
	v_max_f32_e32 v78, 0, v78
	v_max_f32_e32 v79, 0, v79
	v_max_f32_e32 v74, 0, v74
	v_max_f32_e32 v75, 0, v75
	v_max_f32_e32 v77, 0, v77
	v_pk_mul_f32 v[78:79], v[78:79], v[78:79]
	v_pk_mul_f32 v[80:81], v[74:75], v[74:75]
	v_pk_mul_f32 v[86:87], v[76:77], v[76:77]
	v_lshl_add_u64 v[82:83], v[144:145], 1, s[18:19]
	v_cvt_pk_bf16_f32 v74, v78, v79
	v_cvt_pk_bf16_f32 v75, v80, v81
	v_cvt_pk_bf16_f32 v76, v84, v85
	v_cvt_pk_bf16_f32 v77, v86, v87
	v_max_f32_e32 v66, 0, v66
	v_max_f32_e32 v67, 0, v67
	global_store_dwordx4 v[82:83], v[74:77], off
	v_max_f32_e32 v70, v70, v70
	v_max_f32_e32 v71, v71, v71
	v_pk_mul_f32 v[74:75], v[66:67], v[66:67]
	v_max_f32_e32 v67, v68, v68
	v_max_f32_e32 v66, v72, v72
	v_max_f32_e32 v68, 0, v67
	v_max_f32_e32 v67, v73, v73
	v_max_f32_e32 v70, 0, v70
	v_max_f32_e32 v71, 0, v71
	v_max_f32_e32 v66, 0, v66
	v_max_f32_e32 v67, 0, v67
	v_max_f32_e32 v69, 0, v69
	v_pk_mul_f32 v[70:71], v[70:71], v[70:71]
	v_pk_mul_f32 v[72:73], v[66:67], v[66:67]
	v_pk_mul_f32 v[76:77], v[68:69], v[68:69]
	v_cvt_pk_bf16_f32 v66, v70, v71
	v_cvt_pk_bf16_f32 v67, v72, v73
	v_cvt_pk_bf16_f32 v68, v74, v75
	v_cvt_pk_bf16_f32 v69, v76, v77
	v_max_f32_e32 v58, 0, v58
	v_max_f32_e32 v59, 0, v59
	global_store_dwordx4 v[82:83], v[66:69], off offset:256
	v_max_f32_e32 v62, v62, v62
	v_max_f32_e32 v63, v63, v63
	v_pk_mul_f32 v[68:69], v[58:59], v[58:59]
	v_max_f32_e32 v59, v60, v60
	v_max_f32_e32 v58, v64, v64
	v_max_f32_e32 v60, 0, v59
	v_max_f32_e32 v59, v65, v65
	v_max_f32_e32 v62, 0, v62
	v_max_f32_e32 v63, 0, v63
	v_max_f32_e32 v58, 0, v58
	v_max_f32_e32 v59, 0, v59
	v_max_f32_e32 v61, 0, v61
	v_pk_mul_f32 v[62:63], v[62:63], v[62:63]
	v_pk_mul_f32 v[64:65], v[58:59], v[58:59]
	v_pk_mul_f32 v[70:71], v[60:61], v[60:61]
	v_lshl_add_u64 v[66:67], v[146:147], 1, s[18:19]
	v_cvt_pk_bf16_f32 v58, v62, v63
	v_cvt_pk_bf16_f32 v59, v64, v65
	v_cvt_pk_bf16_f32 v60, v68, v69
	v_cvt_pk_bf16_f32 v61, v70, v71
	v_max_f32_e32 v50, 0, v50
	v_max_f32_e32 v51, 0, v51
	global_store_dwordx4 v[66:67], v[58:61], off
	v_max_f32_e32 v54, v54, v54
	v_max_f32_e32 v55, v55, v55
	v_pk_mul_f32 v[58:59], v[50:51], v[50:51]
	v_max_f32_e32 v51, v52, v52
	v_max_f32_e32 v50, v56, v56
	v_max_f32_e32 v52, 0, v51
	v_max_f32_e32 v51, v57, v57
	v_max_f32_e32 v54, 0, v54
	v_max_f32_e32 v55, 0, v55
	v_max_f32_e32 v50, 0, v50
	v_max_f32_e32 v51, 0, v51
	v_max_f32_e32 v53, 0, v53
	v_pk_mul_f32 v[54:55], v[54:55], v[54:55]
	v_pk_mul_f32 v[56:57], v[50:51], v[50:51]
	v_pk_mul_f32 v[60:61], v[52:53], v[52:53]
	v_cvt_pk_bf16_f32 v50, v54, v55
	v_cvt_pk_bf16_f32 v51, v56, v57
	v_cvt_pk_bf16_f32 v52, v58, v59
	v_cvt_pk_bf16_f32 v53, v60, v61
	v_max_f32_e32 v42, 0, v42
	v_max_f32_e32 v43, 0, v43
	global_store_dwordx4 v[66:67], v[50:53], off offset:256
	v_max_f32_e32 v46, v46, v46
	v_max_f32_e32 v47, v47, v47
	v_pk_mul_f32 v[52:53], v[42:43], v[42:43]
	v_max_f32_e32 v43, v44, v44
	v_max_f32_e32 v42, v48, v48
	v_max_f32_e32 v44, 0, v43
	v_max_f32_e32 v43, v49, v49
	v_max_f32_e32 v46, 0, v46
	v_max_f32_e32 v47, 0, v47
	v_max_f32_e32 v42, 0, v42
	v_max_f32_e32 v43, 0, v43
	v_max_f32_e32 v45, 0, v45
	v_pk_mul_f32 v[46:47], v[46:47], v[46:47]
	v_pk_mul_f32 v[48:49], v[42:43], v[42:43]
	v_pk_mul_f32 v[54:55], v[44:45], v[44:45]
	v_lshl_add_u64 v[50:51], v[148:149], 1, s[18:19]
	v_cvt_pk_bf16_f32 v42, v46, v47
	v_cvt_pk_bf16_f32 v43, v48, v49
	v_cvt_pk_bf16_f32 v44, v52, v53
	v_cvt_pk_bf16_f32 v45, v54, v55
	v_max_f32_e32 v34, 0, v34
	v_max_f32_e32 v35, 0, v35
	global_store_dwordx4 v[50:51], v[42:45], off
	v_max_f32_e32 v38, v38, v38
	v_max_f32_e32 v39, v39, v39
	v_pk_mul_f32 v[42:43], v[34:35], v[34:35]
	v_max_f32_e32 v35, v36, v36
	v_max_f32_e32 v34, v40, v40
	v_max_f32_e32 v36, 0, v35
	v_max_f32_e32 v35, v41, v41
	v_max_f32_e32 v38, 0, v38
	v_max_f32_e32 v39, 0, v39
	v_max_f32_e32 v34, 0, v34
	v_max_f32_e32 v35, 0, v35
	v_max_f32_e32 v37, 0, v37
	v_pk_mul_f32 v[38:39], v[38:39], v[38:39]
	v_pk_mul_f32 v[40:41], v[34:35], v[34:35]
	v_pk_mul_f32 v[44:45], v[36:37], v[36:37]
	v_cvt_pk_bf16_f32 v34, v38, v39
	v_cvt_pk_bf16_f32 v35, v40, v41
	v_cvt_pk_bf16_f32 v36, v42, v43
	v_cvt_pk_bf16_f32 v37, v44, v45
	v_max_f32_e32 v26, 0, v26
	v_max_f32_e32 v27, 0, v27
	global_store_dwordx4 v[50:51], v[34:37], off offset:256
	v_max_f32_e32 v30, v30, v30
	v_max_f32_e32 v31, v31, v31
	v_pk_mul_f32 v[36:37], v[26:27], v[26:27]
	v_max_f32_e32 v27, v28, v28
	v_max_f32_e32 v26, v32, v32
	v_max_f32_e32 v28, 0, v27
	v_max_f32_e32 v27, v33, v33
	v_max_f32_e32 v30, 0, v30
	v_max_f32_e32 v31, 0, v31
	v_max_f32_e32 v26, 0, v26
	v_max_f32_e32 v27, 0, v27
	v_max_f32_e32 v29, 0, v29
	v_pk_mul_f32 v[30:31], v[30:31], v[30:31]
	v_pk_mul_f32 v[32:33], v[26:27], v[26:27]
	v_pk_mul_f32 v[38:39], v[28:29], v[28:29]
	v_lshl_add_u64 v[34:35], v[150:151], 1, s[18:19]
	v_cvt_pk_bf16_f32 v26, v30, v31
	v_cvt_pk_bf16_f32 v27, v32, v33
	v_cvt_pk_bf16_f32 v28, v36, v37
	v_cvt_pk_bf16_f32 v29, v38, v39
	v_max_f32_e32 v18, 0, v18
	v_max_f32_e32 v19, 0, v19
	global_store_dwordx4 v[34:35], v[26:29], off
	v_max_f32_e32 v22, v22, v22
	v_max_f32_e32 v23, v23, v23
	v_pk_mul_f32 v[26:27], v[18:19], v[18:19]
	v_max_f32_e32 v19, v20, v20
	v_max_f32_e32 v18, v24, v24
	v_max_f32_e32 v20, 0, v19
	v_max_f32_e32 v19, v25, v25
	v_max_f32_e32 v22, 0, v22
	v_max_f32_e32 v23, 0, v23
	v_max_f32_e32 v18, 0, v18
	v_max_f32_e32 v19, 0, v19
	v_max_f32_e32 v21, 0, v21
	v_pk_mul_f32 v[22:23], v[22:23], v[22:23]
	v_pk_mul_f32 v[24:25], v[18:19], v[18:19]
	v_pk_mul_f32 v[28:29], v[20:21], v[20:21]
	v_cvt_pk_bf16_f32 v18, v22, v23
	v_cvt_pk_bf16_f32 v19, v24, v25
	v_cvt_pk_bf16_f32 v20, v26, v27
	v_cvt_pk_bf16_f32 v21, v28, v29
	v_max_f32_e32 v10, 0, v10
	v_max_f32_e32 v11, 0, v11
	global_store_dwordx4 v[34:35], v[18:21], off offset:256
	v_max_f32_e32 v14, v14, v14
	v_max_f32_e32 v15, v15, v15
	v_pk_mul_f32 v[20:21], v[10:11], v[10:11]
	v_max_f32_e32 v11, v12, v12
	v_max_f32_e32 v10, v16, v16
	v_max_f32_e32 v12, 0, v11
	v_max_f32_e32 v11, v17, v17
	v_max_f32_e32 v14, 0, v14
	v_max_f32_e32 v15, 0, v15
	v_max_f32_e32 v10, 0, v10
	v_max_f32_e32 v11, 0, v11
	v_max_f32_e32 v13, 0, v13
	v_pk_mul_f32 v[14:15], v[14:15], v[14:15]
	v_pk_mul_f32 v[16:17], v[10:11], v[10:11]
	v_pk_mul_f32 v[22:23], v[12:13], v[12:13]
	v_lshl_add_u64 v[18:19], v[152:153], 1, s[18:19]
	v_cvt_pk_bf16_f32 v10, v14, v15
	v_cvt_pk_bf16_f32 v11, v16, v17
	v_cvt_pk_bf16_f32 v12, v20, v21
	v_cvt_pk_bf16_f32 v13, v22, v23
	v_max_f32_e32 v2, 0, v2
	v_max_f32_e32 v3, 0, v3
	global_store_dwordx4 v[18:19], v[10:13], off
	v_max_f32_e32 v6, v6, v6
	v_max_f32_e32 v7, v7, v7
	v_pk_mul_f32 v[10:11], v[2:3], v[2:3]
	v_max_f32_e32 v3, v4, v4
	v_max_f32_e32 v2, v8, v8
	v_max_f32_e32 v4, 0, v3
	v_max_f32_e32 v3, v9, v9
	v_max_f32_e32 v6, 0, v6
	v_max_f32_e32 v7, 0, v7
	v_max_f32_e32 v2, 0, v2
	v_max_f32_e32 v3, 0, v3
	v_max_f32_e32 v5, 0, v5
	v_pk_mul_f32 v[6:7], v[6:7], v[6:7]
	v_pk_mul_f32 v[8:9], v[2:3], v[2:3]
	v_pk_mul_f32 v[12:13], v[4:5], v[4:5]
	v_cvt_pk_bf16_f32 v2, v6, v7
	v_cvt_pk_bf16_f32 v3, v8, v9
	v_cvt_pk_bf16_f32 v4, v10, v11
	v_cvt_pk_bf16_f32 v5, v12, v13
	s_and_b64 vcc, exec, s[0:1]
	s_mov_b32 s51, s30
	s_mov_b32 s52, s38
	s_mov_b64 s[20:21], s[80:81]
	s_mov_b64 s[18:19], s[42:43]
	global_store_dwordx4 v[18:19], v[2:5], off offset:256
	s_cbranch_vccz .LBB0_742
	s_waitcnt vmcnt(0)
	v_readlane_b32 s38, v255, 28
	s_cmpk_gt_u32 s26, 0xff
	v_readlane_b32 s39, v255, 29
	v_readlane_b32 s42, v255, 32
	s_cbranch_scc1 .LBB0_753
	s_barrier

.LBB0_813:
	s_ashr_i32 s83, s82, 31
	s_lshl_b64 s[18:19], s[82:83], 22
	s_add_u32 s18, s68, s18
	s_addc_u32 s19, s69, s19
	s_and_b64 s[20:21], s[38:39], exec
	s_cselect_b32 s51, s19, s85
	s_cselect_b32 s52, s18, s84
	s_ashr_i32 s43, s42, 31
	s_lshl_b64 s[20:21], s[42:43], 22
	s_add_u32 s20, s26, s20
	s_addc_u32 s21, s27, s21
	s_and_b64 s[22:23], s[38:39], exec
	s_cselect_b32 s43, s21, s31
	s_cselect_b32 s53, s20, s30
	s_mov_b32 s54, -2
	s_mov_b64 s[90:91], 0
	s_mov_b32 s55, 0x10000
	v_add_u32_e32 v141, 0x10000, v139
	ds_read_b128 v[142:145], v141
	ds_read_b128 v[146:149], v141 offset:1024
	ds_read_b128 v[150:153], v141 offset:2048
	ds_read_b128 v[154:157], v141 offset:3072
.LBB0_814:
	s_add_i32 s22, s55, 0xffff0000
	s_and_b32 s22, s22, 0x3e0000
	s_and_b32 s23, s90, 0x100
	s_or_b32 s56, s23, s22
	s_and_b32 s22, s55, 0x7e0000
	s_add_u32 vcc_lo, s90, 0x100
	s_addc_u32 vcc_hi, s91, 0
	s_and_b32 s23, vcc_lo, 0x100
	s_or_b32 s22, s22, s23
	s_add_u32 s22, s84, s22
	s_addc_u32 s23, s85, 0
	s_add_u32 s57, s30, s90
	s_addc_u32 s58, s31, s91
	s_add_u32 s57, s57, 0x100
	s_addc_u32 s58, s58, 0
	s_add_i32 s59, 0, 0x10000
	s_cmpk_eq_i32 s54, 0x7c
	s_cselect_b32 s91, s43, s58
	s_cselect_b32 s90, s53, s57
	s_cselect_b32 s23, s51, s23
	s_cselect_b32 s22, s52, s22
	s_add_u32 s56, s84, s56
	s_addc_u32 s57, s85, 0
	s_add_u32 s56, s56, 0x10080
	s_addc_u32 s57, s57, 0
	v_lshl_add_u64 v[204:205], s[56:57], 0, v[136:137]
	s_add_i32 m0, s28, 0xc000
	ds_read_b128 v[158:161], v140
	ds_read_b128 v[162:165], v140 offset:1024
	ds_read_b128 v[168:171], v140 offset:2048
	ds_read_b128 v[172:175], v140 offset:3072
	ds_read_b128 v[176:179], v140 offset:4096
	ds_read_b128 v[192:195], v140 offset:5120
	ds_read_b128 v[196:199], v140 offset:6144
	ds_read_b128 v[200:203], v140 offset:7168
	global_load_lds_dwordx4 v[204:205], off
	v_lshl_add_u64 v[204:205], s[56:57], 0, v[132:133]
	s_add_i32 m0, s28, 0xe000
	s_nop 0
	global_load_lds_dwordx4 v[204:205], off
	s_waitcnt lgkmcnt(8)
	s_barrier
	s_waitcnt lgkmcnt(0)
	s_setprio 1
	s_waitcnt lgkmcnt(0)
	v_mfma_f32_16x16x32_bf16 v[86:89], v[142:145], v[158:161], v[86:89]
	v_mfma_f32_16x16x32_bf16 v[94:97], v[150:153], v[158:161], v[94:97]
	v_mfma_f32_16x16x32_bf16 v[98:101], v[142:145], v[168:171], v[98:101]
	v_mfma_f32_16x16x32_bf16 v[102:105], v[150:153], v[168:171], v[102:105]
	v_mfma_f32_16x16x32_bf16 v[114:117], v[142:145], v[176:179], v[114:117]
	v_mfma_f32_16x16x32_bf16 v[122:125], v[150:153], v[176:179], v[122:125]
	v_mfma_f32_16x16x32_bf16 v[126:129], v[142:145], v[196:199], v[126:129]
	v_mfma_f32_16x16x32_bf16 v[118:121], v[150:153], v[196:199], v[118:121]
	v_mfma_f32_16x16x32_bf16 v[86:89], v[146:149], v[162:165], v[86:89]
	v_mfma_f32_16x16x32_bf16 v[94:97], v[154:157], v[162:165], v[94:97]
	v_mfma_f32_16x16x32_bf16 v[98:101], v[146:149], v[172:175], v[98:101]
	v_mfma_f32_16x16x32_bf16 v[102:105], v[154:157], v[172:175], v[102:105]
	v_mfma_f32_16x16x32_bf16 v[114:117], v[146:149], v[192:195], v[114:117]
	v_mfma_f32_16x16x32_bf16 v[122:125], v[154:157], v[192:195], v[122:125]
	v_mfma_f32_16x16x32_bf16 v[126:129], v[146:149], v[200:203], v[126:129]
	v_mfma_f32_16x16x32_bf16 v[118:121], v[154:157], v[200:203], v[118:121]
	s_setprio 0
	s_barrier
	s_add_i32 s58, 0, 0x14000
	s_add_i32 s56, s59, s81
	v_add_u32_e32 v141, s58, v139
	v_lshl_add_u64 v[212:213], s[90:91], 0, v[134:135]
	s_mov_b32 m0, s56
	ds_read_b128 v[204:207], v141
	ds_read_b128 v[208:211], v141 offset:1024
	ds_read_b128 v[224:227], v141 offset:2048
	ds_read_b128 v[228:231], v141 offset:3072
	global_load_lds_dwordx4 v[212:213], off
	v_lshl_add_u64 v[222:223], s[90:91], 0, v[130:131]
	s_add_i32 m0, s56, 0x2000
	s_nop 0
	global_load_lds_dwordx4 v[222:223], off
	s_barrier
	s_waitcnt lgkmcnt(0)
	s_setprio 1
	s_waitcnt lgkmcnt(0)
	v_mfma_f32_16x16x32_bf16 v[2:5], v[204:207], v[158:161], v[2:5]
	v_mfma_f32_16x16x32_bf16 v[6:9], v[224:227], v[158:161], v[6:9]
	v_mfma_f32_16x16x32_bf16 v[10:13], v[204:207], v[168:171], v[10:13]
	v_mfma_f32_16x16x32_bf16 v[14:17], v[224:227], v[168:171], v[14:17]
	v_mfma_f32_16x16x32_bf16 v[22:25], v[204:207], v[176:179], v[22:25]
	v_mfma_f32_16x16x32_bf16 v[18:21], v[224:227], v[176:179], v[18:21]
	v_mfma_f32_16x16x32_bf16 v[30:33], v[204:207], v[196:199], v[30:33]
	v_mfma_f32_16x16x32_bf16 v[26:29], v[224:227], v[196:199], v[26:29]
	v_mfma_f32_16x16x32_bf16 v[2:5], v[208:211], v[162:165], v[2:5]
	v_mfma_f32_16x16x32_bf16 v[6:9], v[228:231], v[162:165], v[6:9]
	v_mfma_f32_16x16x32_bf16 v[10:13], v[208:211], v[172:175], v[10:13]
	v_mfma_f32_16x16x32_bf16 v[14:17], v[228:231], v[172:175], v[14:17]
	v_mfma_f32_16x16x32_bf16 v[22:25], v[208:211], v[192:195], v[22:25]
	v_mfma_f32_16x16x32_bf16 v[18:21], v[228:231], v[192:195], v[18:21]
	v_mfma_f32_16x16x32_bf16 v[30:33], v[208:211], v[200:203], v[30:33]
	v_mfma_f32_16x16x32_bf16 v[26:29], v[228:231], v[200:203], v[26:29]
	s_setprio 0
	s_mov_b32 m0, s28
	v_lshl_add_u64 v[232:233], s[22:23], 0, v[136:137]
	s_barrier
	ds_read_b128 v[158:161], v140 offset:16384
	ds_read_b128 v[162:165], v140 offset:17408
	ds_read_b128 v[168:171], v140 offset:18432
	ds_read_b128 v[172:175], v140 offset:19456
	ds_read_b128 v[176:179], v140 offset:20480
	ds_read_b128 v[192:195], v140 offset:21504
	ds_read_b128 v[196:199], v140 offset:22528
	ds_read_b128 v[200:203], v140 offset:23552
	global_load_lds_dwordx4 v[232:233], off
	v_lshl_add_u64 v[234:235], s[22:23], 0, v[132:133]
	s_mov_b32 m0, s29
	s_nop 0
	global_load_lds_dwordx4 v[234:235], off
	s_waitcnt vmcnt(10)
	s_barrier
	s_waitcnt lgkmcnt(0)
	s_setprio 1
	s_waitcnt lgkmcnt(0)
	v_mfma_f32_16x16x32_bf16 v[110:113], v[142:145], v[158:161], v[110:113]
	v_mfma_f32_16x16x32_bf16 v[106:109], v[150:153], v[158:161], v[106:109]
	v_mfma_f32_16x16x32_bf16 v[90:93], v[142:145], v[168:171], v[90:93]
	v_mfma_f32_16x16x32_bf16 v[82:85], v[150:153], v[168:171], v[82:85]
	v_mfma_f32_16x16x32_bf16 v[78:81], v[142:145], v[176:179], v[78:81]
	v_mfma_f32_16x16x32_bf16 v[74:77], v[150:153], v[176:179], v[74:77]
	v_mfma_f32_16x16x32_bf16 v[70:73], v[142:145], v[196:199], v[70:73]
	v_mfma_f32_16x16x32_bf16 v[66:69], v[150:153], v[196:199], v[66:69]
	v_mfma_f32_16x16x32_bf16 v[110:113], v[146:149], v[162:165], v[110:113]
	v_mfma_f32_16x16x32_bf16 v[106:109], v[154:157], v[162:165], v[106:109]
	v_mfma_f32_16x16x32_bf16 v[90:93], v[146:149], v[172:175], v[90:93]
	v_mfma_f32_16x16x32_bf16 v[82:85], v[154:157], v[172:175], v[82:85]
	v_mfma_f32_16x16x32_bf16 v[78:81], v[146:149], v[192:195], v[78:81]
	v_mfma_f32_16x16x32_bf16 v[74:77], v[154:157], v[192:195], v[74:77]
	v_mfma_f32_16x16x32_bf16 v[70:73], v[146:149], v[200:203], v[70:73]
	v_mfma_f32_16x16x32_bf16 v[66:69], v[154:157], v[200:203], v[66:69]
	s_setprio 0
	s_barrier
	s_add_u32 s56, s90, 0x200000
	s_addc_u32 s57, s91, 0
	s_add_i32 s58, s58, s81
	v_lshl_add_u64 v[142:143], s[56:57], 0, v[134:135]
	s_mov_b32 m0, s58
	s_nop 0
	global_load_lds_dwordx4 v[142:143], off
	v_lshl_add_u64 v[142:143], s[56:57], 0, v[130:131]
	s_add_i32 m0, s58, 0x2000
	s_nop 0
	global_load_lds_dwordx4 v[142:143], off
	v_add_u32_e32 v141, 0x18000, v139
	ds_read_b128 v[142:145], v141
	ds_read_b128 v[146:149], v141 offset:1024
	ds_read_b128 v[150:153], v141 offset:2048
	ds_read_b128 v[154:157], v141 offset:3072
	s_waitcnt vmcnt(6)
	s_barrier
	s_setprio 1
	v_mfma_f32_16x16x32_bf16 v[38:41], v[204:207], v[158:161], v[38:41]
	v_mfma_f32_16x16x32_bf16 v[34:37], v[224:227], v[158:161], v[34:37]
	v_mfma_f32_16x16x32_bf16 v[46:49], v[204:207], v[168:171], v[46:49]
	v_mfma_f32_16x16x32_bf16 v[42:45], v[224:227], v[168:171], v[42:45]
	v_mfma_f32_16x16x32_bf16 v[54:57], v[204:207], v[176:179], v[54:57]
	v_mfma_f32_16x16x32_bf16 v[50:53], v[224:227], v[176:179], v[50:53]
	v_mfma_f32_16x16x32_bf16 v[62:65], v[204:207], v[196:199], v[62:65]
	v_mfma_f32_16x16x32_bf16 v[58:61], v[224:227], v[196:199], v[58:61]
	v_mfma_f32_16x16x32_bf16 v[38:41], v[208:211], v[162:165], v[38:41]
	v_mfma_f32_16x16x32_bf16 v[34:37], v[228:231], v[162:165], v[34:37]
	v_mfma_f32_16x16x32_bf16 v[46:49], v[208:211], v[172:175], v[46:49]
	v_mfma_f32_16x16x32_bf16 v[42:45], v[228:231], v[172:175], v[42:45]
	v_mfma_f32_16x16x32_bf16 v[54:57], v[208:211], v[192:195], v[54:57]
	v_mfma_f32_16x16x32_bf16 v[50:53], v[228:231], v[192:195], v[50:53]
	v_mfma_f32_16x16x32_bf16 v[62:65], v[208:211], v[200:203], v[62:65]
	v_mfma_f32_16x16x32_bf16 v[58:61], v[228:231], v[200:203], v[58:61]
	s_setprio 0
	s_add_i32 s56, 0, 0x18000
	s_barrier
	s_add_u32 s22, s22, 0x10000
	s_addc_u32 s23, s23, 0
	s_mov_b32 m0, s44
	v_lshl_add_u64 v[204:205], s[22:23], 0, v[136:137]
	ds_read_b128 v[158:161], v140 offset:32768
	ds_read_b128 v[162:165], v140 offset:33792
	ds_read_b128 v[168:171], v140 offset:34816
	ds_read_b128 v[172:175], v140 offset:35840
	ds_read_b128 v[176:179], v140 offset:36864
	ds_read_b128 v[192:195], v140 offset:37888
	ds_read_b128 v[196:199], v140 offset:38912
	ds_read_b128 v[200:203], v140 offset:39936
	global_load_lds_dwordx4 v[204:205], off
	v_lshl_add_u64 v[204:205], s[22:23], 0, v[132:133]
	s_mov_b32 m0, s45
	s_nop 0
	global_load_lds_dwordx4 v[204:205], off
	s_waitcnt lgkmcnt(8)
	s_barrier
	s_waitcnt lgkmcnt(0)
	s_setprio 1
	s_waitcnt lgkmcnt(0)
	v_mfma_f32_16x16x32_bf16 v[86:89], v[142:145], v[158:161], v[86:89]
	v_mfma_f32_16x16x32_bf16 v[94:97], v[150:153], v[158:161], v[94:97]
	v_mfma_f32_16x16x32_bf16 v[98:101], v[142:145], v[168:171], v[98:101]
	v_mfma_f32_16x16x32_bf16 v[102:105], v[150:153], v[168:171], v[102:105]
	v_mfma_f32_16x16x32_bf16 v[114:117], v[142:145], v[176:179], v[114:117]
	v_mfma_f32_16x16x32_bf16 v[122:125], v[150:153], v[176:179], v[122:125]
	v_mfma_f32_16x16x32_bf16 v[126:129], v[142:145], v[196:199], v[126:129]
	v_mfma_f32_16x16x32_bf16 v[118:121], v[150:153], v[196:199], v[118:121]
	v_mfma_f32_16x16x32_bf16 v[86:89], v[146:149], v[162:165], v[86:89]
	v_mfma_f32_16x16x32_bf16 v[94:97], v[154:157], v[162:165], v[94:97]
	v_mfma_f32_16x16x32_bf16 v[98:101], v[146:149], v[172:175], v[98:101]
	v_mfma_f32_16x16x32_bf16 v[102:105], v[154:157], v[172:175], v[102:105]
	v_mfma_f32_16x16x32_bf16 v[114:117], v[146:149], v[192:195], v[114:117]
	v_mfma_f32_16x16x32_bf16 v[122:125], v[154:157], v[192:195], v[122:125]
	v_mfma_f32_16x16x32_bf16 v[126:129], v[146:149], v[200:203], v[126:129]
	v_mfma_f32_16x16x32_bf16 v[118:121], v[154:157], v[200:203], v[118:121]
	s_setprio 0
	s_barrier
	s_add_i32 s57, 0, 0x1c000
	s_add_i32 s22, s56, s81
	v_add_u32_e32 v141, s57, v139
	v_lshl_add_u64 v[212:213], v[212:213], 0, s[78:79]
	s_mov_b32 m0, s22
	ds_read_b128 v[204:207], v141
	ds_read_b128 v[208:211], v141 offset:1024
	ds_read_b128 v[224:227], v141 offset:2048
	ds_read_b128 v[228:231], v141 offset:3072
	global_load_lds_dwordx4 v[212:213], off
	v_lshl_add_u64 v[212:213], v[222:223], 0, s[78:79]
	s_add_i32 m0, s22, 0x2000
	s_nop 0
	global_load_lds_dwordx4 v[212:213], off
	s_barrier
	s_waitcnt lgkmcnt(0)
	s_setprio 1
	s_waitcnt lgkmcnt(0)
	v_mfma_f32_16x16x32_bf16 v[2:5], v[204:207], v[158:161], v[2:5]
	v_mfma_f32_16x16x32_bf16 v[6:9], v[224:227], v[158:161], v[6:9]
	v_mfma_f32_16x16x32_bf16 v[10:13], v[204:207], v[168:171], v[10:13]
	v_mfma_f32_16x16x32_bf16 v[14:17], v[224:227], v[168:171], v[14:17]
	v_mfma_f32_16x16x32_bf16 v[22:25], v[204:207], v[176:179], v[22:25]
	v_mfma_f32_16x16x32_bf16 v[18:21], v[224:227], v[176:179], v[18:21]
	v_mfma_f32_16x16x32_bf16 v[30:33], v[204:207], v[196:199], v[30:33]
	v_mfma_f32_16x16x32_bf16 v[26:29], v[224:227], v[196:199], v[26:29]
	v_mfma_f32_16x16x32_bf16 v[2:5], v[208:211], v[162:165], v[2:5]
	v_mfma_f32_16x16x32_bf16 v[6:9], v[228:231], v[162:165], v[6:9]
	v_mfma_f32_16x16x32_bf16 v[10:13], v[208:211], v[172:175], v[10:13]
	v_mfma_f32_16x16x32_bf16 v[14:17], v[228:231], v[172:175], v[14:17]
	v_mfma_f32_16x16x32_bf16 v[22:25], v[208:211], v[192:195], v[22:25]
	v_mfma_f32_16x16x32_bf16 v[18:21], v[228:231], v[192:195], v[18:21]
	v_mfma_f32_16x16x32_bf16 v[30:33], v[208:211], v[200:203], v[30:33]
	v_mfma_f32_16x16x32_bf16 v[26:29], v[228:231], v[200:203], v[26:29]
	s_setprio 0
	s_mov_b32 m0, s47
	v_lshl_add_u64 v[212:213], v[232:233], 0, s[78:79]
	s_barrier
	ds_read_b128 v[158:161], v140 offset:49152
	ds_read_b128 v[162:165], v140 offset:50176
	ds_read_b128 v[168:171], v140 offset:51200
	ds_read_b128 v[172:175], v140 offset:52224
	ds_read_b128 v[176:179], v140 offset:53248
	ds_read_b128 v[192:195], v140 offset:54272
	ds_read_b128 v[196:199], v140 offset:55296
	ds_read_b128 v[200:203], v140 offset:56320
	global_load_lds_dwordx4 v[212:213], off
	v_lshl_add_u64 v[212:213], v[234:235], 0, s[78:79]
	s_mov_b32 m0, s48
	s_nop 0
	global_load_lds_dwordx4 v[212:213], off
	s_waitcnt vmcnt(10)
	s_barrier
	s_waitcnt lgkmcnt(0)
	s_setprio 1
	s_waitcnt lgkmcnt(0)
	v_mfma_f32_16x16x32_bf16 v[110:113], v[142:145], v[158:161], v[110:113]
	v_mfma_f32_16x16x32_bf16 v[106:109], v[150:153], v[158:161], v[106:109]
	v_mfma_f32_16x16x32_bf16 v[90:93], v[142:145], v[168:171], v[90:93]
	v_mfma_f32_16x16x32_bf16 v[82:85], v[150:153], v[168:171], v[82:85]
	v_mfma_f32_16x16x32_bf16 v[78:81], v[142:145], v[176:179], v[78:81]
	v_mfma_f32_16x16x32_bf16 v[74:77], v[150:153], v[176:179], v[74:77]
	v_mfma_f32_16x16x32_bf16 v[70:73], v[142:145], v[196:199], v[70:73]
	v_mfma_f32_16x16x32_bf16 v[66:69], v[150:153], v[196:199], v[66:69]
	v_mfma_f32_16x16x32_bf16 v[110:113], v[146:149], v[162:165], v[110:113]
	v_mfma_f32_16x16x32_bf16 v[106:109], v[154:157], v[162:165], v[106:109]
	v_mfma_f32_16x16x32_bf16 v[90:93], v[146:149], v[172:175], v[90:93]
	v_mfma_f32_16x16x32_bf16 v[82:85], v[154:157], v[172:175], v[82:85]
	v_mfma_f32_16x16x32_bf16 v[78:81], v[146:149], v[192:195], v[78:81]
	v_mfma_f32_16x16x32_bf16 v[74:77], v[154:157], v[192:195], v[74:77]
	v_mfma_f32_16x16x32_bf16 v[70:73], v[146:149], v[200:203], v[70:73]
	v_mfma_f32_16x16x32_bf16 v[66:69], v[154:157], v[200:203], v[66:69]
	s_setprio 0
	s_barrier
	s_add_u32 s22, s90, 0x200080
	s_addc_u32 s23, s91, 0
	s_add_i32 s56, s57, s81
	v_lshl_add_u64 v[142:143], s[22:23], 0, v[134:135]
	s_mov_b32 m0, s56
	s_nop 0
	global_load_lds_dwordx4 v[142:143], off
	v_lshl_add_u64 v[142:143], s[22:23], 0, v[130:131]
	s_add_i32 m0, s56, 0x2000
	s_nop 0
	global_load_lds_dwordx4 v[142:143], off
	v_add_u32_e32 v141, 0x10000, v139
	ds_read_b128 v[142:145], v141
	ds_read_b128 v[146:149], v141 offset:1024
	ds_read_b128 v[150:153], v141 offset:2048
	ds_read_b128 v[154:157], v141 offset:3072
	s_waitcnt vmcnt(6)
	s_barrier
	s_setprio 1
	v_mfma_f32_16x16x32_bf16 v[38:41], v[204:207], v[158:161], v[38:41]
	v_mfma_f32_16x16x32_bf16 v[34:37], v[224:227], v[158:161], v[34:37]
	v_mfma_f32_16x16x32_bf16 v[46:49], v[204:207], v[168:171], v[46:49]
	v_mfma_f32_16x16x32_bf16 v[42:45], v[224:227], v[168:171], v[42:45]
	v_mfma_f32_16x16x32_bf16 v[54:57], v[204:207], v[176:179], v[54:57]
	v_mfma_f32_16x16x32_bf16 v[50:53], v[224:227], v[176:179], v[50:53]
	v_mfma_f32_16x16x32_bf16 v[62:65], v[204:207], v[196:199], v[62:65]
	v_mfma_f32_16x16x32_bf16 v[58:61], v[224:227], v[196:199], v[58:61]
	v_mfma_f32_16x16x32_bf16 v[38:41], v[208:211], v[162:165], v[38:41]
	v_mfma_f32_16x16x32_bf16 v[34:37], v[228:231], v[162:165], v[34:37]
	v_mfma_f32_16x16x32_bf16 v[46:49], v[208:211], v[172:175], v[46:49]
	v_mfma_f32_16x16x32_bf16 v[42:45], v[228:231], v[172:175], v[42:45]
	v_mfma_f32_16x16x32_bf16 v[54:57], v[208:211], v[192:195], v[54:57]
	v_mfma_f32_16x16x32_bf16 v[50:53], v[228:231], v[192:195], v[50:53]
	v_mfma_f32_16x16x32_bf16 v[62:65], v[208:211], v[200:203], v[62:65]
	v_mfma_f32_16x16x32_bf16 v[58:61], v[228:231], v[200:203], v[58:61]
	s_setprio 0
	s_add_i32 s54, s54, 2
	s_add_i32 s55, s55, 0x10000
	s_cmpk_gt_u32 s54, 0x7d
	s_mov_b64 s[90:91], vcc
	s_barrier
	s_cbranch_scc0 .LBB0_814
	s_waitcnt lgkmcnt(0)
	s_andn2_b64 vcc, exec, s[38:39]
	s_cbranch_vccnz .LBB0_806
	v_mov_b32_e32 v58, 0
	s_mov_b32 s80, s42
	s_mov_b32 s25, s82
	s_mov_b64 s[30:31], s[20:21]
	s_mov_b64 s[84:85], s[18:19]
	s_mov_b32 s49, s50
	v_mov_b32_e32 v59, v58
	v_mov_b32_e32 v60, v58
	v_mov_b32_e32 v61, v58
	v_mov_b32_e32 v62, v58
	v_mov_b32_e32 v63, v58
	v_mov_b32_e32 v64, v58
	v_mov_b32_e32 v65, v58
	v_mov_b32_e32 v50, v58
	v_mov_b32_e32 v51, v58
	v_mov_b32_e32 v52, v58
	v_mov_b32_e32 v53, v58
	v_mov_b32_e32 v54, v58
	v_mov_b32_e32 v55, v58
	v_mov_b32_e32 v56, v58
	v_mov_b32_e32 v57, v58
	v_mov_b32_e32 v42, v58
	v_mov_b32_e32 v43, v58
	v_mov_b32_e32 v44, v58
	v_mov_b32_e32 v45, v58
	v_mov_b32_e32 v46, v58
	v_mov_b32_e32 v47, v58
	v_mov_b32_e32 v48, v58
	v_mov_b32_e32 v49, v58
	v_mov_b32_e32 v34, v58
	v_mov_b32_e32 v35, v58
	v_mov_b32_e32 v36, v58
	v_mov_b32_e32 v37, v58
	v_mov_b32_e32 v38, v58
	v_mov_b32_e32 v39, v58
	v_mov_b32_e32 v40, v58
	v_mov_b32_e32 v41, v58
	v_mov_b32_e32 v66, v58
	v_mov_b32_e32 v67, v58
	v_mov_b32_e32 v68, v58
	v_mov_b32_e32 v69, v58
	v_mov_b32_e32 v70, v58
	v_mov_b32_e32 v71, v58
	v_mov_b32_e32 v72, v58
	v_mov_b32_e32 v73, v58
	v_mov_b32_e32 v74, v58
	v_mov_b32_e32 v75, v58
	v_mov_b32_e32 v76, v58
	v_mov_b32_e32 v77, v58
	v_mov_b32_e32 v78, v58
	v_mov_b32_e32 v79, v58
	v_mov_b32_e32 v80, v58
	v_mov_b32_e32 v81, v58
	v_mov_b32_e32 v82, v58
	v_mov_b32_e32 v83, v58
	v_mov_b32_e32 v84, v58
	v_mov_b32_e32 v85, v58
	v_mov_b32_e32 v90, v58
	v_mov_b32_e32 v91, v58
	v_mov_b32_e32 v92, v58
	v_mov_b32_e32 v93, v58
	v_mov_b32_e32 v106, v58
	v_mov_b32_e32 v107, v58
	v_mov_b32_e32 v108, v58
	v_mov_b32_e32 v109, v58
	v_mov_b32_e32 v110, v58
	v_mov_b32_e32 v111, v58
	v_mov_b32_e32 v112, v58
	v_mov_b32_e32 v113, v58
	v_mov_b32_e32 v26, v58
	v_mov_b32_e32 v27, v58
	v_mov_b32_e32 v28, v58
	v_mov_b32_e32 v29, v58
	v_mov_b32_e32 v30, v58
	v_mov_b32_e32 v31, v58
	v_mov_b32_e32 v32, v58
	v_mov_b32_e32 v33, v58
	v_mov_b32_e32 v18, v58
	v_mov_b32_e32 v19, v58
	v_mov_b32_e32 v20, v58
	v_mov_b32_e32 v21, v58
	v_mov_b32_e32 v22, v58
	v_mov_b32_e32 v23, v58
	v_mov_b32_e32 v24, v58
	v_mov_b32_e32 v25, v58
	v_mov_b32_e32 v14, v58
	v_mov_b32_e32 v15, v58
	v_mov_b32_e32 v16, v58
	v_mov_b32_e32 v17, v58
	v_mov_b32_e32 v10, v58
	v_mov_b32_e32 v11, v58
	v_mov_b32_e32 v12, v58
	v_mov_b32_e32 v13, v58
	v_mov_b32_e32 v6, v58
	v_mov_b32_e32 v7, v58
	v_mov_b32_e32 v8, v58
	v_mov_b32_e32 v9, v58
	v_mov_b32_e32 v2, v58
	v_mov_b32_e32 v3, v58
	v_mov_b32_e32 v4, v58
	v_mov_b32_e32 v5, v58
	v_mov_b32_e32 v118, v58
	v_mov_b32_e32 v119, v58
	v_mov_b32_e32 v120, v58
	v_mov_b32_e32 v121, v58
	v_mov_b32_e32 v126, v58
	v_mov_b32_e32 v127, v58
	v_mov_b32_e32 v128, v58
	v_mov_b32_e32 v129, v58
	v_mov_b32_e32 v122, v58
	v_mov_b32_e32 v123, v58
	v_mov_b32_e32 v124, v58
	v_mov_b32_e32 v125, v58
	v_mov_b32_e32 v114, v58
	v_mov_b32_e32 v115, v58
	v_mov_b32_e32 v116, v58
	v_mov_b32_e32 v117, v58
	v_mov_b32_e32 v102, v58
	v_mov_b32_e32 v103, v58
	v_mov_b32_e32 v104, v58
	v_mov_b32_e32 v105, v58
	v_mov_b32_e32 v98, v58
	v_mov_b32_e32 v99, v58
	v_mov_b32_e32 v100, v58
	v_mov_b32_e32 v101, v58
	v_mov_b32_e32 v94, v58
	v_mov_b32_e32 v95, v58
	v_mov_b32_e32 v96, v58
	v_mov_b32_e32 v97, v58
	v_mov_b32_e32 v86, v58
	v_mov_b32_e32 v87, v58
	v_mov_b32_e32 v88, v58
	v_mov_b32_e32 v89, v58
	s_branch .LBB0_806
